# K-loops: in the B0+A load segments the 8 A-fragment ds_reads are issued right after the 4 B-fragment reads, before the address SALU (plus earlier trims)
# speedup vs baseline: 1.0008x; 1.0008x over previous
; #define PG8_STAGE(bufoff, gbase, voff) do { _Pragma("unroll") for (int _i = 0; _i < 2; ++_i) \
;         __builtin_amdgcn_global_load_lds((const unsigned*)((const char*)(gbase) + (voff)[_i]), (LAS unsigned*)(lds + (bufoff) + ldsw + _i * 8192), 16, 0, 0); } while (0)
; #define PG8_LDA(dst, b, h) do { _Pragma("unroll") for (int m = 0; m < 4; ++m) _Pragma("unroll") for (int k = 0; k < 2; ++k) dst[m][k] = *(const LAS bf16x8*)(lds + PG8_SA(b, h) + aoff + m * 2048 + k * 1024); } while (0)
; #define PG8_LDB(dst, b, h) do { _Pragma("unroll") for (int n = 0; n < 2; ++n) _Pragma("unroll") for (int k = 0; k < 2; ++k) dst[n][k] = *(const LAS bf16x8*)(lds + PG8_SB(b, h) + boff + n * 2048 + k * 1024); } while (0)
; #define PG8_MMA(ai, bj, At, Bt) do { __builtin_amdgcn_s_setprio(1); _Pragma("unroll") for (int m = 0; m < 4; ++m) _Pragma("unroll") for (int n = 0; n < 2; ++n) _Pragma("unroll") for (int k = 0; k < 2; ++k) \
;         acc[ai][bj][m][n] = __builtin_amdgcn_mfma_f32_16x16x32_bf16(Bt[n][k], At[m][k], acc[ai][bj][m][n], 0, 0, 0); __builtin_amdgcn_s_setprio(0); } while (0)
; #define PG8_WAIT_L(n) asm volatile("s_waitcnt lgkmcnt(" #n ")" ::: "memory")
; template <int MODE, class EpiT, class Sched>
; __device__ __forceinline__ void gemm_phase(LAS unsigned char* lds, const Gemm g, const Sched& S, const EpiT& E) {
;     ...
;         const bool has_next = S.next(ui + 1, nxt);
;         const char* nA = has_next ? (const char*)g.A + (size_t)nxt.pm * tstep : cA; const char* nB = has_next ? (const char*)g.Bt + (size_t)nxt.pn * tstep : cB;
;         for (int t = 0; t < nt; t += 2) {
;             const bool last = (t == nt - 2);
;             const char* a1 = cA + (size_t)(t + 1) * kstep;
;             const char* a2 = last ? nA : cA + (size_t)(t + 2) * kstep; const char* b2 = last ? nB : cB + (size_t)(t + 2) * kstep;
;             const char* a3 = a2 + kstep; const char* b3 = b2 + kstep;
;             PG8_LDB(B0, 0, 0); PG8_SCHED; PG8_LDA(At, 0, 0); PG8_STAGE(PG8_SA(1, 1), a1 + hstep, voffA);
;             PG8_WAIT_L(8); PG8_BAR; PG8_WAIT_L(0); PG8_MMA(0, 0, At, B0); PG8_BAR; PG8_SCHED;
;             PG8_LDB(B1, 0, 1); PG8_STAGE(PG8_SB(0, 0), b2, voffB);
;             PG8_BAR; PG8_WAIT_L(0); PG8_MMA(0, 1, At, B1); PG8_BAR;
;             PG8_LDA(At, 0, 1); PG8_STAGE(PG8_SA(0, 0), a2, voffA);
;             PG8_BAR; PG8_WAIT_L(0); PG8_MMA(1, 0, At, B0); PG8_BAR; PG8_SCHED;
.LBB0_115:
	s_add_i32 s58, s52, 2
	s_add_u32 s59, s44, 0x80
	s_addc_u32 s53, s45, 0
	s_add_i32 s91, 0, 0x10000
	v_add_u32_e32 v86, s91, v192
	ds_read_b128 v[70:73], v86
	ds_read_b128 v[74:77], v86 offset:1024
	ds_read_b128 v[82:85], v86 offset:2048
	ds_read_b128 v[86:89], v86 offset:3072
	ds_read_b128 v[138:141], v194
	ds_read_b128 v[142:145], v194 offset:1024
	ds_read_b128 v[146:149], v194 offset:2048
	ds_read_b128 v[154:157], v194 offset:3072
	ds_read_b128 v[162:165], v194 offset:4096
	ds_read_b128 v[166:169], v194 offset:5120
	ds_read_b128 v[170:173], v194 offset:6144
	ds_read_b128 v[184:187], v194 offset:7168
	s_cmp_eq_u32 s57, s52
	s_cselect_b32 s52, s4, s59
	s_cselect_b32 s53, s5, s53
	s_cselect_b32 s75, s47, vcc_hi
	s_cselect_b32 s74, s46, vcc_lo
	s_add_i32 m0, s20, 0xc000
	v_lshl_add_u64 v[188:189], s[44:45], 0, v[176:177]
	global_load_lds_dwordx4 v[188:189], off
	v_lshl_add_u64 v[188:189], s[44:45], 0, v[182:183]
	s_add_i32 m0, s20, 0xe000
	s_nop 0
	global_load_lds_dwordx4 v[188:189], off
	s_waitcnt lgkmcnt(8)
	s_barrier
	s_waitcnt lgkmcnt(0)
	v_mfma_f32_16x16x32_bf16 v[158:161], v[70:73], v[138:141], v[158:161]
	v_mfma_f32_16x16x32_bf16 v[150:153], v[82:85], v[138:141], v[150:153]
	v_mfma_f32_16x16x32_bf16 v[126:129], v[70:73], v[146:149], v[126:129]
	v_mfma_f32_16x16x32_bf16 v[122:125], v[82:85], v[146:149], v[122:125]
	v_mfma_f32_16x16x32_bf16 v[110:113], v[70:73], v[162:165], v[110:113]
	v_mfma_f32_16x16x32_bf16 v[106:109], v[82:85], v[162:165], v[106:109]
	v_mfma_f32_16x16x32_bf16 v[94:97], v[70:73], v[170:173], v[94:97]
	v_mfma_f32_16x16x32_bf16 v[90:93], v[82:85], v[170:173], v[90:93]
	v_mfma_f32_16x16x32_bf16 v[158:161], v[74:77], v[142:145], v[158:161]
	v_mfma_f32_16x16x32_bf16 v[150:153], v[86:89], v[142:145], v[150:153]
	v_mfma_f32_16x16x32_bf16 v[126:129], v[74:77], v[154:157], v[126:129]
	v_mfma_f32_16x16x32_bf16 v[122:125], v[86:89], v[154:157], v[122:125]
	v_mfma_f32_16x16x32_bf16 v[110:113], v[74:77], v[166:169], v[110:113]
	v_mfma_f32_16x16x32_bf16 v[106:109], v[86:89], v[166:169], v[106:109]
	v_mfma_f32_16x16x32_bf16 v[94:97], v[74:77], v[184:187], v[94:97]
	v_mfma_f32_16x16x32_bf16 v[90:93], v[86:89], v[184:187], v[90:93]
	s_barrier
	s_add_i32 s59, 0, 0x14000
	s_add_i32 s91, s91, s9
	v_add_u32_e32 v195, s59, v192
	v_lshl_add_u64 v[228:229], s[74:75], 0, v[0:1]
	s_mov_b32 m0, s91
	ds_read_b128 v[188:191], v195
	ds_read_b128 v[196:199], v195 offset:1024
	ds_read_b128 v[220:223], v195 offset:2048
	ds_read_b128 v[224:227], v195 offset:3072
	global_load_lds_dwordx4 v[228:229], off
	v_lshl_add_u64 v[230:231], s[74:75], 0, v[174:175]
	s_add_i32 m0, s91, 0x2000
	s_nop 0
	global_load_lds_dwordx4 v[230:231], off
	s_barrier
	s_waitcnt lgkmcnt(0)
	v_mfma_f32_16x16x32_bf16 v[134:137], v[188:191], v[138:141], v[134:137]
	v_mfma_f32_16x16x32_bf16 v[130:133], v[220:223], v[138:141], v[130:133]
	v_mfma_f32_16x16x32_bf16 v[118:121], v[188:191], v[146:149], v[118:121]
	v_mfma_f32_16x16x32_bf16 v[114:117], v[220:223], v[146:149], v[114:117]
	v_mfma_f32_16x16x32_bf16 v[102:105], v[188:191], v[162:165], v[102:105]
	v_mfma_f32_16x16x32_bf16 v[98:101], v[220:223], v[162:165], v[98:101]
	v_mfma_f32_16x16x32_bf16 v[78:81], v[188:191], v[170:173], v[78:81]
	v_mfma_f32_16x16x32_bf16 v[66:69], v[220:223], v[170:173], v[66:69]
	v_mfma_f32_16x16x32_bf16 v[134:137], v[196:199], v[142:145], v[134:137]
	v_mfma_f32_16x16x32_bf16 v[130:133], v[224:227], v[142:145], v[130:133]
	v_mfma_f32_16x16x32_bf16 v[118:121], v[196:199], v[154:157], v[118:121]
	v_mfma_f32_16x16x32_bf16 v[114:117], v[224:227], v[154:157], v[114:117]
	v_mfma_f32_16x16x32_bf16 v[102:105], v[196:199], v[166:169], v[102:105]
	v_mfma_f32_16x16x32_bf16 v[98:101], v[224:227], v[166:169], v[98:101]
	v_mfma_f32_16x16x32_bf16 v[78:81], v[196:199], v[184:187], v[78:81]
	v_mfma_f32_16x16x32_bf16 v[66:69], v[224:227], v[184:187], v[66:69]
	s_barrier
	s_mov_b32 m0, s20
	v_lshl_add_u64 v[232:233], s[52:53], 0, v[0:1]
	ds_read_b128 v[138:141], v194 offset:16384
	ds_read_b128 v[142:145], v194 offset:17408
	ds_read_b128 v[146:149], v194 offset:18432
	ds_read_b128 v[154:157], v194 offset:19456
	ds_read_b128 v[162:165], v194 offset:20480
	ds_read_b128 v[166:169], v194 offset:21504
	ds_read_b128 v[170:173], v194 offset:22528
	ds_read_b128 v[184:187], v194 offset:23552
	global_load_lds_dwordx4 v[232:233], off
	v_lshl_add_u64 v[234:235], s[52:53], 0, v[174:175]
	s_mov_b32 m0, s21
	s_nop 0
	global_load_lds_dwordx4 v[234:235], off
	s_barrier
	s_waitcnt lgkmcnt(0)
	v_mfma_f32_16x16x32_bf16 v[62:65], v[70:73], v[138:141], v[62:65]
	v_mfma_f32_16x16x32_bf16 v[58:61], v[82:85], v[138:141], v[58:61]
	v_mfma_f32_16x16x32_bf16 v[46:49], v[70:73], v[146:149], v[46:49]
	v_mfma_f32_16x16x32_bf16 v[42:45], v[82:85], v[146:149], v[42:45]
	v_mfma_f32_16x16x32_bf16 v[30:33], v[70:73], v[162:165], v[30:33]
	v_mfma_f32_16x16x32_bf16 v[26:29], v[82:85], v[162:165], v[26:29]
	v_mfma_f32_16x16x32_bf16 v[14:17], v[70:73], v[170:173], v[14:17]
	v_mfma_f32_16x16x32_bf16 v[10:13], v[82:85], v[170:173], v[10:13]
	v_mfma_f32_16x16x32_bf16 v[62:65], v[74:77], v[142:145], v[62:65]
	v_mfma_f32_16x16x32_bf16 v[58:61], v[86:89], v[142:145], v[58:61]
	v_mfma_f32_16x16x32_bf16 v[46:49], v[74:77], v[154:157], v[46:49]
	v_mfma_f32_16x16x32_bf16 v[42:45], v[86:89], v[154:157], v[42:45]
	v_mfma_f32_16x16x32_bf16 v[30:33], v[74:77], v[166:169], v[30:33]
	v_mfma_f32_16x16x32_bf16 v[26:29], v[86:89], v[166:169], v[26:29]
	v_mfma_f32_16x16x32_bf16 v[14:17], v[74:77], v[184:187], v[14:17]
	v_mfma_f32_16x16x32_bf16 v[10:13], v[86:89], v[184:187], v[10:13]
	s_barrier
; #define PG8_STAGE(bufoff, gbase, voff) do { _Pragma("unroll") for (int _i = 0; _i < 2; ++_i) \
;         __builtin_amdgcn_global_load_lds((const unsigned*)((const char*)(gbase) + (voff)[_i]), (LAS unsigned*)(lds + (bufoff) + ldsw + _i * 8192), 16, 0, 0); } while (0)
; #define PG8_LDA(dst, b, h) do { _Pragma("unroll") for (int m = 0; m < 4; ++m) _Pragma("unroll") for (int k = 0; k < 2; ++k) dst[m][k] = *(const LAS bf16x8*)(lds + PG8_SA(b, h) + aoff + m * 2048 + k * 1024); } while (0)
; #define PG8_LDB(dst, b, h) do { _Pragma("unroll") for (int n = 0; n < 2; ++n) _Pragma("unroll") for (int k = 0; k < 2; ++k) dst[n][k] = *(const LAS bf16x8*)(lds + PG8_SB(b, h) + boff + n * 2048 + k * 1024); } while (0)
; #define PG8_MMA(ai, bj, At, Bt) do { __builtin_amdgcn_s_setprio(1); _Pragma("unroll") for (int m = 0; m < 4; ++m) _Pragma("unroll") for (int n = 0; n < 2; ++n) _Pragma("unroll") for (int k = 0; k < 2; ++k) \
;         acc[ai][bj][m][n] = __builtin_amdgcn_mfma_f32_16x16x32_bf16(Bt[n][k], At[m][k], acc[ai][bj][m][n], 0, 0, 0); __builtin_amdgcn_s_setprio(0); } while (0)
; #define PG8_WAIT_V(n) asm volatile("s_waitcnt vmcnt(" #n ")" ::: "memory")
; #define PG8_WAIT_L(n) asm volatile("s_waitcnt lgkmcnt(" #n ")" ::: "memory")
; #define PG8_BAR __builtin_amdgcn_s_barrier()
; #define PG8_SCHED __builtin_amdgcn_sched_barrier(0)
; template <int MODE, class EpiT, class Sched>
; __device__ __forceinline__ void gemm_phase(LAS unsigned char* lds, const Gemm g, const Sched& S, const EpiT& E) {
;     ...
;             PG8_STAGE(PG8_SB(0, 1), b2 + hstep, voffB);
;             PG8_WAIT_V(6); PG8_BAR; PG8_MMA(1, 1, At, B1); PG8_BAR;
;             PG8_LDB(B0, 1, 0); PG8_SCHED; PG8_LDA(At, 1, 0); PG8_STAGE(PG8_SA(0, 1), a2 + hstep, voffA);
;             PG8_WAIT_L(8); PG8_BAR; PG8_WAIT_L(0); PG8_MMA(0, 0, At, B0); PG8_BAR; PG8_SCHED;
;             PG8_LDB(B1, 1, 1); PG8_STAGE(PG8_SB(1, 0), b3, voffB);
;             PG8_BAR; PG8_WAIT_L(0); PG8_MMA(0, 1, At, B1); PG8_BAR;
;             PG8_LDA(At, 1, 1); PG8_STAGE(PG8_SA(1, 0), a3, voffA);
	s_add_u32 s74, s74, s78
	s_addc_u32 s75, s75, 0
	s_add_i32 s59, s59, s9
	v_lshl_add_u64 v[236:237], s[74:75], 0, v[0:1]
	s_mov_b32 m0, s59
	v_lshl_add_u64 v[238:239], s[74:75], 0, v[174:175]
	global_load_lds_dwordx4 v[236:237], off
	s_add_i32 m0, s59, 0x2000
	s_nop 0
	global_load_lds_dwordx4 v[238:239], off
	s_waitcnt vmcnt(6)
	s_barrier
	v_mfma_f32_16x16x32_bf16 v[54:57], v[188:191], v[138:141], v[54:57]
	v_mfma_f32_16x16x32_bf16 v[50:53], v[220:223], v[138:141], v[50:53]
	v_mfma_f32_16x16x32_bf16 v[38:41], v[188:191], v[146:149], v[38:41]
	v_mfma_f32_16x16x32_bf16 v[34:37], v[220:223], v[146:149], v[34:37]
	v_mfma_f32_16x16x32_bf16 v[22:25], v[188:191], v[162:165], v[22:25]
	v_mfma_f32_16x16x32_bf16 v[18:21], v[220:223], v[162:165], v[18:21]
	v_mfma_f32_16x16x32_bf16 v[6:9], v[188:191], v[170:173], v[6:9]
	v_mfma_f32_16x16x32_bf16 v[2:5], v[220:223], v[170:173], v[2:5]
	v_mfma_f32_16x16x32_bf16 v[54:57], v[196:199], v[142:145], v[54:57]
	v_mfma_f32_16x16x32_bf16 v[50:53], v[224:227], v[142:145], v[50:53]
	v_mfma_f32_16x16x32_bf16 v[38:41], v[196:199], v[154:157], v[38:41]
	v_mfma_f32_16x16x32_bf16 v[34:37], v[224:227], v[154:157], v[34:37]
	v_mfma_f32_16x16x32_bf16 v[22:25], v[196:199], v[166:169], v[22:25]
	v_mfma_f32_16x16x32_bf16 v[18:21], v[224:227], v[166:169], v[18:21]
	v_mfma_f32_16x16x32_bf16 v[6:9], v[196:199], v[184:187], v[6:9]
	v_mfma_f32_16x16x32_bf16 v[2:5], v[224:227], v[184:187], v[2:5]
	s_barrier
	s_add_i32 s59, 0, 0x18000
	v_add_u32_e32 v86, s59, v192
	ds_read_b128 v[70:73], v86
	ds_read_b128 v[74:77], v86 offset:1024
	ds_read_b128 v[82:85], v86 offset:2048
	ds_read_b128 v[86:89], v86 offset:3072
	ds_read_b128 v[138:141], v194 offset:32768
	ds_read_b128 v[142:145], v194 offset:33792
	ds_read_b128 v[146:149], v194 offset:34816
	ds_read_b128 v[154:157], v194 offset:35840
	ds_read_b128 v[162:165], v194 offset:36864
	ds_read_b128 v[166:169], v194 offset:37888
	ds_read_b128 v[170:173], v194 offset:38912
	ds_read_b128 v[184:187], v194 offset:39936
	s_add_u32 s52, s52, s78
	s_addc_u32 s53, s53, 0
	s_mov_b32 m0, s22
	v_lshl_add_u64 v[188:189], s[52:53], 0, v[0:1]
	global_load_lds_dwordx4 v[188:189], off
	v_lshl_add_u64 v[188:189], s[52:53], 0, v[174:175]
	s_mov_b32 m0, s23
	s_nop 0
	global_load_lds_dwordx4 v[188:189], off
	s_waitcnt lgkmcnt(8)
	s_barrier
	s_waitcnt lgkmcnt(0)
	v_mfma_f32_16x16x32_bf16 v[158:161], v[70:73], v[138:141], v[158:161]
	v_mfma_f32_16x16x32_bf16 v[150:153], v[82:85], v[138:141], v[150:153]
	v_mfma_f32_16x16x32_bf16 v[126:129], v[70:73], v[146:149], v[126:129]
	v_mfma_f32_16x16x32_bf16 v[122:125], v[82:85], v[146:149], v[122:125]
	v_mfma_f32_16x16x32_bf16 v[110:113], v[70:73], v[162:165], v[110:113]
	v_mfma_f32_16x16x32_bf16 v[106:109], v[82:85], v[162:165], v[106:109]
	v_mfma_f32_16x16x32_bf16 v[94:97], v[70:73], v[170:173], v[94:97]
	v_mfma_f32_16x16x32_bf16 v[90:93], v[82:85], v[170:173], v[90:93]
	v_mfma_f32_16x16x32_bf16 v[158:161], v[74:77], v[142:145], v[158:161]
	v_mfma_f32_16x16x32_bf16 v[150:153], v[86:89], v[142:145], v[150:153]
	v_mfma_f32_16x16x32_bf16 v[126:129], v[74:77], v[154:157], v[126:129]
	v_mfma_f32_16x16x32_bf16 v[122:125], v[86:89], v[154:157], v[122:125]
	v_mfma_f32_16x16x32_bf16 v[110:113], v[74:77], v[166:169], v[110:113]
	v_mfma_f32_16x16x32_bf16 v[106:109], v[86:89], v[166:169], v[106:109]
	v_mfma_f32_16x16x32_bf16 v[94:97], v[74:77], v[184:187], v[94:97]
	v_mfma_f32_16x16x32_bf16 v[90:93], v[86:89], v[184:187], v[90:93]
	s_barrier
	s_add_i32 s52, 0, 0x1c000
	s_add_i32 s53, s59, s9
	v_add_u32_e32 v195, s52, v192
	v_lshl_add_u64 v[228:229], v[228:229], 0, s[76:77]
	s_mov_b32 m0, s53
	ds_read_b128 v[188:191], v195
	ds_read_b128 v[196:199], v195 offset:1024
	ds_read_b128 v[220:223], v195 offset:2048
	ds_read_b128 v[224:227], v195 offset:3072
	global_load_lds_dwordx4 v[228:229], off
	v_lshl_add_u64 v[228:229], v[230:231], 0, s[76:77]
	s_add_i32 m0, s53, 0x2000
	s_nop 0
	global_load_lds_dwordx4 v[228:229], off
	s_barrier
; #define PG8_STAGE(bufoff, gbase, voff) do { _Pragma("unroll") for (int _i = 0; _i < 2; ++_i) \
;         __builtin_amdgcn_global_load_lds((const unsigned*)((const char*)(gbase) + (voff)[_i]), (LAS unsigned*)(lds + (bufoff) + ldsw + _i * 8192), 16, 0, 0); } while (0)
; #define PG8_LDA(dst, b, h) do { _Pragma("unroll") for (int m = 0; m < 4; ++m) _Pragma("unroll") for (int k = 0; k < 2; ++k) dst[m][k] = *(const LAS bf16x8*)(lds + PG8_SA(b, h) + aoff + m * 2048 + k * 1024); } while (0)
; #define PG8_MMA(ai, bj, At, Bt) do { __builtin_amdgcn_s_setprio(1); _Pragma("unroll") for (int m = 0; m < 4; ++m) _Pragma("unroll") for (int n = 0; n < 2; ++n) _Pragma("unroll") for (int k = 0; k < 2; ++k) \
;         acc[ai][bj][m][n] = __builtin_amdgcn_mfma_f32_16x16x32_bf16(Bt[n][k], At[m][k], acc[ai][bj][m][n], 0, 0, 0); __builtin_amdgcn_s_setprio(0); } while (0)
; #define PG8_WAIT_V(n) asm volatile("s_waitcnt vmcnt(" #n ")" ::: "memory")
; #define PG8_WAIT_L(n) asm volatile("s_waitcnt lgkmcnt(" #n ")" ::: "memory")
; #define PG8_BAR __builtin_amdgcn_s_barrier()
; #define PG8_SCHED __builtin_amdgcn_sched_barrier(0)
;     template <int mode> __device__ __forceinline__ void run(const f32x4 (&acc)[2][2][4][2], const Unit& u, int wr, int wc, int fr, int fq, const LAS float* sc) const {
;     ...
; #pragma unroll
;             for (int q = 0; q < 4; ++q) bvv[q] = (mode != 4 && bias) ? *(const f32x4*)(bias + col0 + (q >> 1) * HALF + (q & 1) * 4) : (f32x4){0.f, 0.f, 0.f, 0.f};
; template <int MODE, class EpiT, class Sched>
; __device__ __forceinline__ void gemm_phase(LAS unsigned char* lds, const Gemm g, const Sched& S, const EpiT& E) {
;     ...
;             PG8_LDA(At, 1, 1); PG8_STAGE(PG8_SA(1, 0), a3, voffA);
;             PG8_BAR; PG8_WAIT_L(0); PG8_MMA(1, 0, At, B0); PG8_BAR; PG8_SCHED;
;             PG8_STAGE(PG8_SB(1, 1), b3 + hstep, voffB);
;             PG8_WAIT_V(6); PG8_BAR; PG8_MMA(1, 1, At, B1); PG8_BAR;
;         }
	s_waitcnt lgkmcnt(0)
	v_mfma_f32_16x16x32_bf16 v[134:137], v[188:191], v[138:141], v[134:137]
	v_mfma_f32_16x16x32_bf16 v[130:133], v[220:223], v[138:141], v[130:133]
	v_mfma_f32_16x16x32_bf16 v[118:121], v[188:191], v[146:149], v[118:121]
	v_mfma_f32_16x16x32_bf16 v[114:117], v[220:223], v[146:149], v[114:117]
	v_mfma_f32_16x16x32_bf16 v[102:105], v[188:191], v[162:165], v[102:105]
	v_mfma_f32_16x16x32_bf16 v[98:101], v[220:223], v[162:165], v[98:101]
	v_mfma_f32_16x16x32_bf16 v[78:81], v[188:191], v[170:173], v[78:81]
	v_mfma_f32_16x16x32_bf16 v[66:69], v[220:223], v[170:173], v[66:69]
	v_mfma_f32_16x16x32_bf16 v[134:137], v[196:199], v[142:145], v[134:137]
	v_mfma_f32_16x16x32_bf16 v[130:133], v[224:227], v[142:145], v[130:133]
	v_mfma_f32_16x16x32_bf16 v[118:121], v[196:199], v[154:157], v[118:121]
	v_mfma_f32_16x16x32_bf16 v[114:117], v[224:227], v[154:157], v[114:117]
	v_mfma_f32_16x16x32_bf16 v[102:105], v[196:199], v[166:169], v[102:105]
	v_mfma_f32_16x16x32_bf16 v[98:101], v[224:227], v[166:169], v[98:101]
	v_mfma_f32_16x16x32_bf16 v[78:81], v[196:199], v[184:187], v[78:81]
	v_mfma_f32_16x16x32_bf16 v[66:69], v[224:227], v[184:187], v[66:69]
	s_barrier
	s_mov_b32 m0, s51
	v_lshl_add_u64 v[228:229], v[232:233], 0, s[76:77]
	ds_read_b128 v[138:141], v194 offset:49152
	ds_read_b128 v[142:145], v194 offset:50176
	ds_read_b128 v[146:149], v194 offset:51200
	ds_read_b128 v[154:157], v194 offset:52224
	ds_read_b128 v[162:165], v194 offset:53248
	ds_read_b128 v[166:169], v194 offset:54272
	ds_read_b128 v[170:173], v194 offset:55296
	ds_read_b128 v[184:187], v194 offset:56320
	global_load_lds_dwordx4 v[228:229], off
	v_lshl_add_u64 v[228:229], v[234:235], 0, s[76:77]
	s_mov_b32 m0, s56
	s_nop 0
	global_load_lds_dwordx4 v[228:229], off
	s_barrier
	s_waitcnt lgkmcnt(0)
	v_mfma_f32_16x16x32_bf16 v[62:65], v[70:73], v[138:141], v[62:65]
	v_mfma_f32_16x16x32_bf16 v[58:61], v[82:85], v[138:141], v[58:61]
	v_mfma_f32_16x16x32_bf16 v[46:49], v[70:73], v[146:149], v[46:49]
	v_mfma_f32_16x16x32_bf16 v[42:45], v[82:85], v[146:149], v[42:45]
	v_mfma_f32_16x16x32_bf16 v[30:33], v[70:73], v[162:165], v[30:33]
	v_mfma_f32_16x16x32_bf16 v[26:29], v[82:85], v[162:165], v[26:29]
	v_mfma_f32_16x16x32_bf16 v[14:17], v[70:73], v[170:173], v[14:17]
	v_mfma_f32_16x16x32_bf16 v[10:13], v[82:85], v[170:173], v[10:13]
	v_mfma_f32_16x16x32_bf16 v[62:65], v[74:77], v[142:145], v[62:65]
	v_mfma_f32_16x16x32_bf16 v[58:61], v[86:89], v[142:145], v[58:61]
	v_mfma_f32_16x16x32_bf16 v[46:49], v[74:77], v[154:157], v[46:49]
	v_mfma_f32_16x16x32_bf16 v[42:45], v[86:89], v[154:157], v[42:45]
	v_mfma_f32_16x16x32_bf16 v[30:33], v[74:77], v[166:169], v[30:33]
	v_mfma_f32_16x16x32_bf16 v[26:29], v[86:89], v[166:169], v[26:29]
	v_mfma_f32_16x16x32_bf16 v[14:17], v[74:77], v[184:187], v[14:17]
	v_mfma_f32_16x16x32_bf16 v[10:13], v[86:89], v[184:187], v[10:13]
	s_barrier
	s_add_i32 s52, s52, s9
	v_lshl_add_u64 v[70:71], v[236:237], 0, s[76:77]
	s_mov_b32 m0, s52
	s_nop 0
	global_load_lds_dwordx4 v[70:71], off
	v_lshl_add_u64 v[70:71], v[238:239], 0, s[76:77]
	s_add_i32 m0, s52, 0x2000
	s_nop 0
	global_load_lds_dwordx4 v[70:71], off
	s_waitcnt vmcnt(6)
	s_barrier
	v_mfma_f32_16x16x32_bf16 v[54:57], v[188:191], v[138:141], v[54:57]
	v_mfma_f32_16x16x32_bf16 v[50:53], v[220:223], v[138:141], v[50:53]
	v_mfma_f32_16x16x32_bf16 v[38:41], v[188:191], v[146:149], v[38:41]
	v_mfma_f32_16x16x32_bf16 v[34:37], v[220:223], v[146:149], v[34:37]
	v_mfma_f32_16x16x32_bf16 v[22:25], v[188:191], v[162:165], v[22:25]
	v_mfma_f32_16x16x32_bf16 v[18:21], v[220:223], v[162:165], v[18:21]
	v_mfma_f32_16x16x32_bf16 v[6:9], v[188:191], v[170:173], v[6:9]
	v_mfma_f32_16x16x32_bf16 v[2:5], v[220:223], v[170:173], v[2:5]
	v_mfma_f32_16x16x32_bf16 v[54:57], v[196:199], v[142:145], v[54:57]
	v_mfma_f32_16x16x32_bf16 v[50:53], v[224:227], v[142:145], v[50:53]
	v_mfma_f32_16x16x32_bf16 v[38:41], v[196:199], v[154:157], v[38:41]
	v_mfma_f32_16x16x32_bf16 v[34:37], v[224:227], v[154:157], v[34:37]
	v_mfma_f32_16x16x32_bf16 v[22:25], v[196:199], v[166:169], v[22:25]
	v_mfma_f32_16x16x32_bf16 v[18:21], v[224:227], v[166:169], v[18:21]
	v_mfma_f32_16x16x32_bf16 v[6:9], v[196:199], v[184:187], v[6:9]
	v_mfma_f32_16x16x32_bf16 v[2:5], v[224:227], v[184:187], v[2:5]
	s_barrier
	s_add_u32 s44, s44, 0x100
	s_addc_u32 s45, s45, 0
	s_add_u32 vcc_lo, vcc_lo, 0x100
	s_addc_u32 vcc_hi, vcc_hi, 0
	s_cmp_ge_u32 s58, s50
	s_mov_b32 s52, s58
	s_cbranch_scc0 .LBB0_115
	v_lshl_or_b32 v184, s24, 8, v193
	v_ashrrev_i32_e32 v185, 31, v184
	v_mov_b32_e32 v74, 0
	v_cndmask_b32_e64 v70, 0, 1, s[68:69]
	v_lshl_add_u64 v[138:139], v[184:185], 2, s[12:13]
	v_cmp_ne_u32_e64 s[44:45], 1, v70
	s_andn2_b64 vcc, exec, s[68:69]
	v_mov_b32_e32 v86, 0
	v_mov_b32_e32 v87, v74
	v_mov_b32_e32 v186, 0
	v_mov_b32_e32 v187, v74
	s_cbranch_vccnz .LBB0_118
	global_load_dwordx4 v[86:89], v[138:139], off
	s_waitcnt vmcnt(0)
	v_mov_b32_e32 v186, v88
	v_mov_b32_e32 v187, v89

; #define PG8_STAGE(bufoff, gbase, voff) do { _Pragma("unroll") for (int _i = 0; _i < 2; ++_i) \
;         __builtin_amdgcn_global_load_lds((const unsigned*)((const char*)(gbase) + (voff)[_i]), (LAS unsigned*)(lds + (bufoff) + ldsw + _i * 8192), 16, 0, 0); } while (0)
; #define PG8_LDA(dst, b, h) do { _Pragma("unroll") for (int m = 0; m < 4; ++m) _Pragma("unroll") for (int k = 0; k < 2; ++k) dst[m][k] = *(const LAS bf16x8*)(lds + PG8_SA(b, h) + aoff + m * 2048 + k * 1024); } while (0)
; #define PG8_LDB(dst, b, h) do { _Pragma("unroll") for (int n = 0; n < 2; ++n) _Pragma("unroll") for (int k = 0; k < 2; ++k) dst[n][k] = *(const LAS bf16x8*)(lds + PG8_SB(b, h) + boff + n * 2048 + k * 1024); } while (0)
; #define PG8_MMA(ai, bj, At, Bt) do { __builtin_amdgcn_s_setprio(1); _Pragma("unroll") for (int m = 0; m < 4; ++m) _Pragma("unroll") for (int n = 0; n < 2; ++n) _Pragma("unroll") for (int k = 0; k < 2; ++k) \
;         acc[ai][bj][m][n] = __builtin_amdgcn_mfma_f32_16x16x32_bf16(Bt[n][k], At[m][k], acc[ai][bj][m][n], 0, 0, 0); __builtin_amdgcn_s_setprio(0); } while (0)
; #define PG8_WAIT_L(n) asm volatile("s_waitcnt lgkmcnt(" #n ")" ::: "memory")
; template <int MODE, class EpiT, class Sched>
; __device__ __forceinline__ void gemm_phase(LAS unsigned char* lds, const Gemm g, const Sched& S, const EpiT& E) {
;     ...
;         const bool has_next = S.next(ui + 1, nxt);
;         const char* nA = has_next ? (const char*)g.A + (size_t)nxt.pm * tstep : cA; const char* nB = has_next ? (const char*)g.Bt + (size_t)nxt.pn * tstep : cB;
;         for (int t = 0; t < nt; t += 2) {
;             const bool last = (t == nt - 2);
;             const char* a1 = cA + (size_t)(t + 1) * kstep;
;             const char* a2 = last ? nA : cA + (size_t)(t + 2) * kstep; const char* b2 = last ? nB : cB + (size_t)(t + 2) * kstep;
;             const char* a3 = a2 + kstep; const char* b3 = b2 + kstep;
;             PG8_LDB(B0, 0, 0); PG8_SCHED; PG8_LDA(At, 0, 0); PG8_STAGE(PG8_SA(1, 1), a1 + hstep, voffA);
;             PG8_WAIT_L(8); PG8_BAR; PG8_WAIT_L(0); PG8_MMA(0, 0, At, B0); PG8_BAR; PG8_SCHED;
;             PG8_LDB(B1, 0, 1); PG8_STAGE(PG8_SB(0, 0), b2, voffB);
;             PG8_BAR; PG8_WAIT_L(0); PG8_MMA(0, 1, At, B1); PG8_BAR;
;             PG8_LDA(At, 0, 1); PG8_STAGE(PG8_SA(0, 0), a2, voffA);
;             PG8_BAR; PG8_WAIT_L(0); PG8_MMA(1, 0, At, B0); PG8_BAR; PG8_SCHED;
.LBB0_159:
	s_add_i32 s89, s30, 2
	s_add_u32 s44, s4, 0x80
	s_addc_u32 s45, s5, 0
	s_add_i32 s58, 0, 0x10000
	v_add_u32_e32 v142, s58, v220
	ds_read_b128 v[130:133], v142
	ds_read_b128 v[134:137], v142 offset:1024
	ds_read_b128 v[138:141], v142 offset:2048
	ds_read_b128 v[142:145], v142 offset:3072
	ds_read_b128 v[146:149], v223
	ds_read_b128 v[150:153], v223 offset:1024
	ds_read_b128 v[154:157], v223 offset:2048
	ds_read_b128 v[158:161], v223 offset:3072
	ds_read_b128 v[162:165], v223 offset:4096
	ds_read_b128 v[166:169], v223 offset:5120
	ds_read_b128 v[170:173], v223 offset:6144
	ds_read_b128 v[174:177], v223 offset:7168
	s_cmp_eq_u32 s61, s30
	s_cselect_b32 s45, s79, s45
	s_cselect_b32 s44, s78, s44
	s_cselect_b32 s53, s47, s24
	s_cselect_b32 s52, s46, s23
	s_add_i32 m0, s69, 0xc000
	v_lshl_add_u64 v[188:189], s[4:5], 0, v[184:185]
	global_load_lds_dwordx4 v[188:189], off
	v_lshl_add_u64 v[188:189], s[4:5], 0, v[186:187]
	s_add_i32 m0, s69, 0xe000
	s_nop 0
	global_load_lds_dwordx4 v[188:189], off
	s_waitcnt lgkmcnt(8)
	s_barrier
	s_waitcnt lgkmcnt(0)
	v_mfma_f32_16x16x32_bf16 v[126:129], v[130:133], v[146:149], v[126:129]
	v_mfma_f32_16x16x32_bf16 v[122:125], v[138:141], v[146:149], v[122:125]
	v_mfma_f32_16x16x32_bf16 v[110:113], v[130:133], v[154:157], v[110:113]
	v_mfma_f32_16x16x32_bf16 v[106:109], v[138:141], v[154:157], v[106:109]
	v_mfma_f32_16x16x32_bf16 v[94:97], v[130:133], v[162:165], v[94:97]
	v_mfma_f32_16x16x32_bf16 v[90:93], v[138:141], v[162:165], v[90:93]
	v_mfma_f32_16x16x32_bf16 v[78:81], v[130:133], v[170:173], v[78:81]
	v_mfma_f32_16x16x32_bf16 v[74:77], v[138:141], v[170:173], v[74:77]
	v_mfma_f32_16x16x32_bf16 v[126:129], v[134:137], v[150:153], v[126:129]
	v_mfma_f32_16x16x32_bf16 v[122:125], v[142:145], v[150:153], v[122:125]
	v_mfma_f32_16x16x32_bf16 v[110:113], v[134:137], v[158:161], v[110:113]
	v_mfma_f32_16x16x32_bf16 v[106:109], v[142:145], v[158:161], v[106:109]
	v_mfma_f32_16x16x32_bf16 v[94:97], v[134:137], v[166:169], v[94:97]
	v_mfma_f32_16x16x32_bf16 v[90:93], v[142:145], v[166:169], v[90:93]
	v_mfma_f32_16x16x32_bf16 v[78:81], v[134:137], v[174:177], v[78:81]
	v_mfma_f32_16x16x32_bf16 v[74:77], v[142:145], v[174:177], v[74:77]
	s_barrier
	s_add_i32 s30, 0, 0x14000
	s_add_i32 s58, s58, s68
	v_add_u32_e32 v200, s30, v220
	v_lshl_add_u64 v[228:229], s[52:53], 0, v[0:1]
	s_mov_b32 m0, s58
	ds_read_b128 v[188:191], v200
	ds_read_b128 v[192:195], v200 offset:1024
	ds_read_b128 v[196:199], v200 offset:2048
	ds_read_b128 v[224:227], v200 offset:3072
	global_load_lds_dwordx4 v[228:229], off
	v_lshl_add_u64 v[230:231], s[52:53], 0, v[182:183]
	s_add_i32 m0, s58, 0x2000
	s_nop 0
	global_load_lds_dwordx4 v[230:231], off
	s_barrier
	s_waitcnt lgkmcnt(0)
	v_mfma_f32_16x16x32_bf16 v[118:121], v[188:191], v[146:149], v[118:121]
	v_mfma_f32_16x16x32_bf16 v[114:117], v[196:199], v[146:149], v[114:117]
	v_mfma_f32_16x16x32_bf16 v[102:105], v[188:191], v[154:157], v[102:105]
	v_mfma_f32_16x16x32_bf16 v[98:101], v[196:199], v[154:157], v[98:101]
	v_mfma_f32_16x16x32_bf16 v[86:89], v[188:191], v[162:165], v[86:89]
	v_mfma_f32_16x16x32_bf16 v[82:85], v[196:199], v[162:165], v[82:85]
	v_mfma_f32_16x16x32_bf16 v[70:73], v[188:191], v[170:173], v[70:73]
	v_mfma_f32_16x16x32_bf16 v[66:69], v[196:199], v[170:173], v[66:69]
	v_mfma_f32_16x16x32_bf16 v[118:121], v[192:195], v[150:153], v[118:121]
	v_mfma_f32_16x16x32_bf16 v[114:117], v[224:227], v[150:153], v[114:117]
	v_mfma_f32_16x16x32_bf16 v[102:105], v[192:195], v[158:161], v[102:105]
	v_mfma_f32_16x16x32_bf16 v[98:101], v[224:227], v[158:161], v[98:101]
	v_mfma_f32_16x16x32_bf16 v[86:89], v[192:195], v[166:169], v[86:89]
	v_mfma_f32_16x16x32_bf16 v[82:85], v[224:227], v[166:169], v[82:85]
	v_mfma_f32_16x16x32_bf16 v[70:73], v[192:195], v[174:177], v[70:73]
	v_mfma_f32_16x16x32_bf16 v[66:69], v[224:227], v[174:177], v[66:69]
	s_barrier
	s_mov_b32 m0, s69
	v_lshl_add_u64 v[232:233], s[44:45], 0, v[0:1]
	ds_read_b128 v[146:149], v223 offset:16384
	ds_read_b128 v[150:153], v223 offset:17408
	ds_read_b128 v[154:157], v223 offset:18432
	ds_read_b128 v[158:161], v223 offset:19456
	ds_read_b128 v[162:165], v223 offset:20480
	ds_read_b128 v[166:169], v223 offset:21504
	ds_read_b128 v[170:173], v223 offset:22528
	ds_read_b128 v[174:177], v223 offset:23552
	global_load_lds_dwordx4 v[232:233], off
	v_lshl_add_u64 v[234:235], s[44:45], 0, v[182:183]
	s_mov_b32 m0, s74
	s_nop 0
	global_load_lds_dwordx4 v[234:235], off
	s_barrier
	s_waitcnt lgkmcnt(0)
	v_mfma_f32_16x16x32_bf16 v[62:65], v[130:133], v[146:149], v[62:65]
	v_mfma_f32_16x16x32_bf16 v[58:61], v[138:141], v[146:149], v[58:61]
	v_mfma_f32_16x16x32_bf16 v[46:49], v[130:133], v[154:157], v[46:49]
	v_mfma_f32_16x16x32_bf16 v[42:45], v[138:141], v[154:157], v[42:45]
	v_mfma_f32_16x16x32_bf16 v[30:33], v[130:133], v[162:165], v[30:33]
	v_mfma_f32_16x16x32_bf16 v[26:29], v[138:141], v[162:165], v[26:29]
	v_mfma_f32_16x16x32_bf16 v[14:17], v[130:133], v[170:173], v[14:17]
	v_mfma_f32_16x16x32_bf16 v[10:13], v[138:141], v[170:173], v[10:13]
	v_mfma_f32_16x16x32_bf16 v[62:65], v[134:137], v[150:153], v[62:65]
	v_mfma_f32_16x16x32_bf16 v[58:61], v[142:145], v[150:153], v[58:61]
	v_mfma_f32_16x16x32_bf16 v[46:49], v[134:137], v[158:161], v[46:49]
	v_mfma_f32_16x16x32_bf16 v[42:45], v[142:145], v[158:161], v[42:45]
	v_mfma_f32_16x16x32_bf16 v[30:33], v[134:137], v[166:169], v[30:33]
	v_mfma_f32_16x16x32_bf16 v[26:29], v[142:145], v[166:169], v[26:29]
	v_mfma_f32_16x16x32_bf16 v[14:17], v[134:137], v[174:177], v[14:17]
	v_mfma_f32_16x16x32_bf16 v[10:13], v[142:145], v[174:177], v[10:13]
	s_barrier
; #define PG8_STAGE(bufoff, gbase, voff) do { _Pragma("unroll") for (int _i = 0; _i < 2; ++_i) \
;         __builtin_amdgcn_global_load_lds((const unsigned*)((const char*)(gbase) + (voff)[_i]), (LAS unsigned*)(lds + (bufoff) + ldsw + _i * 8192), 16, 0, 0); } while (0)
; #define PG8_LDA(dst, b, h) do { _Pragma("unroll") for (int m = 0; m < 4; ++m) _Pragma("unroll") for (int k = 0; k < 2; ++k) dst[m][k] = *(const LAS bf16x8*)(lds + PG8_SA(b, h) + aoff + m * 2048 + k * 1024); } while (0)
; #define PG8_LDB(dst, b, h) do { _Pragma("unroll") for (int n = 0; n < 2; ++n) _Pragma("unroll") for (int k = 0; k < 2; ++k) dst[n][k] = *(const LAS bf16x8*)(lds + PG8_SB(b, h) + boff + n * 2048 + k * 1024); } while (0)
; #define PG8_MMA(ai, bj, At, Bt) do { __builtin_amdgcn_s_setprio(1); _Pragma("unroll") for (int m = 0; m < 4; ++m) _Pragma("unroll") for (int n = 0; n < 2; ++n) _Pragma("unroll") for (int k = 0; k < 2; ++k) \
;         acc[ai][bj][m][n] = __builtin_amdgcn_mfma_f32_16x16x32_bf16(Bt[n][k], At[m][k], acc[ai][bj][m][n], 0, 0, 0); __builtin_amdgcn_s_setprio(0); } while (0)
; #define PG8_WAIT_V(n) asm volatile("s_waitcnt vmcnt(" #n ")" ::: "memory")
; #define PG8_WAIT_L(n) asm volatile("s_waitcnt lgkmcnt(" #n ")" ::: "memory")
; #define PG8_BAR __builtin_amdgcn_s_barrier()
; #define PG8_SCHED __builtin_amdgcn_sched_barrier(0)
; template <int MODE, class EpiT, class Sched>
; __device__ __forceinline__ void gemm_phase(LAS unsigned char* lds, const Gemm g, const Sched& S, const EpiT& E) {
;     ...
;             PG8_STAGE(PG8_SB(0, 1), b2 + hstep, voffB);
;             PG8_WAIT_V(6); PG8_BAR; PG8_MMA(1, 1, At, B1); PG8_BAR;
;             PG8_LDB(B0, 1, 0); PG8_SCHED; PG8_LDA(At, 1, 0); PG8_STAGE(PG8_SA(0, 1), a2 + hstep, voffA);
;             PG8_WAIT_L(8); PG8_BAR; PG8_WAIT_L(0); PG8_MMA(0, 0, At, B0); PG8_BAR; PG8_SCHED;
;             PG8_LDB(B1, 1, 1); PG8_STAGE(PG8_SB(1, 0), b3, voffB);
;             PG8_BAR; PG8_WAIT_L(0); PG8_MMA(0, 1, At, B1); PG8_BAR;
;             PG8_LDA(At, 1, 1); PG8_STAGE(PG8_SA(1, 0), a3, voffA);
	s_add_u32 s52, s52, s38
	s_addc_u32 s53, s53, 0
	s_add_i32 s30, s30, s68
	v_lshl_add_u64 v[236:237], s[52:53], 0, v[0:1]
	s_mov_b32 m0, s30
	v_lshl_add_u64 v[238:239], s[52:53], 0, v[182:183]
	global_load_lds_dwordx4 v[236:237], off
	s_add_i32 m0, s30, 0x2000
	s_nop 0
	global_load_lds_dwordx4 v[238:239], off
	s_waitcnt vmcnt(6)
	s_barrier
	v_mfma_f32_16x16x32_bf16 v[54:57], v[188:191], v[146:149], v[54:57]
	v_mfma_f32_16x16x32_bf16 v[50:53], v[196:199], v[146:149], v[50:53]
	v_mfma_f32_16x16x32_bf16 v[38:41], v[188:191], v[154:157], v[38:41]
	v_mfma_f32_16x16x32_bf16 v[34:37], v[196:199], v[154:157], v[34:37]
	v_mfma_f32_16x16x32_bf16 v[22:25], v[188:191], v[162:165], v[22:25]
	v_mfma_f32_16x16x32_bf16 v[18:21], v[196:199], v[162:165], v[18:21]
	v_mfma_f32_16x16x32_bf16 v[6:9], v[188:191], v[170:173], v[6:9]
	v_mfma_f32_16x16x32_bf16 v[2:5], v[196:199], v[170:173], v[2:5]
	v_mfma_f32_16x16x32_bf16 v[54:57], v[192:195], v[150:153], v[54:57]
	v_mfma_f32_16x16x32_bf16 v[50:53], v[224:227], v[150:153], v[50:53]
	v_mfma_f32_16x16x32_bf16 v[38:41], v[192:195], v[158:161], v[38:41]
	v_mfma_f32_16x16x32_bf16 v[34:37], v[224:227], v[158:161], v[34:37]
	v_mfma_f32_16x16x32_bf16 v[22:25], v[192:195], v[166:169], v[22:25]
	v_mfma_f32_16x16x32_bf16 v[18:21], v[224:227], v[166:169], v[18:21]
	v_mfma_f32_16x16x32_bf16 v[6:9], v[192:195], v[174:177], v[6:9]
	v_mfma_f32_16x16x32_bf16 v[2:5], v[224:227], v[174:177], v[2:5]
	s_barrier
	s_add_i32 s30, 0, 0x18000
	v_add_u32_e32 v142, s30, v220
	ds_read_b128 v[130:133], v142
	ds_read_b128 v[134:137], v142 offset:1024
	ds_read_b128 v[138:141], v142 offset:2048
	ds_read_b128 v[142:145], v142 offset:3072
	ds_read_b128 v[146:149], v223 offset:32768
	ds_read_b128 v[150:153], v223 offset:33792
	ds_read_b128 v[154:157], v223 offset:34816
	ds_read_b128 v[158:161], v223 offset:35840
	ds_read_b128 v[162:165], v223 offset:36864
	ds_read_b128 v[166:169], v223 offset:37888
	ds_read_b128 v[170:173], v223 offset:38912
	ds_read_b128 v[174:177], v223 offset:39936
	s_add_u32 s44, s44, s38
	s_addc_u32 s45, s45, 0
	s_mov_b32 m0, s75
	v_lshl_add_u64 v[188:189], s[44:45], 0, v[0:1]
	global_load_lds_dwordx4 v[188:189], off
	v_lshl_add_u64 v[188:189], s[44:45], 0, v[182:183]
	s_mov_b32 m0, s9
	s_nop 0
	global_load_lds_dwordx4 v[188:189], off
	s_waitcnt lgkmcnt(8)
	s_barrier
	s_waitcnt lgkmcnt(0)
	v_mfma_f32_16x16x32_bf16 v[126:129], v[130:133], v[146:149], v[126:129]
	v_mfma_f32_16x16x32_bf16 v[122:125], v[138:141], v[146:149], v[122:125]
	v_mfma_f32_16x16x32_bf16 v[110:113], v[130:133], v[154:157], v[110:113]
	v_mfma_f32_16x16x32_bf16 v[106:109], v[138:141], v[154:157], v[106:109]
	v_mfma_f32_16x16x32_bf16 v[94:97], v[130:133], v[162:165], v[94:97]
	v_mfma_f32_16x16x32_bf16 v[90:93], v[138:141], v[162:165], v[90:93]
	v_mfma_f32_16x16x32_bf16 v[78:81], v[130:133], v[170:173], v[78:81]
	v_mfma_f32_16x16x32_bf16 v[74:77], v[138:141], v[170:173], v[74:77]
	v_mfma_f32_16x16x32_bf16 v[126:129], v[134:137], v[150:153], v[126:129]
	v_mfma_f32_16x16x32_bf16 v[122:125], v[142:145], v[150:153], v[122:125]
	v_mfma_f32_16x16x32_bf16 v[110:113], v[134:137], v[158:161], v[110:113]
	v_mfma_f32_16x16x32_bf16 v[106:109], v[142:145], v[158:161], v[106:109]
	v_mfma_f32_16x16x32_bf16 v[94:97], v[134:137], v[166:169], v[94:97]
	v_mfma_f32_16x16x32_bf16 v[90:93], v[142:145], v[166:169], v[90:93]
	v_mfma_f32_16x16x32_bf16 v[78:81], v[134:137], v[174:177], v[78:81]
	v_mfma_f32_16x16x32_bf16 v[74:77], v[142:145], v[174:177], v[74:77]
	s_barrier
	s_add_i32 s44, 0, 0x1c000
	s_add_i32 s30, s30, s68
	v_add_u32_e32 v200, s44, v220
	v_lshl_add_u64 v[228:229], v[228:229], 0, s[76:77]
	s_mov_b32 m0, s30
	ds_read_b128 v[188:191], v200
	ds_read_b128 v[192:195], v200 offset:1024
	ds_read_b128 v[196:199], v200 offset:2048
	ds_read_b128 v[224:227], v200 offset:3072
	global_load_lds_dwordx4 v[228:229], off
	v_lshl_add_u64 v[228:229], v[230:231], 0, s[76:77]
	s_add_i32 m0, s30, 0x2000
	s_nop 0
	global_load_lds_dwordx4 v[228:229], off
	s_barrier
	s_waitcnt lgkmcnt(0)
	v_mfma_f32_16x16x32_bf16 v[118:121], v[188:191], v[146:149], v[118:121]
	v_mfma_f32_16x16x32_bf16 v[114:117], v[196:199], v[146:149], v[114:117]
	v_mfma_f32_16x16x32_bf16 v[102:105], v[188:191], v[154:157], v[102:105]
	v_mfma_f32_16x16x32_bf16 v[98:101], v[196:199], v[154:157], v[98:101]
	v_mfma_f32_16x16x32_bf16 v[86:89], v[188:191], v[162:165], v[86:89]
	v_mfma_f32_16x16x32_bf16 v[82:85], v[196:199], v[162:165], v[82:85]
	v_mfma_f32_16x16x32_bf16 v[70:73], v[188:191], v[170:173], v[70:73]
	v_mfma_f32_16x16x32_bf16 v[66:69], v[196:199], v[170:173], v[66:69]
	v_mfma_f32_16x16x32_bf16 v[118:121], v[192:195], v[150:153], v[118:121]
	v_mfma_f32_16x16x32_bf16 v[114:117], v[224:227], v[150:153], v[114:117]
	v_mfma_f32_16x16x32_bf16 v[102:105], v[192:195], v[158:161], v[102:105]
	v_mfma_f32_16x16x32_bf16 v[98:101], v[224:227], v[158:161], v[98:101]
	v_mfma_f32_16x16x32_bf16 v[86:89], v[192:195], v[166:169], v[86:89]
	v_mfma_f32_16x16x32_bf16 v[82:85], v[224:227], v[166:169], v[82:85]
	v_mfma_f32_16x16x32_bf16 v[70:73], v[192:195], v[174:177], v[70:73]
	v_mfma_f32_16x16x32_bf16 v[66:69], v[224:227], v[174:177], v[66:69]
	s_barrier
	s_mov_b32 m0, s57
	v_lshl_add_u64 v[228:229], v[232:233], 0, s[76:77]
	ds_read_b128 v[146:149], v223 offset:49152
	ds_read_b128 v[150:153], v223 offset:50176
	ds_read_b128 v[154:157], v223 offset:51200
	ds_read_b128 v[158:161], v223 offset:52224
	ds_read_b128 v[162:165], v223 offset:53248
	ds_read_b128 v[166:169], v223 offset:54272
	ds_read_b128 v[170:173], v223 offset:55296
	ds_read_b128 v[174:177], v223 offset:56320
	global_load_lds_dwordx4 v[228:229], off
	v_lshl_add_u64 v[228:229], v[234:235], 0, s[76:77]
	s_mov_b32 m0, s60
	s_nop 0
	global_load_lds_dwordx4 v[228:229], off
	s_barrier
;     __device__ __forceinline__ void scales2(const Unit& u, int wr, int fr, int fq, float& sA, float& sB) const {
;         const int rowA = u.pm * BM + wr * 64 + fq * 16 + fr;
;         const f32x4* pa = (const f32x4*)(ssq_in + (size_t)rowA * 16); const f32x4* pb = (const f32x4*)(ssq_in + (size_t)(rowA + HALF) * 16);
;         const f32x4 a0 = pa[0], a1 = pa[1], a2 = pa[2], a3 = pa[3], b0 = pb[0], b1 = pb[1], b2 = pb[2], b3 = pb[3];
;         const float ta = (((a0[0] + a0[1]) + (a0[2] + a0[3])) + ((a1[0] + a1[1]) + (a1[2] + a1[3]))) + (((a2[0] + a2[1]) + (a2[2] + a2[3])) + ((a3[0] + a3[1]) + (a3[2] + a3[3])));
;         const float tb = (((b0[0] + b0[1]) + (b0[2] + b0[3])) + ((b1[0] + b1[1]) + (b1[2] + b1[3]))) + (((b2[0] + b2[1]) + (b2[2] + b2[3])) + ((b3[0] + b3[1]) + (b3[2] + b3[3])));
;         sA = rsqrtf(ta * (1.0f / 1024.0f) + EPS); sB = rsqrtf(tb * (1.0f / 1024.0f) + EPS);
;     template <int mode> __device__ __forceinline__ void run(const f32x4 (&acc)[2][2][4][2], const Unit& u, int wr, int wc, int fr, int fq, const LAS float* sc) const {
;     ...
;             if (mode == 4) scales2(u, wr, fr, fq, sA, sB);
;             f32x4 bvv[4];
; #pragma unroll
;             for (int q = 0; q < 4; ++q) bvv[q] = (mode != 4 && bias) ? *(const f32x4*)(bias + col0 + (q >> 1) * HALF + (q & 1) * 4) : (f32x4){0.f, 0.f, 0.f, 0.f};
;             f32x4 xi[2][4]; u32x4 pq[2][2]; u32x4 xh[2][2], xl[2][2];
;             {
;                 const size_t off = (size_t)row0 * D + col0;
; #pragma unroll
;                 for (int bj = 0; bj < 2; ++bj) {
;                     const size_t o = off + bj * HALF;
;                     if (mode == 5) { xi[0][2 * bj] = *(const f32x4*)(xin + o); xi[0][2 * bj + 1] = *(const f32x4*)(xin + o + 4); }
;                     else { xh[0][bj] = *(const u32x4*)(hin + o); xl[0][bj] = *(const u32x4*)(lin + o); }
;                     if (mode == 4) pq[0][bj] = *(const u32x4*)(ob + o);
;                 }
;             }
; #pragma unroll
;             for (int g = 0; g < 8; ++g) {
;                 const int ai = g >> 2, m = g & 3, cb = g & 1, nb = cb ^ 1;
;                 const int row = row0 + ai * HALF + m * 16;
;                 const size_t off = (size_t)row * D + col0;
;                 if (g < 7) {
;                     const size_t offn = (size_t)(row0 + ((g + 1) >> 2) * HALF + ((g + 1) & 3) * 16) * D + col0;
; #pragma unroll
	s_waitcnt lgkmcnt(0)
	v_mfma_f32_16x16x32_bf16 v[62:65], v[130:133], v[146:149], v[62:65]
	v_mfma_f32_16x16x32_bf16 v[58:61], v[138:141], v[146:149], v[58:61]
	v_mfma_f32_16x16x32_bf16 v[46:49], v[130:133], v[154:157], v[46:49]
	v_mfma_f32_16x16x32_bf16 v[42:45], v[138:141], v[154:157], v[42:45]
	v_mfma_f32_16x16x32_bf16 v[30:33], v[130:133], v[162:165], v[30:33]
	v_mfma_f32_16x16x32_bf16 v[26:29], v[138:141], v[162:165], v[26:29]
	v_mfma_f32_16x16x32_bf16 v[14:17], v[130:133], v[170:173], v[14:17]
	v_mfma_f32_16x16x32_bf16 v[10:13], v[138:141], v[170:173], v[10:13]
	v_mfma_f32_16x16x32_bf16 v[62:65], v[134:137], v[150:153], v[62:65]
	v_mfma_f32_16x16x32_bf16 v[58:61], v[142:145], v[150:153], v[58:61]
	v_mfma_f32_16x16x32_bf16 v[46:49], v[134:137], v[158:161], v[46:49]
	v_mfma_f32_16x16x32_bf16 v[42:45], v[142:145], v[158:161], v[42:45]
	v_mfma_f32_16x16x32_bf16 v[30:33], v[134:137], v[166:169], v[30:33]
	v_mfma_f32_16x16x32_bf16 v[26:29], v[142:145], v[166:169], v[26:29]
	v_mfma_f32_16x16x32_bf16 v[14:17], v[134:137], v[174:177], v[14:17]
	v_mfma_f32_16x16x32_bf16 v[10:13], v[142:145], v[174:177], v[10:13]
	s_barrier
	s_add_i32 s30, s44, s68
	v_lshl_add_u64 v[130:131], v[236:237], 0, s[76:77]
	s_mov_b32 m0, s30
	s_nop 0
	global_load_lds_dwordx4 v[130:131], off
	v_lshl_add_u64 v[130:131], v[238:239], 0, s[76:77]
	s_add_i32 m0, s30, 0x2000
	s_nop 0
	global_load_lds_dwordx4 v[130:131], off
	s_waitcnt vmcnt(6)
	s_barrier
	v_mfma_f32_16x16x32_bf16 v[54:57], v[188:191], v[146:149], v[54:57]
	v_mfma_f32_16x16x32_bf16 v[50:53], v[196:199], v[146:149], v[50:53]
	v_mfma_f32_16x16x32_bf16 v[38:41], v[188:191], v[154:157], v[38:41]
	v_mfma_f32_16x16x32_bf16 v[34:37], v[196:199], v[154:157], v[34:37]
	v_mfma_f32_16x16x32_bf16 v[22:25], v[188:191], v[162:165], v[22:25]
	v_mfma_f32_16x16x32_bf16 v[18:21], v[196:199], v[162:165], v[18:21]
	v_mfma_f32_16x16x32_bf16 v[6:9], v[188:191], v[170:173], v[6:9]
	v_mfma_f32_16x16x32_bf16 v[2:5], v[196:199], v[170:173], v[2:5]
	v_mfma_f32_16x16x32_bf16 v[54:57], v[192:195], v[150:153], v[54:57]
	v_mfma_f32_16x16x32_bf16 v[50:53], v[224:227], v[150:153], v[50:53]
	v_mfma_f32_16x16x32_bf16 v[38:41], v[192:195], v[158:161], v[38:41]
	v_mfma_f32_16x16x32_bf16 v[34:37], v[224:227], v[158:161], v[34:37]
	v_mfma_f32_16x16x32_bf16 v[22:25], v[192:195], v[166:169], v[22:25]
	v_mfma_f32_16x16x32_bf16 v[18:21], v[224:227], v[166:169], v[18:21]
	v_mfma_f32_16x16x32_bf16 v[6:9], v[192:195], v[174:177], v[6:9]
	v_mfma_f32_16x16x32_bf16 v[2:5], v[224:227], v[174:177], v[2:5]
	s_barrier
	s_add_u32 s4, s4, 0x100
	s_addc_u32 s5, s5, 0
	s_add_u32 s23, s23, 0x100
	s_addc_u32 s24, s24, 0
	s_cmp_ge_u32 s89, s21
	s_mov_b32 s30, s89
	s_cbranch_scc0 .LBB0_159
	s_lshl_b32 s4, s22, 8
	s_add_i32 s4, s4, s56
	v_or_b32_e32 v130, s4, v222
	v_ashrrev_i32_e32 v131, 31, v130
	v_lshlrev_b64 v[130:131], 6, v[130:131]
	v_lshl_add_u64 v[146:147], s[66:67], 0, v[130:131]
	global_load_dwordx4 v[130:133], v[146:147], off offset:16
	global_load_dwordx4 v[134:137], v[146:147], off offset:48
	global_load_dwordx4 v[138:141], v[146:147], off
	global_load_dwordx4 v[142:145], v[146:147], off offset:32
	v_or_b32_e32 v192, s4, v181
	s_mov_b64 s[4:5], 0x2000
	v_lshl_add_u64 v[158:159], v[146:147], 0, s[4:5]
	v_add_co_u32_e32 v146, vcc, 0x2000, v146
	s_mov_b32 s4, 0x3a800000
	s_nop 0
	v_addc_co_u32_e32 v147, vcc, 0, v147, vcc
	global_load_dwordx4 v[146:149], v[146:147], off
	s_nop 0
	global_load_dwordx4 v[150:153], v[158:159], off offset:16
	global_load_dwordx4 v[154:157], v[158:159], off offset:48
	s_nop 0
	global_load_dwordx4 v[158:161], v[158:159], off offset:32
	v_lshl_or_b32 v188, s2, 8, v221
	v_ashrrev_i32_e32 v193, 31, v192
	v_ashrrev_i32_e32 v189, 31, v188
	v_or_b32_e32 v194, 16, v192
	v_ashrrev_i32_e32 v195, 31, v194
	s_waitcnt vmcnt(0)
	v_mov_b32_e32 v162, v138
	v_mov_b32_e32 v163, v142
	v_mov_b32_e32 v142, v139
	v_pk_add_f32 v[138:139], v[162:163], v[142:143]
	v_mov_b32_e32 v142, v140
	v_mov_b32_e32 v143, v144
	v_mov_b32_e32 v144, v141
	v_pk_add_f32 v[140:141], v[142:143], v[144:145]
	s_nop 0
	v_pk_add_f32 v[138:139], v[138:139], v[140:141]
	v_mov_b32_e32 v140, v130
	v_mov_b32_e32 v141, v134
	v_mov_b32_e32 v134, v131
	v_pk_add_f32 v[130:131], v[140:141], v[134:135]
	v_mov_b32_e32 v134, v132
	v_mov_b32_e32 v135, v136
	v_mov_b32_e32 v136, v133
	v_pk_add_f32 v[132:133], v[134:135], v[136:137]
	v_mov_b32_e32 v134, v148
	v_pk_add_f32 v[130:131], v[130:131], v[132:133]
	v_mov_b32_e32 v132, v146
	v_mov_b32_e32 v133, v158
	v_mov_b32_e32 v158, v147
	v_mov_b32_e32 v135, v160
	v_mov_b32_e32 v160, v149
	v_pk_add_f32 v[132:133], v[132:133], v[158:159]
	v_pk_add_f32 v[134:135], v[134:135], v[160:161]
	v_mov_b32_e32 v136, v152
	v_pk_add_f32 v[132:133], v[132:133], v[134:135]
	v_mov_b32_e32 v134, v150
	v_mov_b32_e32 v135, v154
	v_mov_b32_e32 v154, v151
	v_mov_b32_e32 v137, v156
	v_mov_b32_e32 v156, v153
	v_pk_add_f32 v[134:135], v[134:135], v[154:155]
	v_pk_add_f32 v[136:137], v[136:137], v[156:157]
	v_pk_add_f32 v[130:131], v[138:139], v[130:131]
	v_pk_add_f32 v[134:135], v[134:135], v[136:137]
	s_nop 0
	v_pk_add_f32 v[132:133], v[132:133], v[134:135]
	v_mov_b32_e32 v135, v130
	v_mov_b32_e32 v134, v132
	v_mov_b32_e32 v130, v133
	v_pk_add_f32 v[130:131], v[134:135], v[130:131]
	s_nop 0
	v_pk_fma_f32 v[190:191], v[130:131], s[4:5], v[178:179] op_sel_hi:[1,0,0]
	s_mov_b32 s4, 0x800000
	v_mul_f32_e32 v130, 0x4b800000, v191
	v_cmp_gt_f32_e64 s[44:45], s4, v191
	v_cmp_gt_f32_e32 vcc, s4, v190
	s_nop 0
	v_cndmask_b32_e64 v130, v191, v130, s[44:45]
	v_rsq_f32_e32 v130, v130
	s_nop 0
	v_mul_f32_e32 v131, 0x45800000, v130
	v_cndmask_b32_e64 v226, v130, v131, s[44:45]
	v_lshlrev_b64 v[130:131], 10, v[192:193]
	v_lshl_add_u64 v[130:131], v[130:131], 0, v[188:189]
	v_lshlrev_b64 v[198:199], 1, v[130:131]
	v_lshl_add_u64 v[130:131], s[34:35], 0, v[198:199]
	v_lshl_add_u64 v[132:133], s[92:93], 0, v[198:199]
	global_load_dwordx4 v[170:173], v[130:131], off
	global_load_dwordx4 v[174:177], v[132:133], off
	v_lshl_add_u64 v[134:135], s[6:7], 0, v[198:199]
	global_load_dwordx4 v[166:169], v[134:135], off
	global_load_dwordx4 v[158:161], v[130:131], off offset:256
	global_load_dwordx4 v[162:165], v[132:133], off offset:256
	global_load_dwordx4 v[146:149], v[134:135], off offset:256
	v_and_b32_e32 v130, 64, v205
	v_or_b32_e32 v200, v130, v181
	v_lshlrev_b32_e32 v225, 2, v200
	ds_bpermute_b32 v200, v225, v226
	v_xor_b32_e32 v131, 16, v205
	v_add_u32_e32 v130, 64, v130
	v_cmp_lt_i32_e64 s[44:45], v131, v130
	s_waitcnt lgkmcnt(0)
;     template <int mode> __device__ __forceinline__ void run(const f32x4 (&acc)[2][2][4][2], const Unit& u, int wr, int wc, int fr, int fq, const LAS float* sc) const {
;     ...
; #pragma unroll
;             for (int g = 0; g < 8; ++g) {
;                 const int ai = g >> 2, m = g & 3, cb = g & 1, nb = cb ^ 1;
;                 const int row = row0 + ai * HALF + m * 16;
;                 const size_t off = (size_t)row * D + col0;
;                 if (g < 7) {
;                     const size_t offn = (size_t)(row0 + ((g + 1) >> 2) * HALF + ((g + 1) & 3) * 16) * D + col0;
; #pragma unroll
;                     for (int bj = 0; bj < 2; ++bj) {
;                         const size_t o = offn + bj * HALF;
;                         if (mode == 5) { xi[nb][2 * bj] = *(const f32x4*)(xin + o); xi[nb][2 * bj + 1] = *(const f32x4*)(xin + o + 4); }
;                         else { xh[nb][bj] = *(const u32x4*)(hin + o); xl[nb][bj] = *(const u32x4*)(lin + o); }
;                         if (mode == 4) pq[nb][bj] = *(const u32x4*)(ob + o);
;                     }
;                 }
;                 float s = 1.f;
;                 if (mode == 4) s = __shfl(ai ? sB : sA, m * 16 + fr);
;                 float ss = 0.f;
; #pragma unroll
;                 for (int bj = 0; bj < 2; ++bj) {
;                     u32x4 wh, wl;
; #pragma unroll
;                     for (int n = 0; n < 2; ++n) {
;                         const int q = 2 * bj + n;
;                         const unsigned h0 = n ? xh[cb][bj].z : xh[cb][bj].x, h1 = n ? xh[cb][bj].w : xh[cb][bj].y, l0 = n ? xl[cb][bj].z : xl[cb][bj].x, l1 = n ? xl[cb][bj].w : xl[cb][bj].y;
;                         f32x4 xo;
;                         if (mode == 5) xo = xi[cb][q];
;                         else { xo[0] = bf_lo(h0) + bf_lo(l0); xo[1] = bf_hi(h0) + bf_hi(l0); xo[2] = bf_lo(h1) + bf_lo(l1); xo[3] = bf_hi(h1) + bf_hi(l1); }
;                         f32x4 v;
;                         if (mode != 4) v = xo + acc[ai][bj][m][n] * alpha + bvv[q];
;                         else {
;                             const f32x4 a = acc[ai][bj][m][n] * s;
;                             const unsigned p0 = n ? pq[cb][bj].z : pq[cb][bj].x, p1 = n ? pq[cb][bj].w : pq[cb][bj].y;
;                             v[0] = xo[0] + sigmoidf_(a[0]) * bf_lo(p0); v[1] = xo[1] + sigmoidf_(a[1]) * bf_hi(p0);
	v_pk_mul_f32 v[126:127], v[126:127], v[200:201] op_sel_hi:[1,0]
	v_cndmask_b32_e64 v131, v205, v131, s[44:45]
	v_lshlrev_b32_e32 v191, 2, v131
	v_xor_b32_e32 v131, 32, v205
	v_mul_f32_e32 v126, 0xbfb8aa3b, v126
	v_cmp_lt_i32_e64 s[44:45], v131, v130
	v_exp_f32_e32 v126, v126
	v_pk_mul_f32 v[128:129], v[128:129], v[200:201] op_sel_hi:[1,0]
	v_cndmask_b32_e64 v130, v205, v131, s[44:45]
	v_lshlrev_b32_e32 v224, 2, v130
	v_lshlrev_b64 v[130:131], 10, v[194:195]
	v_lshl_add_u64 v[130:131], v[130:131], 0, v[188:189]
	v_lshlrev_b64 v[196:197], 1, v[130:131]
	v_add_f32_e32 v126, 1.0, v126
	v_lshl_add_u64 v[130:131], s[34:35], 0, v[196:197]
	v_lshl_add_u64 v[132:133], s[92:93], 0, v[196:197]
	v_lshl_add_u64 v[228:229], s[6:7], 0, v[196:197]
	v_rcp_f32_e32 v126, v126
	global_load_dwordx4 v[150:153], v[130:131], off
	global_load_dwordx4 v[154:157], v[132:133], off
	global_load_dwordx4 v[142:145], v[228:229], off
	global_load_dwordx4 v[134:137], v[130:131], off offset:256
	global_load_dwordx4 v[138:141], v[132:133], off offset:256
	s_nop 0
	global_load_dwordx4 v[130:133], v[228:229], off offset:256
	v_pk_mul_f32 v[122:123], v[122:123], v[200:201] op_sel_hi:[1,0]
	v_pk_mul_f32 v[124:125], v[124:125], v[200:201] op_sel_hi:[1,0]
	v_mul_f32_e32 v122, 0xbfb8aa3b, v122
	v_exp_f32_e32 v122, v122
	v_pk_mul_f32 v[118:119], v[118:119], v[200:201] op_sel_hi:[1,0]
	v_pk_mul_f32 v[120:121], v[120:121], v[200:201] op_sel_hi:[1,0]
	v_mul_f32_e32 v118, 0xbfb8aa3b, v118
	v_add_f32_e32 v122, 1.0, v122
	v_rcp_f32_e32 v122, v122
	v_exp_f32_e32 v118, v118
	v_pk_mul_f32 v[114:115], v[114:115], v[200:201] op_sel_hi:[1,0]
	v_pk_mul_f32 v[116:117], v[116:117], v[200:201] op_sel_hi:[1,0]
	v_mul_f32_e32 v114, 0xbfb8aa3b, v114
	v_add_f32_e32 v118, 1.0, v118
	v_rcp_f32_e32 v118, v118
	v_exp_f32_e32 v114, v114
	s_lshl_b32 s44, s2, 2
	s_ashr_i32 s45, s44, 31
	v_add_f32_e32 v114, 1.0, v114
	v_rcp_f32_e32 v114, v114
	s_waitcnt vmcnt(11)
	v_lshlrev_b32_e32 v227, 16, v170
	s_waitcnt vmcnt(10)
	v_lshlrev_b32_e32 v228, 16, v174
	v_and_b32_e32 v174, 0xffff0000, v174
	v_and_b32_e32 v170, 0xffff0000, v170
	v_add_f32_e32 v227, v228, v227
	v_add_f32_e32 v170, v174, v170
	v_lshlrev_b32_e32 v174, 16, v171
	v_lshlrev_b32_e32 v228, 16, v175
	v_and_b32_e32 v175, 0xffff0000, v175
	v_and_b32_e32 v171, 0xffff0000, v171
	v_add_f32_e32 v171, v175, v171
	s_waitcnt vmcnt(9)
	v_lshlrev_b32_e32 v175, 16, v166
	v_fmac_f32_e32 v227, v126, v175
	v_mul_f32_e32 v126, 0xbfb8aa3b, v127
	v_exp_f32_e32 v126, v126
	v_and_b32_e32 v127, 0xffff0000, v166
	v_add_f32_e32 v174, v228, v174
	v_add_f32_e32 v126, 1.0, v126
	v_rcp_f32_e32 v126, v126
	s_nop 0
	v_fmac_f32_e32 v170, v126, v127
	v_mul_f32_e32 v126, 0xbfb8aa3b, v128
	v_exp_f32_e32 v126, v126
	v_lshlrev_b32_e32 v127, 16, v167
	v_add_f32_e32 v126, 1.0, v126
	v_rcp_f32_e32 v126, v126
	s_nop 0
	v_fmac_f32_e32 v174, v126, v127
	v_mul_f32_e32 v126, 0xbfb8aa3b, v129
	v_exp_f32_e32 v126, v126
	v_and_b32_e32 v127, 0xffff0000, v167
	v_add_f32_e32 v126, 1.0, v126
	v_rcp_f32_e32 v126, v126
	s_nop 0
	v_fmac_f32_e32 v171, v126, v127
	v_cvt_pk_bf16_f32 v126, v227, v170
	v_cvt_pk_bf16_f32 v127, v174, v171
	s_nop 0
	v_lshlrev_b32_e32 v128, 16, v126
	v_and_b32_e32 v129, 0xffff0000, v126
	v_sub_f32_e32 v128, v227, v128
	v_sub_f32_e32 v129, v170, v129
	v_cvt_pk_bf16_f32 v166, v128, v129
	v_lshlrev_b32_e32 v128, 16, v127
	v_and_b32_e32 v129, 0xffff0000, v127
	v_sub_f32_e32 v128, v174, v128
	v_sub_f32_e32 v129, v171, v129
	v_cvt_pk_bf16_f32 v167, v128, v129
	v_mul_f32_e32 v128, v170, v170
	v_mul_f32_e32 v129, v171, v171
	v_fmac_f32_e32 v128, v227, v227
	v_fmac_f32_e32 v129, v174, v174
	v_add_f32_e32 v170, v128, v129
	v_lshlrev_b32_e32 v128, 16, v172
	v_lshlrev_b32_e32 v129, 16, v176
	v_add_f32_e32 v171, v129, v128
	v_and_b32_e32 v128, 0xffff0000, v176
	v_and_b32_e32 v129, 0xffff0000, v172
	v_add_f32_e32 v172, v128, v129
	v_lshlrev_b32_e32 v128, 16, v173
	v_lshlrev_b32_e32 v129, 16, v177
	v_add_f32_e32 v174, v129, v128
	v_and_b32_e32 v128, 0xffff0000, v177
	v_and_b32_e32 v129, 0xffff0000, v173
	v_add_f32_e32 v173, v128, v129
	v_lshlrev_b32_e32 v128, 16, v168
	v_fmac_f32_e32 v171, v122, v128
	v_mul_f32_e32 v122, 0xbfb8aa3b, v123
	v_exp_f32_e32 v122, v122
	v_and_b32_e32 v123, 0xffff0000, v168
	v_add_f32_e32 v122, 1.0, v122
	v_rcp_f32_e32 v122, v122
	s_nop 0
	v_fmac_f32_e32 v172, v122, v123
	v_mul_f32_e32 v122, 0xbfb8aa3b, v124
	v_exp_f32_e32 v122, v122
	v_lshlrev_b32_e32 v123, 16, v169
	v_cvt_pk_bf16_f32 v128, v171, v172
	v_add_f32_e32 v122, 1.0, v122
	v_rcp_f32_e32 v122, v122
	s_nop 0
	v_fmac_f32_e32 v174, v122, v123
	v_mul_f32_e32 v122, 0xbfb8aa3b, v125
	v_exp_f32_e32 v122, v122
	v_and_b32_e32 v123, 0xffff0000, v169
	v_lshl_add_u64 v[124:125], s[28:29], 0, v[198:199]
	v_add_f32_e32 v122, 1.0, v122
	v_rcp_f32_e32 v122, v122
	s_nop 0
	v_fmac_f32_e32 v173, v122, v123
	v_lshlrev_b32_e32 v122, 16, v128
	v_and_b32_e32 v123, 0xffff0000, v128
	v_sub_f32_e32 v122, v171, v122
	v_sub_f32_e32 v123, v172, v123
	v_cvt_pk_bf16_f32 v129, v174, v173
	v_cvt_pk_bf16_f32 v168, v122, v123
	s_nop 0
	v_lshlrev_b32_e32 v122, 16, v129
	v_and_b32_e32 v123, 0xffff0000, v129
	v_sub_f32_e32 v122, v174, v122
	v_sub_f32_e32 v123, v173, v123
	v_cvt_pk_bf16_f32 v169, v122, v123
	v_mul_f32_e32 v122, v172, v172
	v_mul_f32_e32 v123, v173, v173
	v_fmac_f32_e32 v122, v171, v171
	v_fmac_f32_e32 v123, v174, v174
	v_add_f32_e32 v122, v122, v123
	v_add_f32_e32 v170, v170, v122
	v_lshl_add_u64 v[122:123], s[10:11], 0, v[198:199]
	global_store_dwordx4 v[122:123], v[126:129], off
	global_store_dwordx4 v[124:125], v[166:169], off
	s_waitcnt vmcnt(10)
; __device__ __forceinline__ float bf_lo(unsigned w) { return __uint_as_float(w << 16); }
; __device__ __forceinline__ float bf_hi(unsigned w) { return __uint_as_float(w & 0xffff0000u); }
;     template <int mode> __device__ __forceinline__ void run(const f32x4 (&acc)[2][2][4][2], const Unit& u, int wr, int wc, int fr, int fq, const LAS float* sc) const {
;     ...
;                 for (int bj = 0; bj < 2; ++bj) {
;                     u32x4 wh, wl;
; #pragma unroll
;                     for (int n = 0; n < 2; ++n) {
;                         const int q = 2 * bj + n;
;                         const unsigned h0 = n ? xh[cb][bj].z : xh[cb][bj].x, h1 = n ? xh[cb][bj].w : xh[cb][bj].y, l0 = n ? xl[cb][bj].z : xl[cb][bj].x, l1 = n ? xl[cb][bj].w : xl[cb][bj].y;
;                         f32x4 xo;
;                         if (mode == 5) xo = xi[cb][q];
;                         else { xo[0] = bf_lo(h0) + bf_lo(l0); xo[1] = bf_hi(h0) + bf_hi(l0); xo[2] = bf_lo(h1) + bf_lo(l1); xo[3] = bf_hi(h1) + bf_hi(l1); }
;                         f32x4 v;
;                         if (mode != 4) v = xo + acc[ai][bj][m][n] * alpha + bvv[q];
;                         else {
;                             const f32x4 a = acc[ai][bj][m][n] * s;
;                             const unsigned p0 = n ? pq[cb][bj].z : pq[cb][bj].x, p1 = n ? pq[cb][bj].w : pq[cb][bj].y;
;                             v[0] = xo[0] + sigmoidf_(a[0]) * bf_lo(p0); v[1] = xo[1] + sigmoidf_(a[1]) * bf_hi(p0);
;                             v[2] = xo[2] + sigmoidf_(a[2]) * bf_lo(p1); v[3] = xo[3] + sigmoidf_(a[3]) * bf_hi(p1);
;                         }
;                         const unsigned w0 = pk2(v[0], v[1]), w1 = pk2(v[2], v[3]);
;                         const unsigned m0 = pk2(v[0] - bf_lo(w0), v[1] - bf_hi(w0)), m1 = pk2(v[2] - bf_lo(w1), v[3] - bf_hi(w1));
;                         if (n == 0) { wh.x = w0; wh.y = w1; wl.x = m0; wl.y = m1; } else { wh.z = w0; wh.w = w1; wl.z = m0; wl.w = m1; }
;                         ss += (v[0] * v[0] + v[1] * v[1]) + (v[2] * v[2] + v[3] * v[3]);
;                     }
;                     *(u32x4*)(xb + off + bj * HALF) = wh;
;                     *(u32x4*)(lout + off + bj * HALF) = wl;
;                 }
;                 ss += __shfl_xor(ss, 16); ss += __shfl_xor(ss, 32);
;                 if (fq == 0) ssq_out[(size_t)row * 16 + u.pn * 4 + wc] = ss;
	v_lshlrev_b32_e32 v126, 16, v158
	s_waitcnt vmcnt(9)
	v_lshlrev_b32_e32 v127, 16, v162
	v_add_f32_e32 v128, v127, v126
	v_and_b32_e32 v126, 0xffff0000, v162
	v_and_b32_e32 v127, 0xffff0000, v158
	v_add_f32_e32 v129, v126, v127
	v_lshlrev_b32_e32 v126, 16, v159
	v_lshlrev_b32_e32 v127, 16, v163
	v_add_f32_e32 v158, v127, v126
	v_and_b32_e32 v126, 0xffff0000, v163
	v_and_b32_e32 v127, 0xffff0000, v159
	v_add_f32_e32 v159, v126, v127
	s_waitcnt vmcnt(8)
	v_lshlrev_b32_e32 v126, 16, v146
	v_fmac_f32_e32 v128, v118, v126
	v_mul_f32_e32 v118, 0xbfb8aa3b, v119
	v_exp_f32_e32 v118, v118
	v_and_b32_e32 v119, 0xffff0000, v146
	v_add_f32_e32 v118, 1.0, v118
	v_rcp_f32_e32 v118, v118
	s_nop 0
	v_fmac_f32_e32 v129, v118, v119
	v_mul_f32_e32 v118, 0xbfb8aa3b, v120
	v_exp_f32_e32 v118, v118
	v_lshlrev_b32_e32 v119, 16, v147
	v_add_f32_e32 v118, 1.0, v118
	v_rcp_f32_e32 v118, v118
	s_nop 0
	v_fmac_f32_e32 v158, v118, v119
	v_mul_f32_e32 v118, 0xbfb8aa3b, v121
	v_exp_f32_e32 v118, v118
	v_and_b32_e32 v119, 0xffff0000, v147
	v_add_f32_e32 v118, 1.0, v118
	v_rcp_f32_e32 v118, v118
	s_nop 0
	v_fmac_f32_e32 v159, v118, v119
	v_cvt_pk_bf16_f32 v118, v128, v129
	v_cvt_pk_bf16_f32 v119, v158, v159
	s_nop 0
	v_lshlrev_b32_e32 v120, 16, v118
	v_and_b32_e32 v121, 0xffff0000, v118
	v_sub_f32_e32 v120, v128, v120
	v_sub_f32_e32 v121, v129, v121
	v_cvt_pk_bf16_f32 v126, v120, v121
	v_lshlrev_b32_e32 v120, 16, v119
	v_and_b32_e32 v121, 0xffff0000, v119
	v_sub_f32_e32 v120, v158, v120
	v_sub_f32_e32 v121, v159, v121
	v_cvt_pk_bf16_f32 v127, v120, v121
	v_mul_f32_e32 v120, v129, v129
	v_mul_f32_e32 v121, v159, v159
	v_fmac_f32_e32 v120, v128, v128
	v_fmac_f32_e32 v121, v158, v158
	v_add_f32_e32 v120, v120, v121
	v_add_f32_e32 v146, v120, v170
	v_lshlrev_b32_e32 v120, 16, v160
	v_lshlrev_b32_e32 v121, 16, v164
	v_add_f32_e32 v147, v121, v120
	v_and_b32_e32 v120, 0xffff0000, v164
	v_and_b32_e32 v121, 0xffff0000, v160
	v_add_f32_e32 v158, v120, v121
	v_lshlrev_b32_e32 v120, 16, v161
	v_lshlrev_b32_e32 v121, 16, v165
	v_add_f32_e32 v159, v121, v120
	v_and_b32_e32 v120, 0xffff0000, v165
	v_and_b32_e32 v121, 0xffff0000, v161
	v_add_f32_e32 v160, v120, v121
	v_lshlrev_b32_e32 v120, 16, v148
	v_fmac_f32_e32 v147, v114, v120
	v_mul_f32_e32 v114, 0xbfb8aa3b, v115
	v_exp_f32_e32 v114, v114
	v_and_b32_e32 v115, 0xffff0000, v148
	v_add_f32_e32 v114, 1.0, v114
	v_rcp_f32_e32 v114, v114
	s_nop 0
	v_fmac_f32_e32 v158, v114, v115
	v_mul_f32_e32 v114, 0xbfb8aa3b, v116
	v_exp_f32_e32 v114, v114
	v_lshlrev_b32_e32 v115, 16, v149
	v_cvt_pk_bf16_f32 v120, v147, v158
	v_add_f32_e32 v114, 1.0, v114
	v_rcp_f32_e32 v114, v114
	s_nop 0
	v_fmac_f32_e32 v159, v114, v115
	v_mul_f32_e32 v114, 0xbfb8aa3b, v117
	v_exp_f32_e32 v114, v114
	v_and_b32_e32 v115, 0xffff0000, v149
	v_add_f32_e32 v114, 1.0, v114
	v_rcp_f32_e32 v114, v114
	s_nop 0
	v_fmac_f32_e32 v160, v114, v115
	v_lshlrev_b32_e32 v114, 16, v120
	v_and_b32_e32 v115, 0xffff0000, v120
	v_sub_f32_e32 v114, v147, v114
	v_sub_f32_e32 v115, v158, v115
	v_cvt_pk_bf16_f32 v121, v159, v160
	v_cvt_pk_bf16_f32 v128, v114, v115
	s_nop 0
	v_lshlrev_b32_e32 v114, 16, v121
	v_and_b32_e32 v115, 0xffff0000, v121
	v_sub_f32_e32 v114, v159, v114
	v_sub_f32_e32 v115, v160, v115
	v_cvt_pk_bf16_f32 v129, v114, v115
	v_mul_f32_e32 v114, v158, v158
	v_mul_f32_e32 v115, v160, v160
	v_fmac_f32_e32 v114, v147, v147
	v_fmac_f32_e32 v115, v159, v159
	v_add_f32_e32 v114, v114, v115
	v_add_f32_e32 v114, v114, v146
	ds_bpermute_b32 v115, v191, v114
	global_store_dwordx4 v[122:123], v[118:121], off offset:256
	global_store_dwordx4 v[124:125], v[126:129], off offset:256
	s_waitcnt lgkmcnt(0)
	v_add_f32_e32 v114, v114, v115
	ds_bpermute_b32 v115, v224, v114
	s_and_saveexec_b64 s[4:5], s[40:41]
	s_cbranch_execz .LBB0_162
	v_lshlrev_b64 v[116:117], 6, v[192:193]
	v_lshl_add_u64 v[116:117], s[62:63], 0, v[116:117]
	v_lshl_add_u64 v[116:117], s[44:45], 2, v[116:117]
	s_lshl_b32 s24, s20, 2
	v_lshl_add_u64 v[116:117], v[116:117], 0, s[24:25]
	s_waitcnt lgkmcnt(0)
	v_add_f32_e32 v114, v114, v115
	global_store_dword v[116:117], v114, off

; #define PG8_STAGE(bufoff, gbase, voff) do { _Pragma("unroll") for (int _i = 0; _i < 2; ++_i) \
;         __builtin_amdgcn_global_load_lds((const unsigned*)((const char*)(gbase) + (voff)[_i]), (LAS unsigned*)(lds + (bufoff) + ldsw + _i * 8192), 16, 0, 0); } while (0)
; #define PG8_LDA(dst, b, h) do { _Pragma("unroll") for (int m = 0; m < 4; ++m) _Pragma("unroll") for (int k = 0; k < 2; ++k) dst[m][k] = *(const LAS bf16x8*)(lds + PG8_SA(b, h) + aoff + m * 2048 + k * 1024); } while (0)
; #define PG8_LDB(dst, b, h) do { _Pragma("unroll") for (int n = 0; n < 2; ++n) _Pragma("unroll") for (int k = 0; k < 2; ++k) dst[n][k] = *(const LAS bf16x8*)(lds + PG8_SB(b, h) + boff + n * 2048 + k * 1024); } while (0)
; #define PG8_MMA(ai, bj, At, Bt) do { __builtin_amdgcn_s_setprio(1); _Pragma("unroll") for (int m = 0; m < 4; ++m) _Pragma("unroll") for (int n = 0; n < 2; ++n) _Pragma("unroll") for (int k = 0; k < 2; ++k) \
;         acc[ai][bj][m][n] = __builtin_amdgcn_mfma_f32_16x16x32_bf16(Bt[n][k], At[m][k], acc[ai][bj][m][n], 0, 0, 0); __builtin_amdgcn_s_setprio(0); } while (0)
; #define PG8_WAIT_L(n) asm volatile("s_waitcnt lgkmcnt(" #n ")" ::: "memory")
; template <int MODE, class EpiT, class Sched>
; __device__ __forceinline__ void gemm_phase(LAS unsigned char* lds, const Gemm g, const Sched& S, const EpiT& E) {
;     ...
;         const bool has_next = S.next(ui + 1, nxt);
;         const char* nA = has_next ? (const char*)g.A + (size_t)nxt.pm * tstep : cA; const char* nB = has_next ? (const char*)g.Bt + (size_t)nxt.pn * tstep : cB;
;         for (int t = 0; t < nt; t += 2) {
;             const bool last = (t == nt - 2);
;             const char* a1 = cA + (size_t)(t + 1) * kstep;
;             const char* a2 = last ? nA : cA + (size_t)(t + 2) * kstep; const char* b2 = last ? nB : cB + (size_t)(t + 2) * kstep;
;             const char* a3 = a2 + kstep; const char* b3 = b2 + kstep;
;             PG8_LDB(B0, 0, 0); PG8_SCHED; PG8_LDA(At, 0, 0); PG8_STAGE(PG8_SA(1, 1), a1 + hstep, voffA);
;             PG8_WAIT_L(8); PG8_BAR; PG8_WAIT_L(0); PG8_MMA(0, 0, At, B0); PG8_BAR; PG8_SCHED;
;             PG8_LDB(B1, 0, 1); PG8_STAGE(PG8_SB(0, 0), b2, voffB);
;             PG8_BAR; PG8_WAIT_L(0); PG8_MMA(0, 1, At, B1); PG8_BAR;
;             PG8_LDA(At, 0, 1); PG8_STAGE(PG8_SA(0, 0), a2, voffA);
;             PG8_BAR; PG8_WAIT_L(0); PG8_MMA(1, 0, At, B0); PG8_BAR; PG8_SCHED;
.LBB0_195:
	s_add_i32 vcc_lo, s44, 2
	s_add_u32 s52, s4, 0x80
	s_addc_u32 s45, s5, 0
	s_add_i32 s58, 0, 0x10000
	v_add_u32_e32 v74, s58, v194
	ds_read_b128 v[58:61], v74
	ds_read_b128 v[62:65], v74 offset:1024
	ds_read_b128 v[70:73], v74 offset:2048
	ds_read_b128 v[74:77], v74 offset:3072
	ds_read_b128 v[138:141], v196
	ds_read_b128 v[142:145], v196 offset:1024
	ds_read_b128 v[146:149], v196 offset:2048
	ds_read_b128 v[150:153], v196 offset:3072
	ds_read_b128 v[162:165], v196 offset:4096
	ds_read_b128 v[166:169], v196 offset:5120
	ds_read_b128 v[170:173], v196 offset:6144
	ds_read_b128 v[184:187], v196 offset:7168
	s_cmp_eq_u32 s75, s44
	s_cselect_b32 s44, s68, s52
	s_cselect_b32 s45, s69, s45
	s_cselect_b32 s53, s47, s90
	s_cselect_b32 s52, s46, s89
	s_add_i32 m0, s21, 0xc000
	v_lshl_add_u64 v[188:189], s[4:5], 0, v[176:177]
	global_load_lds_dwordx4 v[188:189], off
	v_lshl_add_u64 v[188:189], s[4:5], 0, v[182:183]
	s_add_i32 m0, s21, 0xe000
	s_nop 0
	global_load_lds_dwordx4 v[188:189], off
	s_waitcnt lgkmcnt(8)
	s_barrier
	s_waitcnt lgkmcnt(0)
	v_mfma_f32_16x16x32_bf16 v[158:161], v[58:61], v[138:141], v[158:161]
	v_mfma_f32_16x16x32_bf16 v[154:157], v[70:73], v[138:141], v[154:157]
	v_mfma_f32_16x16x32_bf16 v[126:129], v[58:61], v[146:149], v[126:129]
	v_mfma_f32_16x16x32_bf16 v[122:125], v[70:73], v[146:149], v[122:125]
	v_mfma_f32_16x16x32_bf16 v[110:113], v[58:61], v[162:165], v[110:113]
	v_mfma_f32_16x16x32_bf16 v[106:109], v[70:73], v[162:165], v[106:109]
	v_mfma_f32_16x16x32_bf16 v[94:97], v[58:61], v[170:173], v[94:97]
	v_mfma_f32_16x16x32_bf16 v[90:93], v[70:73], v[170:173], v[90:93]
	v_mfma_f32_16x16x32_bf16 v[158:161], v[62:65], v[142:145], v[158:161]
	v_mfma_f32_16x16x32_bf16 v[154:157], v[74:77], v[142:145], v[154:157]
	v_mfma_f32_16x16x32_bf16 v[126:129], v[62:65], v[150:153], v[126:129]
	v_mfma_f32_16x16x32_bf16 v[122:125], v[74:77], v[150:153], v[122:125]
	v_mfma_f32_16x16x32_bf16 v[110:113], v[62:65], v[166:169], v[110:113]
	v_mfma_f32_16x16x32_bf16 v[106:109], v[74:77], v[166:169], v[106:109]
	v_mfma_f32_16x16x32_bf16 v[94:97], v[62:65], v[184:187], v[94:97]
	v_mfma_f32_16x16x32_bf16 v[90:93], v[74:77], v[184:187], v[90:93]
	s_barrier
	s_add_i32 s59, 0, 0x14000
	v_add_u32_e32 v192, s59, v194
	s_add_i32 s58, s58, s20
	ds_read_b128 v[188:191], v192
	ds_read_b128 v[220:223], v192 offset:1024
	ds_read_b128 v[224:227], v192 offset:2048
	ds_read_b128 v[228:231], v192 offset:3072
	v_lshl_add_u64 v[192:193], s[52:53], 0, v[0:1]
	s_mov_b32 m0, s58
	v_lshl_add_u64 v[198:199], s[52:53], 0, v[174:175]
	global_load_lds_dwordx4 v[192:193], off
	s_add_i32 m0, s58, 0x2000
	s_nop 0
	global_load_lds_dwordx4 v[198:199], off
	s_barrier
	s_waitcnt lgkmcnt(0)
	v_mfma_f32_16x16x32_bf16 v[134:137], v[188:191], v[138:141], v[134:137]
	v_mfma_f32_16x16x32_bf16 v[130:133], v[224:227], v[138:141], v[130:133]
	v_mfma_f32_16x16x32_bf16 v[118:121], v[188:191], v[146:149], v[118:121]
	v_mfma_f32_16x16x32_bf16 v[114:117], v[224:227], v[146:149], v[114:117]
	v_mfma_f32_16x16x32_bf16 v[102:105], v[188:191], v[162:165], v[102:105]
	v_mfma_f32_16x16x32_bf16 v[98:101], v[224:227], v[162:165], v[98:101]
	v_mfma_f32_16x16x32_bf16 v[86:89], v[188:191], v[170:173], v[86:89]
	v_mfma_f32_16x16x32_bf16 v[82:85], v[224:227], v[170:173], v[82:85]
	v_mfma_f32_16x16x32_bf16 v[134:137], v[220:223], v[142:145], v[134:137]
	v_mfma_f32_16x16x32_bf16 v[130:133], v[228:231], v[142:145], v[130:133]
	v_mfma_f32_16x16x32_bf16 v[118:121], v[220:223], v[150:153], v[118:121]
	v_mfma_f32_16x16x32_bf16 v[114:117], v[228:231], v[150:153], v[114:117]
	v_mfma_f32_16x16x32_bf16 v[102:105], v[220:223], v[166:169], v[102:105]
	v_mfma_f32_16x16x32_bf16 v[98:101], v[228:231], v[166:169], v[98:101]
	v_mfma_f32_16x16x32_bf16 v[86:89], v[220:223], v[184:187], v[86:89]
	v_mfma_f32_16x16x32_bf16 v[82:85], v[228:231], v[184:187], v[82:85]
	s_barrier
	s_mov_b32 m0, s21
	v_lshl_add_u64 v[232:233], s[44:45], 0, v[0:1]
	ds_read_b128 v[138:141], v196 offset:16384
	ds_read_b128 v[142:145], v196 offset:17408
	ds_read_b128 v[146:149], v196 offset:18432
	ds_read_b128 v[150:153], v196 offset:19456
	ds_read_b128 v[162:165], v196 offset:20480
	ds_read_b128 v[166:169], v196 offset:21504
	ds_read_b128 v[170:173], v196 offset:22528
	ds_read_b128 v[184:187], v196 offset:23552
	global_load_lds_dwordx4 v[232:233], off
	v_lshl_add_u64 v[234:235], s[44:45], 0, v[174:175]
	s_mov_b32 m0, s50
	s_nop 0
	global_load_lds_dwordx4 v[234:235], off
	s_barrier
	s_waitcnt lgkmcnt(0)
	v_mfma_f32_16x16x32_bf16 v[78:81], v[58:61], v[138:141], v[78:81]
	v_mfma_f32_16x16x32_bf16 v[66:69], v[70:73], v[138:141], v[66:69]
	v_mfma_f32_16x16x32_bf16 v[46:49], v[58:61], v[146:149], v[46:49]
	v_mfma_f32_16x16x32_bf16 v[42:45], v[70:73], v[146:149], v[42:45]
	v_mfma_f32_16x16x32_bf16 v[30:33], v[58:61], v[162:165], v[30:33]
	v_mfma_f32_16x16x32_bf16 v[26:29], v[70:73], v[162:165], v[26:29]
	v_mfma_f32_16x16x32_bf16 v[14:17], v[58:61], v[170:173], v[14:17]
	v_mfma_f32_16x16x32_bf16 v[10:13], v[70:73], v[170:173], v[10:13]
	v_mfma_f32_16x16x32_bf16 v[78:81], v[62:65], v[142:145], v[78:81]
	v_mfma_f32_16x16x32_bf16 v[66:69], v[74:77], v[142:145], v[66:69]
	v_mfma_f32_16x16x32_bf16 v[46:49], v[62:65], v[150:153], v[46:49]
	v_mfma_f32_16x16x32_bf16 v[42:45], v[74:77], v[150:153], v[42:45]
	v_mfma_f32_16x16x32_bf16 v[30:33], v[62:65], v[166:169], v[30:33]
	v_mfma_f32_16x16x32_bf16 v[26:29], v[74:77], v[166:169], v[26:29]
	v_mfma_f32_16x16x32_bf16 v[14:17], v[62:65], v[184:187], v[14:17]
	v_mfma_f32_16x16x32_bf16 v[10:13], v[74:77], v[184:187], v[10:13]
	s_barrier
; #define PG8_STAGE(bufoff, gbase, voff) do { _Pragma("unroll") for (int _i = 0; _i < 2; ++_i) \
;         __builtin_amdgcn_global_load_lds((const unsigned*)((const char*)(gbase) + (voff)[_i]), (LAS unsigned*)(lds + (bufoff) + ldsw + _i * 8192), 16, 0, 0); } while (0)
; #define PG8_LDA(dst, b, h) do { _Pragma("unroll") for (int m = 0; m < 4; ++m) _Pragma("unroll") for (int k = 0; k < 2; ++k) dst[m][k] = *(const LAS bf16x8*)(lds + PG8_SA(b, h) + aoff + m * 2048 + k * 1024); } while (0)
; #define PG8_LDB(dst, b, h) do { _Pragma("unroll") for (int n = 0; n < 2; ++n) _Pragma("unroll") for (int k = 0; k < 2; ++k) dst[n][k] = *(const LAS bf16x8*)(lds + PG8_SB(b, h) + boff + n * 2048 + k * 1024); } while (0)
; #define PG8_MMA(ai, bj, At, Bt) do { __builtin_amdgcn_s_setprio(1); _Pragma("unroll") for (int m = 0; m < 4; ++m) _Pragma("unroll") for (int n = 0; n < 2; ++n) _Pragma("unroll") for (int k = 0; k < 2; ++k) \
;         acc[ai][bj][m][n] = __builtin_amdgcn_mfma_f32_16x16x32_bf16(Bt[n][k], At[m][k], acc[ai][bj][m][n], 0, 0, 0); __builtin_amdgcn_s_setprio(0); } while (0)
; #define PG8_WAIT_V(n) asm volatile("s_waitcnt vmcnt(" #n ")" ::: "memory")
; #define PG8_WAIT_L(n) asm volatile("s_waitcnt lgkmcnt(" #n ")" ::: "memory")
; #define PG8_BAR __builtin_amdgcn_s_barrier()
; #define PG8_SCHED __builtin_amdgcn_sched_barrier(0)
; template <int MODE, class EpiT, class Sched>
; __device__ __forceinline__ void gemm_phase(LAS unsigned char* lds, const Gemm g, const Sched& S, const EpiT& E) {
;     ...
;             PG8_STAGE(PG8_SB(0, 1), b2 + hstep, voffB);
;             PG8_WAIT_V(6); PG8_BAR; PG8_MMA(1, 1, At, B1); PG8_BAR;
;             PG8_LDB(B0, 1, 0); PG8_SCHED; PG8_LDA(At, 1, 0); PG8_STAGE(PG8_SA(0, 1), a2 + hstep, voffA);
;             PG8_WAIT_L(8); PG8_BAR; PG8_WAIT_L(0); PG8_MMA(0, 0, At, B0); PG8_BAR; PG8_SCHED;
;             PG8_LDB(B1, 1, 1); PG8_STAGE(PG8_SB(1, 0), b3, voffB);
;             PG8_BAR; PG8_WAIT_L(0); PG8_MMA(0, 1, At, B1); PG8_BAR;
;             PG8_LDA(At, 1, 1); PG8_STAGE(PG8_SA(1, 0), a3, voffA);
	s_add_u32 s52, s52, s38
	s_addc_u32 s53, s53, 0
	s_add_i32 s58, s59, s20
	v_lshl_add_u64 v[236:237], s[52:53], 0, v[0:1]
	s_mov_b32 m0, s58
	v_lshl_add_u64 v[238:239], s[52:53], 0, v[174:175]
	global_load_lds_dwordx4 v[236:237], off
	s_add_i32 m0, s58, 0x2000
	s_nop 0
	global_load_lds_dwordx4 v[238:239], off
	s_waitcnt vmcnt(6)
	s_barrier
	v_mfma_f32_16x16x32_bf16 v[54:57], v[188:191], v[138:141], v[54:57]
	v_mfma_f32_16x16x32_bf16 v[50:53], v[224:227], v[138:141], v[50:53]
	v_mfma_f32_16x16x32_bf16 v[38:41], v[188:191], v[146:149], v[38:41]
	v_mfma_f32_16x16x32_bf16 v[34:37], v[224:227], v[146:149], v[34:37]
	v_mfma_f32_16x16x32_bf16 v[22:25], v[188:191], v[162:165], v[22:25]
	v_mfma_f32_16x16x32_bf16 v[18:21], v[224:227], v[162:165], v[18:21]
	v_mfma_f32_16x16x32_bf16 v[6:9], v[188:191], v[170:173], v[6:9]
	v_mfma_f32_16x16x32_bf16 v[2:5], v[224:227], v[170:173], v[2:5]
	v_mfma_f32_16x16x32_bf16 v[54:57], v[220:223], v[142:145], v[54:57]
	v_mfma_f32_16x16x32_bf16 v[50:53], v[228:231], v[142:145], v[50:53]
	v_mfma_f32_16x16x32_bf16 v[38:41], v[220:223], v[150:153], v[38:41]
	v_mfma_f32_16x16x32_bf16 v[34:37], v[228:231], v[150:153], v[34:37]
	v_mfma_f32_16x16x32_bf16 v[22:25], v[220:223], v[166:169], v[22:25]
	v_mfma_f32_16x16x32_bf16 v[18:21], v[228:231], v[166:169], v[18:21]
	v_mfma_f32_16x16x32_bf16 v[6:9], v[220:223], v[184:187], v[6:9]
	v_mfma_f32_16x16x32_bf16 v[2:5], v[228:231], v[184:187], v[2:5]
	s_barrier
	s_add_i32 s52, 0, 0x18000
	v_add_u32_e32 v74, s52, v194
	ds_read_b128 v[58:61], v74
	ds_read_b128 v[62:65], v74 offset:1024
	ds_read_b128 v[70:73], v74 offset:2048
	ds_read_b128 v[74:77], v74 offset:3072
	ds_read_b128 v[138:141], v196 offset:32768
	ds_read_b128 v[142:145], v196 offset:33792
	ds_read_b128 v[146:149], v196 offset:34816
	ds_read_b128 v[150:153], v196 offset:35840
	ds_read_b128 v[162:165], v196 offset:36864
	ds_read_b128 v[166:169], v196 offset:37888
	ds_read_b128 v[170:173], v196 offset:38912
	ds_read_b128 v[184:187], v196 offset:39936
	s_add_u32 s44, s44, s38
	s_addc_u32 s45, s45, 0
	s_mov_b32 m0, s51
	v_lshl_add_u64 v[188:189], s[44:45], 0, v[0:1]
	global_load_lds_dwordx4 v[188:189], off
	v_lshl_add_u64 v[188:189], s[44:45], 0, v[174:175]
	s_mov_b32 m0, s56
	s_nop 0
	global_load_lds_dwordx4 v[188:189], off
	s_waitcnt lgkmcnt(8)
	s_barrier
	s_waitcnt lgkmcnt(0)
	v_mfma_f32_16x16x32_bf16 v[158:161], v[58:61], v[138:141], v[158:161]
	v_mfma_f32_16x16x32_bf16 v[154:157], v[70:73], v[138:141], v[154:157]
	v_mfma_f32_16x16x32_bf16 v[126:129], v[58:61], v[146:149], v[126:129]
	v_mfma_f32_16x16x32_bf16 v[122:125], v[70:73], v[146:149], v[122:125]
	v_mfma_f32_16x16x32_bf16 v[110:113], v[58:61], v[162:165], v[110:113]
	v_mfma_f32_16x16x32_bf16 v[106:109], v[70:73], v[162:165], v[106:109]
	v_mfma_f32_16x16x32_bf16 v[94:97], v[58:61], v[170:173], v[94:97]
	v_mfma_f32_16x16x32_bf16 v[90:93], v[70:73], v[170:173], v[90:93]
	v_mfma_f32_16x16x32_bf16 v[158:161], v[62:65], v[142:145], v[158:161]
	v_mfma_f32_16x16x32_bf16 v[154:157], v[74:77], v[142:145], v[154:157]
	v_mfma_f32_16x16x32_bf16 v[126:129], v[62:65], v[150:153], v[126:129]
	v_mfma_f32_16x16x32_bf16 v[122:125], v[74:77], v[150:153], v[122:125]
	v_mfma_f32_16x16x32_bf16 v[110:113], v[62:65], v[166:169], v[110:113]
	v_mfma_f32_16x16x32_bf16 v[106:109], v[74:77], v[166:169], v[106:109]
	v_mfma_f32_16x16x32_bf16 v[94:97], v[62:65], v[184:187], v[94:97]
	v_mfma_f32_16x16x32_bf16 v[90:93], v[74:77], v[184:187], v[90:93]
	s_barrier
	s_add_i32 s44, 0, 0x1c000
	s_add_i32 s45, s52, s20
	v_add_u32_e32 v197, s44, v194
	v_lshl_add_u64 v[192:193], v[192:193], 0, s[76:77]
	s_mov_b32 m0, s45
	ds_read_b128 v[188:191], v197
	ds_read_b128 v[220:223], v197 offset:1024
	ds_read_b128 v[224:227], v197 offset:2048
	ds_read_b128 v[228:231], v197 offset:3072
	global_load_lds_dwordx4 v[192:193], off
	v_lshl_add_u64 v[192:193], v[198:199], 0, s[76:77]
	s_add_i32 m0, s45, 0x2000
	s_nop 0
	global_load_lds_dwordx4 v[192:193], off
	s_barrier
; #define PG8_STAGE(bufoff, gbase, voff) do { _Pragma("unroll") for (int _i = 0; _i < 2; ++_i) \
;         __builtin_amdgcn_global_load_lds((const unsigned*)((const char*)(gbase) + (voff)[_i]), (LAS unsigned*)(lds + (bufoff) + ldsw + _i * 8192), 16, 0, 0); } while (0)
; #define PG8_LDA(dst, b, h) do { _Pragma("unroll") for (int m = 0; m < 4; ++m) _Pragma("unroll") for (int k = 0; k < 2; ++k) dst[m][k] = *(const LAS bf16x8*)(lds + PG8_SA(b, h) + aoff + m * 2048 + k * 1024); } while (0)
; #define PG8_MMA(ai, bj, At, Bt) do { __builtin_amdgcn_s_setprio(1); _Pragma("unroll") for (int m = 0; m < 4; ++m) _Pragma("unroll") for (int n = 0; n < 2; ++n) _Pragma("unroll") for (int k = 0; k < 2; ++k) \
;         acc[ai][bj][m][n] = __builtin_amdgcn_mfma_f32_16x16x32_bf16(Bt[n][k], At[m][k], acc[ai][bj][m][n], 0, 0, 0); __builtin_amdgcn_s_setprio(0); } while (0)
; #define PG8_WAIT_V(n) asm volatile("s_waitcnt vmcnt(" #n ")" ::: "memory")
; #define PG8_WAIT_L(n) asm volatile("s_waitcnt lgkmcnt(" #n ")" ::: "memory")
; #define PG8_BAR __builtin_amdgcn_s_barrier()
; #define PG8_SCHED __builtin_amdgcn_sched_barrier(0)
;     template <int mode> __device__ __forceinline__ void run(const f32x4 (&acc)[2][2][4][2], const Unit& u, int wr, int wc, int fr, int fq, const LAS float* sc) const {
;     ...
;             const int col0 = u.pn * BM + wc * 32 + 8 * fq;
;             float sA = 1.f, sB = 1.f;
;             if (mode == 4) scales2(u, wr, fr, fq, sA, sB);
;             f32x4 bvv[4];
; #pragma unroll
;             for (int q = 0; q < 4; ++q) bvv[q] = (mode != 4 && bias) ? *(const f32x4*)(bias + col0 + (q >> 1) * HALF + (q & 1) * 4) : (f32x4){0.f, 0.f, 0.f, 0.f};
; template <int MODE, class EpiT, class Sched>
; __device__ __forceinline__ void gemm_phase(LAS unsigned char* lds, const Gemm g, const Sched& S, const EpiT& E) {
;     ...
;             PG8_LDA(At, 1, 1); PG8_STAGE(PG8_SA(1, 0), a3, voffA);
;             PG8_BAR; PG8_WAIT_L(0); PG8_MMA(1, 0, At, B0); PG8_BAR; PG8_SCHED;
;             PG8_STAGE(PG8_SB(1, 1), b3 + hstep, voffB);
;             PG8_WAIT_V(6); PG8_BAR; PG8_MMA(1, 1, At, B1); PG8_BAR;
;         }
	s_waitcnt lgkmcnt(0)
	v_mfma_f32_16x16x32_bf16 v[134:137], v[188:191], v[138:141], v[134:137]
	v_mfma_f32_16x16x32_bf16 v[130:133], v[224:227], v[138:141], v[130:133]
	v_mfma_f32_16x16x32_bf16 v[118:121], v[188:191], v[146:149], v[118:121]
	v_mfma_f32_16x16x32_bf16 v[114:117], v[224:227], v[146:149], v[114:117]
	v_mfma_f32_16x16x32_bf16 v[102:105], v[188:191], v[162:165], v[102:105]
	v_mfma_f32_16x16x32_bf16 v[98:101], v[224:227], v[162:165], v[98:101]
	v_mfma_f32_16x16x32_bf16 v[86:89], v[188:191], v[170:173], v[86:89]
	v_mfma_f32_16x16x32_bf16 v[82:85], v[224:227], v[170:173], v[82:85]
	v_mfma_f32_16x16x32_bf16 v[134:137], v[220:223], v[142:145], v[134:137]
	v_mfma_f32_16x16x32_bf16 v[130:133], v[228:231], v[142:145], v[130:133]
	v_mfma_f32_16x16x32_bf16 v[118:121], v[220:223], v[150:153], v[118:121]
	v_mfma_f32_16x16x32_bf16 v[114:117], v[228:231], v[150:153], v[114:117]
	v_mfma_f32_16x16x32_bf16 v[102:105], v[220:223], v[166:169], v[102:105]
	v_mfma_f32_16x16x32_bf16 v[98:101], v[228:231], v[166:169], v[98:101]
	v_mfma_f32_16x16x32_bf16 v[86:89], v[220:223], v[184:187], v[86:89]
	v_mfma_f32_16x16x32_bf16 v[82:85], v[228:231], v[184:187], v[82:85]
	s_barrier
	s_mov_b32 m0, s61
	v_lshl_add_u64 v[192:193], v[232:233], 0, s[76:77]
	ds_read_b128 v[138:141], v196 offset:49152
	ds_read_b128 v[142:145], v196 offset:50176
	ds_read_b128 v[146:149], v196 offset:51200
	ds_read_b128 v[150:153], v196 offset:52224
	ds_read_b128 v[162:165], v196 offset:53248
	ds_read_b128 v[166:169], v196 offset:54272
	ds_read_b128 v[170:173], v196 offset:55296
	ds_read_b128 v[184:187], v196 offset:56320
	global_load_lds_dwordx4 v[192:193], off
	v_lshl_add_u64 v[192:193], v[234:235], 0, s[76:77]
	s_mov_b32 m0, s74
	s_nop 0
	global_load_lds_dwordx4 v[192:193], off
	s_barrier
	s_waitcnt lgkmcnt(0)
	v_mfma_f32_16x16x32_bf16 v[78:81], v[58:61], v[138:141], v[78:81]
	v_mfma_f32_16x16x32_bf16 v[66:69], v[70:73], v[138:141], v[66:69]
	v_mfma_f32_16x16x32_bf16 v[46:49], v[58:61], v[146:149], v[46:49]
	v_mfma_f32_16x16x32_bf16 v[42:45], v[70:73], v[146:149], v[42:45]
	v_mfma_f32_16x16x32_bf16 v[30:33], v[58:61], v[162:165], v[30:33]
	v_mfma_f32_16x16x32_bf16 v[26:29], v[70:73], v[162:165], v[26:29]
	v_mfma_f32_16x16x32_bf16 v[14:17], v[58:61], v[170:173], v[14:17]
	v_mfma_f32_16x16x32_bf16 v[10:13], v[70:73], v[170:173], v[10:13]
	v_mfma_f32_16x16x32_bf16 v[78:81], v[62:65], v[142:145], v[78:81]
	v_mfma_f32_16x16x32_bf16 v[66:69], v[74:77], v[142:145], v[66:69]
	v_mfma_f32_16x16x32_bf16 v[46:49], v[62:65], v[150:153], v[46:49]
	v_mfma_f32_16x16x32_bf16 v[42:45], v[74:77], v[150:153], v[42:45]
	v_mfma_f32_16x16x32_bf16 v[30:33], v[62:65], v[166:169], v[30:33]
	v_mfma_f32_16x16x32_bf16 v[26:29], v[74:77], v[166:169], v[26:29]
	v_mfma_f32_16x16x32_bf16 v[14:17], v[62:65], v[184:187], v[14:17]
	v_mfma_f32_16x16x32_bf16 v[10:13], v[74:77], v[184:187], v[10:13]
	s_barrier
	s_add_i32 s44, s44, s20
	v_lshl_add_u64 v[58:59], v[236:237], 0, s[76:77]
	s_mov_b32 m0, s44
	s_nop 0
	global_load_lds_dwordx4 v[58:59], off
	v_lshl_add_u64 v[58:59], v[238:239], 0, s[76:77]
	s_add_i32 m0, s44, 0x2000
	s_nop 0
	global_load_lds_dwordx4 v[58:59], off
	s_waitcnt vmcnt(6)
	s_barrier
	v_mfma_f32_16x16x32_bf16 v[54:57], v[188:191], v[138:141], v[54:57]
	v_mfma_f32_16x16x32_bf16 v[50:53], v[224:227], v[138:141], v[50:53]
	v_mfma_f32_16x16x32_bf16 v[38:41], v[188:191], v[146:149], v[38:41]
	v_mfma_f32_16x16x32_bf16 v[34:37], v[224:227], v[146:149], v[34:37]
	v_mfma_f32_16x16x32_bf16 v[22:25], v[188:191], v[162:165], v[22:25]
	v_mfma_f32_16x16x32_bf16 v[18:21], v[224:227], v[162:165], v[18:21]
	v_mfma_f32_16x16x32_bf16 v[6:9], v[188:191], v[170:173], v[6:9]
	v_mfma_f32_16x16x32_bf16 v[2:5], v[224:227], v[170:173], v[2:5]
	v_mfma_f32_16x16x32_bf16 v[54:57], v[220:223], v[142:145], v[54:57]
	v_mfma_f32_16x16x32_bf16 v[50:53], v[228:231], v[142:145], v[50:53]
	v_mfma_f32_16x16x32_bf16 v[38:41], v[220:223], v[150:153], v[38:41]
	v_mfma_f32_16x16x32_bf16 v[34:37], v[228:231], v[150:153], v[34:37]
	v_mfma_f32_16x16x32_bf16 v[22:25], v[220:223], v[166:169], v[22:25]
	v_mfma_f32_16x16x32_bf16 v[18:21], v[228:231], v[166:169], v[18:21]
	v_mfma_f32_16x16x32_bf16 v[6:9], v[220:223], v[184:187], v[6:9]
	v_mfma_f32_16x16x32_bf16 v[2:5], v[228:231], v[184:187], v[2:5]
	s_barrier
	s_add_u32 s4, s4, 0x100
	s_addc_u32 s5, s5, 0
	s_add_u32 s89, s89, 0x100
	s_addc_u32 s90, s90, 0
	s_cmp_ge_u32 vcc_lo, s60
	s_mov_b32 s44, vcc_lo
	s_cbranch_scc0 .LBB0_195
	v_lshl_or_b32 v186, s24, 8, v195
	v_ashrrev_i32_e32 v187, 31, v186
	v_mov_b32_e32 v70, 0
	v_cndmask_b32_e64 v58, 0, 1, s[78:79]
	v_lshl_add_u64 v[138:139], v[186:187], 2, s[12:13]
	v_cmp_ne_u32_e64 s[44:45], 1, v58
	s_andn2_b64 vcc, exec, s[78:79]
	v_mov_b32_e32 v74, 0
	v_mov_b32_e32 v75, v70
	v_mov_b32_e32 v184, 0
	v_mov_b32_e32 v185, v70
	s_cbranch_vccnz .LBB0_198
	global_load_dwordx4 v[74:77], v[138:139], off
	s_waitcnt vmcnt(0)
	v_mov_b32_e32 v184, v76
	v_mov_b32_e32 v185, v77

; #define PG8_STAGE(bufoff, gbase, voff) do { _Pragma("unroll") for (int _i = 0; _i < 2; ++_i) \
;         __builtin_amdgcn_global_load_lds((const unsigned*)((const char*)(gbase) + (voff)[_i]), (LAS unsigned*)(lds + (bufoff) + ldsw + _i * 8192), 16, 0, 0); } while (0)
; #define PG8_LDA(dst, b, h) do { _Pragma("unroll") for (int m = 0; m < 4; ++m) _Pragma("unroll") for (int k = 0; k < 2; ++k) dst[m][k] = *(const LAS bf16x8*)(lds + PG8_SA(b, h) + aoff + m * 2048 + k * 1024); } while (0)
; #define PG8_LDB(dst, b, h) do { _Pragma("unroll") for (int n = 0; n < 2; ++n) _Pragma("unroll") for (int k = 0; k < 2; ++k) dst[n][k] = *(const LAS bf16x8*)(lds + PG8_SB(b, h) + boff + n * 2048 + k * 1024); } while (0)
; #define PG8_MMA(ai, bj, At, Bt) do { __builtin_amdgcn_s_setprio(1); _Pragma("unroll") for (int m = 0; m < 4; ++m) _Pragma("unroll") for (int n = 0; n < 2; ++n) _Pragma("unroll") for (int k = 0; k < 2; ++k) \
;         acc[ai][bj][m][n] = __builtin_amdgcn_mfma_f32_16x16x32_bf16(Bt[n][k], At[m][k], acc[ai][bj][m][n], 0, 0, 0); __builtin_amdgcn_s_setprio(0); } while (0)
; #define PG8_WAIT_L(n) asm volatile("s_waitcnt lgkmcnt(" #n ")" ::: "memory")
; template <int MODE, class EpiT, class Sched>
; __device__ __forceinline__ void gemm_phase(LAS unsigned char* lds, const Gemm g, const Sched& S, const EpiT& E) {
;     ...
;         const bool has_next = S.next(ui + 1, nxt);
;         const char* nA = has_next ? (const char*)g.A + (size_t)nxt.pm * tstep : cA; const char* nB = has_next ? (const char*)g.Bt + (size_t)nxt.pn * tstep : cB;
;         for (int t = 0; t < nt; t += 2) {
;             const bool last = (t == nt - 2);
;             const char* a1 = cA + (size_t)(t + 1) * kstep;
;             const char* a2 = last ? nA : cA + (size_t)(t + 2) * kstep; const char* b2 = last ? nB : cB + (size_t)(t + 2) * kstep;
;             const char* a3 = a2 + kstep; const char* b3 = b2 + kstep;
;             PG8_LDB(B0, 0, 0); PG8_SCHED; PG8_LDA(At, 0, 0); PG8_STAGE(PG8_SA(1, 1), a1 + hstep, voffA);
;             PG8_WAIT_L(8); PG8_BAR; PG8_WAIT_L(0); PG8_MMA(0, 0, At, B0); PG8_BAR; PG8_SCHED;
;             PG8_LDB(B1, 0, 1); PG8_STAGE(PG8_SB(0, 0), b2, voffB);
;             PG8_BAR; PG8_WAIT_L(0); PG8_MMA(0, 1, At, B1); PG8_BAR;
;             PG8_LDA(At, 0, 1); PG8_STAGE(PG8_SA(0, 0), a2, voffA);
;             PG8_BAR; PG8_WAIT_L(0); PG8_MMA(1, 0, At, B0); PG8_BAR; PG8_SCHED;
.LBB0_236:
	s_add_i32 s44, s34, 2
	s_add_u32 s38, s28, 0x80
	s_addc_u32 s35, s29, 0
	s_add_i32 s45, 0, 0x10000
	v_add_u32_e32 v136, s45, v139
	ds_read_b128 v[142:145], v136
	ds_read_b128 v[146:149], v136 offset:1024
	ds_read_b128 v[150:153], v136 offset:2048
	ds_read_b128 v[154:157], v136 offset:3072
	ds_read_b128 v[158:161], v141
	ds_read_b128 v[162:165], v141 offset:1024
	ds_read_b128 v[166:169], v141 offset:2048
	ds_read_b128 v[170:173], v141 offset:3072
	ds_read_b128 v[174:177], v141 offset:4096
	ds_read_b128 v[182:185], v141 offset:5120
	ds_read_b128 v[186:189], v141 offset:6144
	ds_read_b128 v[190:193], v141 offset:7168
	s_cmp_eq_u32 s52, s34
	s_cselect_b32 s34, s4, s38
	s_cselect_b32 s35, s5, s35
	s_cselect_b32 s39, s11, s43
	s_cselect_b32 s38, s10, s42
	s_add_i32 m0, s22, 0xc000
	v_lshl_add_u64 v[136:137], s[28:29], 0, v[132:133]
	global_load_lds_dwordx4 v[136:137], off
	v_lshl_add_u64 v[136:137], s[28:29], 0, v[134:135]
	s_add_i32 m0, s22, 0xe000
	s_nop 0
	global_load_lds_dwordx4 v[136:137], off
	s_waitcnt lgkmcnt(8)
	s_barrier
	s_waitcnt lgkmcnt(0)
	v_mfma_f32_16x16x32_bf16 v[126:129], v[142:145], v[158:161], v[126:129]
	v_mfma_f32_16x16x32_bf16 v[122:125], v[150:153], v[158:161], v[122:125]
	v_mfma_f32_16x16x32_bf16 v[118:121], v[142:145], v[166:169], v[118:121]
	v_mfma_f32_16x16x32_bf16 v[110:113], v[150:153], v[166:169], v[110:113]
	v_mfma_f32_16x16x32_bf16 v[102:105], v[142:145], v[174:177], v[102:105]
	v_mfma_f32_16x16x32_bf16 v[94:97], v[150:153], v[174:177], v[94:97]
	v_mfma_f32_16x16x32_bf16 v[86:89], v[142:145], v[186:189], v[86:89]
	v_mfma_f32_16x16x32_bf16 v[78:81], v[150:153], v[186:189], v[78:81]
	v_mfma_f32_16x16x32_bf16 v[126:129], v[146:149], v[162:165], v[126:129]
	v_mfma_f32_16x16x32_bf16 v[122:125], v[154:157], v[162:165], v[122:125]
	v_mfma_f32_16x16x32_bf16 v[118:121], v[146:149], v[170:173], v[118:121]
	v_mfma_f32_16x16x32_bf16 v[110:113], v[154:157], v[170:173], v[110:113]
	v_mfma_f32_16x16x32_bf16 v[102:105], v[146:149], v[182:185], v[102:105]
	v_mfma_f32_16x16x32_bf16 v[94:97], v[154:157], v[182:185], v[94:97]
	v_mfma_f32_16x16x32_bf16 v[86:89], v[146:149], v[190:193], v[86:89]
	v_mfma_f32_16x16x32_bf16 v[78:81], v[154:157], v[190:193], v[78:81]
	s_barrier
	s_add_i32 s58, 0, 0x14000
	v_add_u32_e32 v136, s58, v139
	s_add_i32 s45, s45, s9
	ds_read_b128 v[194:197], v136
	ds_read_b128 v[220:223], v136 offset:1024
	ds_read_b128 v[224:227], v136 offset:2048
	ds_read_b128 v[228:231], v136 offset:3072
	v_lshl_add_u64 v[136:137], s[38:39], 0, v[0:1]
	s_mov_b32 m0, s45
	v_lshl_add_u64 v[198:199], s[38:39], 0, v[130:131]
	global_load_lds_dwordx4 v[136:137], off
	s_add_i32 m0, s45, 0x2000
	s_nop 0
	global_load_lds_dwordx4 v[198:199], off
	s_barrier
	s_waitcnt lgkmcnt(0)
	v_mfma_f32_16x16x32_bf16 v[114:117], v[194:197], v[158:161], v[114:117]
	v_mfma_f32_16x16x32_bf16 v[106:109], v[224:227], v[158:161], v[106:109]
	v_mfma_f32_16x16x32_bf16 v[98:101], v[194:197], v[166:169], v[98:101]
	v_mfma_f32_16x16x32_bf16 v[90:93], v[224:227], v[166:169], v[90:93]
	v_mfma_f32_16x16x32_bf16 v[82:85], v[194:197], v[174:177], v[82:85]
	v_mfma_f32_16x16x32_bf16 v[74:77], v[224:227], v[174:177], v[74:77]
	v_mfma_f32_16x16x32_bf16 v[70:73], v[194:197], v[186:189], v[70:73]
	v_mfma_f32_16x16x32_bf16 v[66:69], v[224:227], v[186:189], v[66:69]
	v_mfma_f32_16x16x32_bf16 v[114:117], v[220:223], v[162:165], v[114:117]
	v_mfma_f32_16x16x32_bf16 v[106:109], v[228:231], v[162:165], v[106:109]
	v_mfma_f32_16x16x32_bf16 v[98:101], v[220:223], v[170:173], v[98:101]
	v_mfma_f32_16x16x32_bf16 v[90:93], v[228:231], v[170:173], v[90:93]
	v_mfma_f32_16x16x32_bf16 v[82:85], v[220:223], v[182:185], v[82:85]
	v_mfma_f32_16x16x32_bf16 v[74:77], v[228:231], v[182:185], v[74:77]
	v_mfma_f32_16x16x32_bf16 v[70:73], v[220:223], v[190:193], v[70:73]
	v_mfma_f32_16x16x32_bf16 v[66:69], v[228:231], v[190:193], v[66:69]
	s_barrier
	s_mov_b32 m0, s22
	v_lshl_add_u64 v[232:233], s[34:35], 0, v[0:1]
	ds_read_b128 v[158:161], v141 offset:16384
	ds_read_b128 v[162:165], v141 offset:17408
	ds_read_b128 v[166:169], v141 offset:18432
	ds_read_b128 v[170:173], v141 offset:19456
	ds_read_b128 v[174:177], v141 offset:20480
	ds_read_b128 v[182:185], v141 offset:21504
	ds_read_b128 v[186:189], v141 offset:22528
	ds_read_b128 v[190:193], v141 offset:23552
	global_load_lds_dwordx4 v[232:233], off
	v_lshl_add_u64 v[234:235], s[34:35], 0, v[130:131]
	s_mov_b32 m0, s23
	s_nop 0
	global_load_lds_dwordx4 v[234:235], off
	s_barrier
	s_waitcnt lgkmcnt(0)
	v_mfma_f32_16x16x32_bf16 v[62:65], v[142:145], v[158:161], v[62:65]
	v_mfma_f32_16x16x32_bf16 v[58:61], v[150:153], v[158:161], v[58:61]
	v_mfma_f32_16x16x32_bf16 v[54:57], v[142:145], v[166:169], v[54:57]
	v_mfma_f32_16x16x32_bf16 v[46:49], v[150:153], v[166:169], v[46:49]
	v_mfma_f32_16x16x32_bf16 v[38:41], v[142:145], v[174:177], v[38:41]
	v_mfma_f32_16x16x32_bf16 v[30:33], v[150:153], v[174:177], v[30:33]
	v_mfma_f32_16x16x32_bf16 v[22:25], v[142:145], v[186:189], v[22:25]
	v_mfma_f32_16x16x32_bf16 v[14:17], v[150:153], v[186:189], v[14:17]
	v_mfma_f32_16x16x32_bf16 v[62:65], v[146:149], v[162:165], v[62:65]
	v_mfma_f32_16x16x32_bf16 v[58:61], v[154:157], v[162:165], v[58:61]
	v_mfma_f32_16x16x32_bf16 v[54:57], v[146:149], v[170:173], v[54:57]
	v_mfma_f32_16x16x32_bf16 v[46:49], v[154:157], v[170:173], v[46:49]
	v_mfma_f32_16x16x32_bf16 v[38:41], v[146:149], v[182:185], v[38:41]
	v_mfma_f32_16x16x32_bf16 v[30:33], v[154:157], v[182:185], v[30:33]
	v_mfma_f32_16x16x32_bf16 v[22:25], v[146:149], v[190:193], v[22:25]
	v_mfma_f32_16x16x32_bf16 v[14:17], v[154:157], v[190:193], v[14:17]
	s_barrier
; #define PG8_STAGE(bufoff, gbase, voff) do { _Pragma("unroll") for (int _i = 0; _i < 2; ++_i) \
;         __builtin_amdgcn_global_load_lds((const unsigned*)((const char*)(gbase) + (voff)[_i]), (LAS unsigned*)(lds + (bufoff) + ldsw + _i * 8192), 16, 0, 0); } while (0)
; #define PG8_LDA(dst, b, h) do { _Pragma("unroll") for (int m = 0; m < 4; ++m) _Pragma("unroll") for (int k = 0; k < 2; ++k) dst[m][k] = *(const LAS bf16x8*)(lds + PG8_SA(b, h) + aoff + m * 2048 + k * 1024); } while (0)
; #define PG8_LDB(dst, b, h) do { _Pragma("unroll") for (int n = 0; n < 2; ++n) _Pragma("unroll") for (int k = 0; k < 2; ++k) dst[n][k] = *(const LAS bf16x8*)(lds + PG8_SB(b, h) + boff + n * 2048 + k * 1024); } while (0)
; #define PG8_WAIT_V(n) asm volatile("s_waitcnt vmcnt(" #n ")" ::: "memory")
; #define PG8_WAIT_L(n) asm volatile("s_waitcnt lgkmcnt(" #n ")" ::: "memory")
; #define PG8_BAR __builtin_amdgcn_s_barrier()
; #define PG8_SCHED __builtin_amdgcn_sched_barrier(0)
; template <int MODE, class EpiT, class Sched>
; __device__ __forceinline__ void gemm_phase(LAS unsigned char* lds, const Gemm g, const Sched& S, const EpiT& E) {
;     ...
;             PG8_LDB(B0, 0, 0); PG8_SCHED; PG8_LDA(At, 0, 0); PG8_STAGE(PG8_SA(1, 1), a1 + hstep, voffA);
;             PG8_WAIT_L(8); PG8_BAR; PG8_WAIT_L(0); PG8_MMA(0, 0, At, B0); PG8_BAR; PG8_SCHED;
;             PG8_LDB(B1, 0, 1); PG8_STAGE(PG8_SB(0, 0), b2, voffB);
;             PG8_BAR; PG8_WAIT_L(0); PG8_MMA(0, 1, At, B1); PG8_BAR;
;             PG8_LDA(At, 0, 1); PG8_STAGE(PG8_SA(0, 0), a2, voffA);
;             PG8_BAR; PG8_WAIT_L(0); PG8_MMA(1, 0, At, B0); PG8_BAR; PG8_SCHED;
;             PG8_STAGE(PG8_SB(0, 1), b2 + hstep, voffB);
;             PG8_WAIT_V(6); PG8_BAR; PG8_MMA(1, 1, At, B1); PG8_BAR;
;             PG8_LDB(B0, 1, 0); PG8_SCHED; PG8_LDA(At, 1, 0); PG8_STAGE(PG8_SA(0, 1), a2 + hstep, voffA);
;             PG8_WAIT_L(8); PG8_BAR; PG8_WAIT_L(0); PG8_MMA(0, 0, At, B0); PG8_BAR; PG8_SCHED;
;             PG8_LDB(B1, 1, 1); PG8_STAGE(PG8_SB(1, 0), b3, voffB);
;             PG8_BAR; PG8_WAIT_L(0); PG8_MMA(0, 1, At, B1); PG8_BAR;
;             PG8_LDA(At, 1, 1); PG8_STAGE(PG8_SA(1, 0), a3, voffA);
;             PG8_BAR; PG8_WAIT_L(0); PG8_MMA(1, 0, At, B0); PG8_BAR; PG8_SCHED;
;             PG8_STAGE(PG8_SB(1, 1), b3 + hstep, voffB);
;             PG8_WAIT_V(6); PG8_BAR; PG8_MMA(1, 1, At, B1); PG8_BAR;
	s_add_u32 s38, s38, s24
	s_addc_u32 s39, s39, 0
	s_add_i32 s45, s58, s9
	v_lshl_add_u64 v[236:237], s[38:39], 0, v[0:1]
	s_mov_b32 m0, s45
	v_lshl_add_u64 v[238:239], s[38:39], 0, v[130:131]
	global_load_lds_dwordx4 v[236:237], off
	s_add_i32 m0, s45, 0x2000
	s_nop 0
	global_load_lds_dwordx4 v[238:239], off
	s_waitcnt vmcnt(6)
	s_barrier
	v_mfma_f32_16x16x32_bf16 v[50:53], v[194:197], v[158:161], v[50:53]
	v_mfma_f32_16x16x32_bf16 v[42:45], v[224:227], v[158:161], v[42:45]
	v_mfma_f32_16x16x32_bf16 v[34:37], v[194:197], v[166:169], v[34:37]
	v_mfma_f32_16x16x32_bf16 v[26:29], v[224:227], v[166:169], v[26:29]
	v_mfma_f32_16x16x32_bf16 v[18:21], v[194:197], v[174:177], v[18:21]
	v_mfma_f32_16x16x32_bf16 v[10:13], v[224:227], v[174:177], v[10:13]
	v_mfma_f32_16x16x32_bf16 v[6:9], v[194:197], v[186:189], v[6:9]
	v_mfma_f32_16x16x32_bf16 v[2:5], v[224:227], v[186:189], v[2:5]
	v_mfma_f32_16x16x32_bf16 v[50:53], v[220:223], v[162:165], v[50:53]
	v_mfma_f32_16x16x32_bf16 v[42:45], v[228:231], v[162:165], v[42:45]
	v_mfma_f32_16x16x32_bf16 v[34:37], v[220:223], v[170:173], v[34:37]
	v_mfma_f32_16x16x32_bf16 v[26:29], v[228:231], v[170:173], v[26:29]
	v_mfma_f32_16x16x32_bf16 v[18:21], v[220:223], v[182:185], v[18:21]
	v_mfma_f32_16x16x32_bf16 v[10:13], v[228:231], v[182:185], v[10:13]
	v_mfma_f32_16x16x32_bf16 v[6:9], v[220:223], v[190:193], v[6:9]
	v_mfma_f32_16x16x32_bf16 v[2:5], v[228:231], v[190:193], v[2:5]
	s_barrier
	s_add_i32 s38, 0, 0x18000
	v_add_u32_e32 v154, s38, v139
	ds_read_b128 v[142:145], v154
	ds_read_b128 v[146:149], v154 offset:1024
	ds_read_b128 v[150:153], v154 offset:2048
	ds_read_b128 v[154:157], v154 offset:3072
	ds_read_b128 v[158:161], v141 offset:32768
	ds_read_b128 v[162:165], v141 offset:33792
	ds_read_b128 v[166:169], v141 offset:34816
	ds_read_b128 v[170:173], v141 offset:35840
	ds_read_b128 v[174:177], v141 offset:36864
	ds_read_b128 v[182:185], v141 offset:37888
	ds_read_b128 v[186:189], v141 offset:38912
	ds_read_b128 v[190:193], v141 offset:39936
	s_add_u32 s34, s34, s24
	s_addc_u32 s35, s35, 0
	s_mov_b32 m0, s30
	v_lshl_add_u64 v[194:195], s[34:35], 0, v[0:1]
	global_load_lds_dwordx4 v[194:195], off
	v_lshl_add_u64 v[194:195], s[34:35], 0, v[130:131]
	s_mov_b32 m0, s46
	s_nop 0
	global_load_lds_dwordx4 v[194:195], off
	s_waitcnt lgkmcnt(8)
	s_barrier
	s_waitcnt lgkmcnt(0)
	v_mfma_f32_16x16x32_bf16 v[126:129], v[142:145], v[158:161], v[126:129]
	v_mfma_f32_16x16x32_bf16 v[122:125], v[150:153], v[158:161], v[122:125]
	v_mfma_f32_16x16x32_bf16 v[118:121], v[142:145], v[166:169], v[118:121]
	v_mfma_f32_16x16x32_bf16 v[110:113], v[150:153], v[166:169], v[110:113]
	v_mfma_f32_16x16x32_bf16 v[102:105], v[142:145], v[174:177], v[102:105]
	v_mfma_f32_16x16x32_bf16 v[94:97], v[150:153], v[174:177], v[94:97]
	v_mfma_f32_16x16x32_bf16 v[86:89], v[142:145], v[186:189], v[86:89]
	v_mfma_f32_16x16x32_bf16 v[78:81], v[150:153], v[186:189], v[78:81]
	v_mfma_f32_16x16x32_bf16 v[126:129], v[146:149], v[162:165], v[126:129]
	v_mfma_f32_16x16x32_bf16 v[122:125], v[154:157], v[162:165], v[122:125]
	v_mfma_f32_16x16x32_bf16 v[118:121], v[146:149], v[170:173], v[118:121]
	v_mfma_f32_16x16x32_bf16 v[110:113], v[154:157], v[170:173], v[110:113]
	v_mfma_f32_16x16x32_bf16 v[102:105], v[146:149], v[182:185], v[102:105]
	v_mfma_f32_16x16x32_bf16 v[94:97], v[154:157], v[182:185], v[94:97]
	v_mfma_f32_16x16x32_bf16 v[86:89], v[146:149], v[190:193], v[86:89]
	v_mfma_f32_16x16x32_bf16 v[78:81], v[154:157], v[190:193], v[78:81]
	s_barrier
	s_add_i32 s34, 0, 0x1c000
	s_add_i32 s35, s38, s9
	v_add_u32_e32 v181, s34, v139
	v_lshl_add_u64 v[136:137], v[136:137], 0, s[76:77]
	s_mov_b32 m0, s35
	ds_read_b128 v[194:197], v181
	ds_read_b128 v[220:223], v181 offset:1024
	ds_read_b128 v[224:227], v181 offset:2048
	ds_read_b128 v[228:231], v181 offset:3072
	global_load_lds_dwordx4 v[136:137], off
	v_lshl_add_u64 v[136:137], v[198:199], 0, s[76:77]
	s_add_i32 m0, s35, 0x2000
	s_nop 0
	global_load_lds_dwordx4 v[136:137], off
	s_barrier
	s_waitcnt lgkmcnt(0)
	v_mfma_f32_16x16x32_bf16 v[114:117], v[194:197], v[158:161], v[114:117]
	v_mfma_f32_16x16x32_bf16 v[106:109], v[224:227], v[158:161], v[106:109]
	v_mfma_f32_16x16x32_bf16 v[98:101], v[194:197], v[166:169], v[98:101]
	v_mfma_f32_16x16x32_bf16 v[90:93], v[224:227], v[166:169], v[90:93]
	v_mfma_f32_16x16x32_bf16 v[82:85], v[194:197], v[174:177], v[82:85]
	v_mfma_f32_16x16x32_bf16 v[74:77], v[224:227], v[174:177], v[74:77]
	v_mfma_f32_16x16x32_bf16 v[70:73], v[194:197], v[186:189], v[70:73]
	v_mfma_f32_16x16x32_bf16 v[66:69], v[224:227], v[186:189], v[66:69]
	v_mfma_f32_16x16x32_bf16 v[114:117], v[220:223], v[162:165], v[114:117]
	v_mfma_f32_16x16x32_bf16 v[106:109], v[228:231], v[162:165], v[106:109]
	v_mfma_f32_16x16x32_bf16 v[98:101], v[220:223], v[170:173], v[98:101]
	v_mfma_f32_16x16x32_bf16 v[90:93], v[228:231], v[170:173], v[90:93]
	v_mfma_f32_16x16x32_bf16 v[82:85], v[220:223], v[182:185], v[82:85]
	v_mfma_f32_16x16x32_bf16 v[74:77], v[228:231], v[182:185], v[74:77]
	v_mfma_f32_16x16x32_bf16 v[70:73], v[220:223], v[190:193], v[70:73]
	v_mfma_f32_16x16x32_bf16 v[66:69], v[228:231], v[190:193], v[66:69]
	s_barrier
	s_mov_b32 m0, s50
	v_lshl_add_u64 v[136:137], v[232:233], 0, s[76:77]
	ds_read_b128 v[158:161], v141 offset:49152
	ds_read_b128 v[162:165], v141 offset:50176
	ds_read_b128 v[166:169], v141 offset:51200
	ds_read_b128 v[170:173], v141 offset:52224
	ds_read_b128 v[174:177], v141 offset:53248
	ds_read_b128 v[182:185], v141 offset:54272
	ds_read_b128 v[186:189], v141 offset:55296
	ds_read_b128 v[190:193], v141 offset:56320
	global_load_lds_dwordx4 v[136:137], off
	v_lshl_add_u64 v[136:137], v[234:235], 0, s[76:77]
	s_mov_b32 m0, s51
	s_nop 0
	global_load_lds_dwordx4 v[136:137], off
	s_barrier
; #define PG8_STAGE(bufoff, gbase, voff) do { _Pragma("unroll") for (int _i = 0; _i < 2; ++_i) \
;         __builtin_amdgcn_global_load_lds((const unsigned*)((const char*)(gbase) + (voff)[_i]), (LAS unsigned*)(lds + (bufoff) + ldsw + _i * 8192), 16, 0, 0); } while (0)
; #define PG8_LDA(dst, b, h) do { _Pragma("unroll") for (int m = 0; m < 4; ++m) _Pragma("unroll") for (int k = 0; k < 2; ++k) dst[m][k] = *(const LAS bf16x8*)(lds + PG8_SA(b, h) + aoff + m * 2048 + k * 1024); } while (0)
; #define PG8_MMA(ai, bj, At, Bt) do { __builtin_amdgcn_s_setprio(1); _Pragma("unroll") for (int m = 0; m < 4; ++m) _Pragma("unroll") for (int n = 0; n < 2; ++n) _Pragma("unroll") for (int k = 0; k < 2; ++k) \
;         acc[ai][bj][m][n] = __builtin_amdgcn_mfma_f32_16x16x32_bf16(Bt[n][k], At[m][k], acc[ai][bj][m][n], 0, 0, 0); __builtin_amdgcn_s_setprio(0); } while (0)
; #define PG8_WAIT_V(n) asm volatile("s_waitcnt vmcnt(" #n ")" ::: "memory")
; #define PG8_WAIT_L(n) asm volatile("s_waitcnt lgkmcnt(" #n ")" ::: "memory")
; #define PG8_BAR __builtin_amdgcn_s_barrier()
; #define PG8_SCHED __builtin_amdgcn_sched_barrier(0)
; template <int MODE, class EpiT, class Sched>
; __device__ __forceinline__ void gemm_phase(LAS unsigned char* lds, const Gemm g, const Sched& S, const EpiT& E) {
;     ...
;             PG8_LDA(At, 1, 1); PG8_STAGE(PG8_SA(1, 0), a3, voffA);
;             PG8_BAR; PG8_WAIT_L(0); PG8_MMA(1, 0, At, B0); PG8_BAR; PG8_SCHED;
;             PG8_STAGE(PG8_SB(1, 1), b3 + hstep, voffB);
;             PG8_WAIT_V(6); PG8_BAR; PG8_MMA(1, 1, At, B1); PG8_BAR;
;         }
	s_waitcnt lgkmcnt(0)
	v_mfma_f32_16x16x32_bf16 v[62:65], v[142:145], v[158:161], v[62:65]
	v_mfma_f32_16x16x32_bf16 v[58:61], v[150:153], v[158:161], v[58:61]
	v_mfma_f32_16x16x32_bf16 v[54:57], v[142:145], v[166:169], v[54:57]
	v_mfma_f32_16x16x32_bf16 v[46:49], v[150:153], v[166:169], v[46:49]
	v_mfma_f32_16x16x32_bf16 v[38:41], v[142:145], v[174:177], v[38:41]
	v_mfma_f32_16x16x32_bf16 v[30:33], v[150:153], v[174:177], v[30:33]
	v_mfma_f32_16x16x32_bf16 v[22:25], v[142:145], v[186:189], v[22:25]
	v_mfma_f32_16x16x32_bf16 v[14:17], v[150:153], v[186:189], v[14:17]
	v_mfma_f32_16x16x32_bf16 v[62:65], v[146:149], v[162:165], v[62:65]
	v_mfma_f32_16x16x32_bf16 v[58:61], v[154:157], v[162:165], v[58:61]
	v_mfma_f32_16x16x32_bf16 v[54:57], v[146:149], v[170:173], v[54:57]
	v_mfma_f32_16x16x32_bf16 v[46:49], v[154:157], v[170:173], v[46:49]
	v_mfma_f32_16x16x32_bf16 v[38:41], v[146:149], v[182:185], v[38:41]
	v_mfma_f32_16x16x32_bf16 v[30:33], v[154:157], v[182:185], v[30:33]
	v_mfma_f32_16x16x32_bf16 v[22:25], v[146:149], v[190:193], v[22:25]
	v_mfma_f32_16x16x32_bf16 v[14:17], v[154:157], v[190:193], v[14:17]
	s_barrier
	s_add_i32 s34, s34, s9
	v_lshl_add_u64 v[136:137], v[236:237], 0, s[76:77]
	s_mov_b32 m0, s34
	s_nop 0
	global_load_lds_dwordx4 v[136:137], off
	v_lshl_add_u64 v[136:137], v[238:239], 0, s[76:77]
	s_add_i32 m0, s34, 0x2000
	s_nop 0
	global_load_lds_dwordx4 v[136:137], off
	s_waitcnt vmcnt(6)
	s_barrier
	v_mfma_f32_16x16x32_bf16 v[50:53], v[194:197], v[158:161], v[50:53]
	v_mfma_f32_16x16x32_bf16 v[42:45], v[224:227], v[158:161], v[42:45]
	v_mfma_f32_16x16x32_bf16 v[34:37], v[194:197], v[166:169], v[34:37]
	v_mfma_f32_16x16x32_bf16 v[26:29], v[224:227], v[166:169], v[26:29]
	v_mfma_f32_16x16x32_bf16 v[18:21], v[194:197], v[174:177], v[18:21]
	v_mfma_f32_16x16x32_bf16 v[10:13], v[224:227], v[174:177], v[10:13]
	v_mfma_f32_16x16x32_bf16 v[6:9], v[194:197], v[186:189], v[6:9]
	v_mfma_f32_16x16x32_bf16 v[2:5], v[224:227], v[186:189], v[2:5]
	v_mfma_f32_16x16x32_bf16 v[50:53], v[220:223], v[162:165], v[50:53]
	v_mfma_f32_16x16x32_bf16 v[42:45], v[228:231], v[162:165], v[42:45]
	v_mfma_f32_16x16x32_bf16 v[34:37], v[220:223], v[170:173], v[34:37]
	v_mfma_f32_16x16x32_bf16 v[26:29], v[228:231], v[170:173], v[26:29]
	v_mfma_f32_16x16x32_bf16 v[18:21], v[220:223], v[182:185], v[18:21]
	v_mfma_f32_16x16x32_bf16 v[10:13], v[228:231], v[182:185], v[10:13]
	v_mfma_f32_16x16x32_bf16 v[6:9], v[220:223], v[190:193], v[6:9]
	v_mfma_f32_16x16x32_bf16 v[2:5], v[228:231], v[190:193], v[2:5]
	s_barrier
	s_add_u32 s28, s28, 0x100
	s_addc_u32 s29, s29, 0
	s_add_u32 s42, s42, 0x100
	s_addc_u32 s43, s43, 0
	s_cmp_ge_u32 s44, s47
	s_mov_b32 s34, s44
	s_cbranch_scc0 .LBB0_236
; __device__ __forceinline__ unsigned pk2(float lo, float hi) { unsigned r; asm volatile("v_cvt_pk_bf16_f32 %0, %1, %2" : "=v"(r) : "v"(lo), "v"(hi)); return r; }
; #define PG8_WAIT_V(n) asm volatile("s_waitcnt vmcnt(" #n ")" ::: "memory")
; #define PG8_BAR __builtin_amdgcn_s_barrier()
;     template <int mode> __device__ __forceinline__ void run(const f32x4 (&acc)[2][2][4][2], const Unit& u, int wr, int wc, int fr, int fq, const LAS float* sc) const {
;     ...
;         } else if (mode == 2) {
;             const int col0 = u.pn * BM + wc * 32 + 8 * fq;
; #pragma unroll
;             for (int ai = 0; ai < 2; ++ai)
; #pragma unroll
;                 for (int m = 0; m < 4; ++m) {
;                     bf16_t* rowp = ob + (size_t)(row0 + ai * HALF + m * 16) * D + col0;
; #pragma unroll
;                     for (int bj = 0; bj < 2; ++bj) {
;                         const f32x4 v0 = acc[ai][bj][m][0], v1 = acc[ai][bj][m][1];
;                         u32x4 w; w.x = pk2(v0[0], v0[1]); w.y = pk2(v0[2], v0[3]); w.z = pk2(v1[0], v1[1]); w.w = pk2(v1[2], v1[3]);
;                         *(u32x4*)(rowp + bj * HALF) = w;
;                     }
;                 }
; template <int MODE, class EpiT, class Sched>
; __device__ __forceinline__ void gemm_phase(LAS unsigned char* lds, const Gemm g, const Sched& S, const EpiT& E) {
;     ...
;         E.template run<MODE>(acc, cur, wr, wc, fr, fq, SC + ui * 256);
;         if (!has_next) break;
; #pragma unroll
;         for (int a = 0; a < 2; ++a)
; #pragma unroll
;             for (int b = 0; b < 2; ++b)
; #pragma unroll
;                 for (int m = 0; m < 4; ++m)
; #pragma unroll
;                     for (int n = 0; n < 2; ++n) acc[a][b][m][n] = (f32x4){0.f, 0.f, 0.f, 0.f};
;         cur = nxt; cA = nA; cB = nB; ++ui;
;     }
;     PG8_WAIT_V(0);
;     if (wr == 0) PG8_BAR;
;     PG8_BAR;
	v_lshl_add_u32 v142, s56, 8, v138
	v_lshl_or_b32 v136, s61, 8, v140
	v_ashrrev_i32_e32 v143, 31, v142
	v_ashrrev_i32_e32 v137, 31, v136
	v_lshlrev_b64 v[144:145], 11, v[142:143]
	v_lshl_add_u64 v[144:145], s[6:7], 0, v[144:145]
	v_lshlrev_b64 v[146:147], 1, v[136:137]
	v_lshl_add_u64 v[136:137], v[144:145], 0, v[146:147]
	v_cvt_pk_bf16_f32 v126, v126, v127
	v_cvt_pk_bf16_f32 v127, v128, v129
	v_cvt_pk_bf16_f32 v128, v122, v123
	v_cvt_pk_bf16_f32 v129, v124, v125
	global_store_dwordx4 v[136:137], v[126:129], off
	v_cvt_pk_bf16_f32 v114, v114, v115
	v_cvt_pk_bf16_f32 v115, v116, v117
	v_cvt_pk_bf16_f32 v116, v106, v107
	v_or_b32_e32 v106, 16, v142
	v_ashrrev_i32_e32 v107, 31, v106
	v_lshlrev_b64 v[106:107], 11, v[106:107]
	v_lshl_add_u64 v[106:107], s[6:7], 0, v[106:107]
	v_cvt_pk_bf16_f32 v117, v108, v109
	global_store_dwordx4 v[136:137], v[114:117], off offset:256
	s_mov_b64 s[28:29], 0x40000
	s_mov_b32 s61, s57
	v_lshl_add_u64 v[114:115], v[106:107], 0, v[146:147]
	v_cvt_pk_bf16_f32 v106, v118, v119
	v_cvt_pk_bf16_f32 v107, v120, v121
	v_cvt_pk_bf16_f32 v108, v110, v111
	v_cvt_pk_bf16_f32 v109, v112, v113
	global_store_dwordx4 v[114:115], v[106:109], off
	v_cvt_pk_bf16_f32 v98, v98, v99
	v_cvt_pk_bf16_f32 v99, v100, v101
	v_cvt_pk_bf16_f32 v100, v90, v91
	v_or_b32_e32 v90, 32, v142
	v_ashrrev_i32_e32 v91, 31, v90
	v_lshlrev_b64 v[90:91], 11, v[90:91]
	v_lshl_add_u64 v[90:91], s[6:7], 0, v[90:91]
	v_cvt_pk_bf16_f32 v101, v92, v93
	global_store_dwordx4 v[114:115], v[98:101], off offset:256
	s_mov_b32 s56, s60
	s_mov_b64 s[34:35], s[10:11]
	v_lshl_add_u64 v[98:99], v[90:91], 0, v[146:147]
	v_cvt_pk_bf16_f32 v90, v102, v103
	v_cvt_pk_bf16_f32 v91, v104, v105
	v_cvt_pk_bf16_f32 v92, v94, v95
	v_cvt_pk_bf16_f32 v93, v96, v97
	global_store_dwordx4 v[98:99], v[90:93], off
	v_cvt_pk_bf16_f32 v82, v82, v83
	v_cvt_pk_bf16_f32 v83, v84, v85
	v_cvt_pk_bf16_f32 v84, v74, v75
	v_or_b32_e32 v74, 48, v142
	v_ashrrev_i32_e32 v75, 31, v74
	v_lshlrev_b64 v[74:75], 11, v[74:75]
	v_lshl_add_u64 v[74:75], s[6:7], 0, v[74:75]
	v_cvt_pk_bf16_f32 v85, v76, v77
	global_store_dwordx4 v[98:99], v[82:85], off offset:256
	s_nop 1
	v_lshl_add_u64 v[82:83], v[74:75], 0, v[146:147]
	v_cvt_pk_bf16_f32 v74, v86, v87
	v_cvt_pk_bf16_f32 v75, v88, v89
	v_cvt_pk_bf16_f32 v76, v78, v79
	v_cvt_pk_bf16_f32 v77, v80, v81
	global_store_dwordx4 v[82:83], v[74:77], off
	v_cvt_pk_bf16_f32 v70, v70, v71
	v_cvt_pk_bf16_f32 v71, v72, v73
	v_cvt_pk_bf16_f32 v72, v66, v67
	v_cvt_pk_bf16_f32 v73, v68, v69
	global_store_dwordx4 v[82:83], v[70:73], off offset:256
	v_cvt_pk_bf16_f32 v62, v62, v63
	v_cvt_pk_bf16_f32 v63, v64, v65
	v_cvt_pk_bf16_f32 v64, v58, v59
	v_add_co_u32_e32 v58, vcc, s91, v136
	v_lshl_add_u64 v[66:67], v[136:137], 0, s[28:29]
	s_nop 0
	v_addc_co_u32_e32 v59, vcc, 0, v137, vcc
	v_cvt_pk_bf16_f32 v65, v60, v61
	global_store_dwordx4 v[58:59], v[62:65], off
	v_cvt_pk_bf16_f32 v50, v50, v51
	v_cvt_pk_bf16_f32 v51, v52, v53
	s_mov_b64 s[28:29], 0x48000
	v_cvt_pk_bf16_f32 v52, v42, v43
	v_cvt_pk_bf16_f32 v53, v44, v45
	global_store_dwordx4 v[66:67], v[50:53], off offset:256
	v_cvt_pk_bf16_f32 v42, v54, v55
	v_cvt_pk_bf16_f32 v43, v56, v57
	v_cvt_pk_bf16_f32 v44, v46, v47
	v_cvt_pk_bf16_f32 v45, v48, v49
	s_nop 1
	v_lshl_add_u64 v[50:51], v[136:137], 0, s[28:29]
	s_mov_b32 s28, 0x48000
	v_add_co_u32_e32 v46, vcc, s28, v136
	s_mov_b64 s[28:29], 0x50000
	s_nop 0
	v_addc_co_u32_e32 v47, vcc, 0, v137, vcc
	global_store_dwordx4 v[46:47], v[42:45], off
	v_cvt_pk_bf16_f32 v34, v34, v35
	v_cvt_pk_bf16_f32 v35, v36, v37
	v_cvt_pk_bf16_f32 v36, v26, v27
	v_cvt_pk_bf16_f32 v37, v28, v29
	global_store_dwordx4 v[50:51], v[34:37], off offset:256
	v_cvt_pk_bf16_f32 v26, v38, v39
	v_cvt_pk_bf16_f32 v27, v40, v41
	v_cvt_pk_bf16_f32 v28, v30, v31
	v_cvt_pk_bf16_f32 v29, v32, v33
	s_nop 1
	v_lshl_add_u64 v[34:35], v[136:137], 0, s[28:29]
	s_mov_b32 s28, 0x50000
	v_add_co_u32_e32 v30, vcc, s28, v136
	s_mov_b64 s[28:29], 0x58000
	s_nop 0
	v_addc_co_u32_e32 v31, vcc, 0, v137, vcc
	global_store_dwordx4 v[30:31], v[26:29], off
	v_cvt_pk_bf16_f32 v18, v18, v19
	v_cvt_pk_bf16_f32 v19, v20, v21
	v_cvt_pk_bf16_f32 v20, v10, v11
	v_cvt_pk_bf16_f32 v21, v12, v13
	global_store_dwordx4 v[34:35], v[18:21], off offset:256
	v_cvt_pk_bf16_f32 v10, v22, v23
	v_cvt_pk_bf16_f32 v11, v24, v25
	v_cvt_pk_bf16_f32 v12, v14, v15
	v_cvt_pk_bf16_f32 v13, v16, v17
	s_nop 1
	v_lshl_add_u64 v[18:19], v[136:137], 0, s[28:29]
	s_mov_b32 s28, 0x58000
	v_add_co_u32_e32 v14, vcc, s28, v136
	s_mov_b64 s[28:29], s[4:5]
	s_nop 0
	v_addc_co_u32_e32 v15, vcc, 0, v137, vcc
	s_and_b64 vcc, exec, s[40:41]
	global_store_dwordx4 v[14:15], v[10:13], off
	v_cvt_pk_bf16_f32 v6, v6, v7
	v_cvt_pk_bf16_f32 v7, v8, v9
	v_cvt_pk_bf16_f32 v8, v2, v3
	v_cvt_pk_bf16_f32 v9, v4, v5
	global_store_dwordx4 v[18:19], v[6:9], off offset:256
	s_cbranch_vccz .LBB0_229
	s_waitcnt vmcnt(0)
	v_readlane_b32 s46, v247, 49
	v_readlane_b32 s50, v246, 29
	v_readlane_b32 s56, v246, 31
	v_readlane_b32 s58, v246, 33
	v_readlane_b32 s60, v246, 35
	s_cmpk_gt_u32 s2, 0xff
	s_mov_b32 s52, 0x800000
	s_movk_i32 s53, 0x1000
	s_movk_i32 s23, 0x2000
	s_movk_i32 s30, 0x2840
	s_movk_i32 s42, 0x3000
	s_mov_b64 s[44:45], 0x1800
	v_readlane_b32 s47, v247, 50
	v_readlane_b32 s43, v247, 51
	v_readlane_b32 s51, v246, 30
	v_readlane_b32 s57, v246, 32
	v_readlane_b32 s59, v246, 34
	v_readlane_b32 s61, v246, 36
	s_cbranch_scc1 .LBB0_240
	s_barrier

; #define PG8_STAGE(bufoff, gbase, voff) do { _Pragma("unroll") for (int _i = 0; _i < 2; ++_i) \
;         __builtin_amdgcn_global_load_lds((const unsigned*)((const char*)(gbase) + (voff)[_i]), (LAS unsigned*)(lds + (bufoff) + ldsw + _i * 8192), 16, 0, 0); } while (0)
; #define PG8_LDA(dst, b, h) do { _Pragma("unroll") for (int m = 0; m < 4; ++m) _Pragma("unroll") for (int k = 0; k < 2; ++k) dst[m][k] = *(const LAS bf16x8*)(lds + PG8_SA(b, h) + aoff + m * 2048 + k * 1024); } while (0)
; #define PG8_LDB(dst, b, h) do { _Pragma("unroll") for (int n = 0; n < 2; ++n) _Pragma("unroll") for (int k = 0; k < 2; ++k) dst[n][k] = *(const LAS bf16x8*)(lds + PG8_SB(b, h) + boff + n * 2048 + k * 1024); } while (0)
; #define PG8_MMA(ai, bj, At, Bt) do { __builtin_amdgcn_s_setprio(1); _Pragma("unroll") for (int m = 0; m < 4; ++m) _Pragma("unroll") for (int n = 0; n < 2; ++n) _Pragma("unroll") for (int k = 0; k < 2; ++k) \
;         acc[ai][bj][m][n] = __builtin_amdgcn_mfma_f32_16x16x32_bf16(Bt[n][k], At[m][k], acc[ai][bj][m][n], 0, 0, 0); __builtin_amdgcn_s_setprio(0); } while (0)
; #define PG8_WAIT_L(n) asm volatile("s_waitcnt lgkmcnt(" #n ")" ::: "memory")
; template <int MODE, class EpiT, class Sched>
; __device__ __forceinline__ void gemm_phase(LAS unsigned char* lds, const Gemm g, const Sched& S, const EpiT& E) {
;     ...
;         const bool has_next = S.next(ui + 1, nxt);
;         const char* nA = has_next ? (const char*)g.A + (size_t)nxt.pm * tstep : cA; const char* nB = has_next ? (const char*)g.Bt + (size_t)nxt.pn * tstep : cB;
;         for (int t = 0; t < nt; t += 2) {
;             const bool last = (t == nt - 2);
;             const char* a1 = cA + (size_t)(t + 1) * kstep;
;             const char* a2 = last ? nA : cA + (size_t)(t + 2) * kstep; const char* b2 = last ? nB : cB + (size_t)(t + 2) * kstep;
;             const char* a3 = a2 + kstep; const char* b3 = b2 + kstep;
;             PG8_LDB(B0, 0, 0); PG8_SCHED; PG8_LDA(At, 0, 0); PG8_STAGE(PG8_SA(1, 1), a1 + hstep, voffA);
;             PG8_WAIT_L(8); PG8_BAR; PG8_WAIT_L(0); PG8_MMA(0, 0, At, B0); PG8_BAR; PG8_SCHED;
;             PG8_LDB(B1, 0, 1); PG8_STAGE(PG8_SB(0, 0), b2, voffB);
;             PG8_BAR; PG8_WAIT_L(0); PG8_MMA(0, 1, At, B1); PG8_BAR;
;             PG8_LDA(At, 0, 1); PG8_STAGE(PG8_SA(0, 0), a2, voffA);
;             PG8_BAR; PG8_WAIT_L(0); PG8_MMA(1, 0, At, B0); PG8_BAR; PG8_SCHED;
.LBB0_280:
	s_add_i32 s68, s46, 2
	s_add_u32 s52, s10, s44
	s_addc_u32 s47, s11, s45
	s_add_u32 s58, s4, s44
	s_addc_u32 s53, s5, s45
	s_add_i32 s59, 0, 0x10000
	v_add_u32_e32 v152, s59, v157
	ds_read_b128 v[134:137], v152
	ds_read_b128 v[138:141], v152 offset:1024
	ds_read_b128 v[142:145], v152 offset:2048
	ds_read_b128 v[152:155], v152 offset:3072
	ds_read_b128 v[162:165], v160
	ds_read_b128 v[166:169], v160 offset:1024
	ds_read_b128 v[170:173], v160 offset:2048
	ds_read_b128 v[174:177], v160 offset:3072
	ds_read_b128 v[182:185], v160 offset:4096
	ds_read_b128 v[186:189], v160 offset:5120
	ds_read_b128 v[190:193], v160 offset:6144
	ds_read_b128 v[194:197], v160 offset:7168
	s_cmp_eq_u32 s60, s46
	s_cselect_b32 s46, s34, s52
	s_cselect_b32 s47, s35, s47
	s_cselect_b32 s53, s39, s53
	s_cselect_b32 s52, s38, s58
	s_add_i32 m0, s30, 0xc000
	v_lshl_add_u64 v[198:199], s[10:11], 0, v[132:133]
	global_load_lds_dwordx4 v[198:199], off
	v_lshl_add_u64 v[198:199], s[10:11], 0, v[130:131]
	s_add_i32 m0, s30, 0xe000
	s_nop 0
	global_load_lds_dwordx4 v[198:199], off
	s_waitcnt lgkmcnt(8)
	s_barrier
	s_waitcnt lgkmcnt(0)
	v_mfma_f32_16x16x32_bf16 v[126:129], v[134:137], v[162:165], v[126:129]
	v_mfma_f32_16x16x32_bf16 v[122:125], v[142:145], v[162:165], v[122:125]
	v_mfma_f32_16x16x32_bf16 v[118:121], v[134:137], v[170:173], v[118:121]
	v_mfma_f32_16x16x32_bf16 v[114:117], v[142:145], v[170:173], v[114:117]
	v_mfma_f32_16x16x32_bf16 v[110:113], v[134:137], v[182:185], v[110:113]
	v_mfma_f32_16x16x32_bf16 v[106:109], v[142:145], v[182:185], v[106:109]
	v_mfma_f32_16x16x32_bf16 v[102:105], v[134:137], v[190:193], v[102:105]
	v_mfma_f32_16x16x32_bf16 v[98:101], v[142:145], v[190:193], v[98:101]
	v_mfma_f32_16x16x32_bf16 v[126:129], v[138:141], v[166:169], v[126:129]
	v_mfma_f32_16x16x32_bf16 v[122:125], v[152:155], v[166:169], v[122:125]
	v_mfma_f32_16x16x32_bf16 v[118:121], v[138:141], v[174:177], v[118:121]
	v_mfma_f32_16x16x32_bf16 v[114:117], v[152:155], v[174:177], v[114:117]
	v_mfma_f32_16x16x32_bf16 v[110:113], v[138:141], v[186:189], v[110:113]
	v_mfma_f32_16x16x32_bf16 v[106:109], v[152:155], v[186:189], v[106:109]
	v_mfma_f32_16x16x32_bf16 v[102:105], v[138:141], v[194:197], v[102:105]
	v_mfma_f32_16x16x32_bf16 v[98:101], v[152:155], v[194:197], v[98:101]
	s_barrier
	s_add_i32 s58, 0, 0x14000
	s_add_i32 s59, s59, s24
	v_add_u32_e32 v161, s58, v157
	v_lshl_add_u64 v[198:199], s[52:53], 0, v[0:1]
	s_mov_b32 m0, s59
	ds_read_b128 v[220:223], v161
	ds_read_b128 v[224:227], v161 offset:1024
	ds_read_b128 v[228:231], v161 offset:2048
	ds_read_b128 v[232:235], v161 offset:3072
	global_load_lds_dwordx4 v[198:199], off
	v_lshl_add_u64 v[236:237], s[52:53], 0, v[146:147]
	s_add_i32 m0, s59, 0x2000
	s_nop 0
	global_load_lds_dwordx4 v[236:237], off
	s_barrier
	s_waitcnt lgkmcnt(0)
	v_mfma_f32_16x16x32_bf16 v[94:97], v[220:223], v[162:165], v[94:97]
	v_mfma_f32_16x16x32_bf16 v[90:93], v[228:231], v[162:165], v[90:93]
	v_mfma_f32_16x16x32_bf16 v[86:89], v[220:223], v[170:173], v[86:89]
	v_mfma_f32_16x16x32_bf16 v[82:85], v[228:231], v[170:173], v[82:85]
	v_mfma_f32_16x16x32_bf16 v[78:81], v[220:223], v[182:185], v[78:81]
	v_mfma_f32_16x16x32_bf16 v[74:77], v[228:231], v[182:185], v[74:77]
	v_mfma_f32_16x16x32_bf16 v[70:73], v[220:223], v[190:193], v[70:73]
	v_mfma_f32_16x16x32_bf16 v[66:69], v[228:231], v[190:193], v[66:69]
	v_mfma_f32_16x16x32_bf16 v[94:97], v[224:227], v[166:169], v[94:97]
	v_mfma_f32_16x16x32_bf16 v[90:93], v[232:235], v[166:169], v[90:93]
	v_mfma_f32_16x16x32_bf16 v[86:89], v[224:227], v[174:177], v[86:89]
	v_mfma_f32_16x16x32_bf16 v[82:85], v[232:235], v[174:177], v[82:85]
	v_mfma_f32_16x16x32_bf16 v[78:81], v[224:227], v[186:189], v[78:81]
	v_mfma_f32_16x16x32_bf16 v[74:77], v[232:235], v[186:189], v[74:77]
	v_mfma_f32_16x16x32_bf16 v[70:73], v[224:227], v[194:197], v[70:73]
	v_mfma_f32_16x16x32_bf16 v[66:69], v[232:235], v[194:197], v[66:69]
	s_barrier
	s_mov_b32 m0, s30
	v_lshl_add_u64 v[238:239], s[46:47], 0, v[0:1]
	ds_read_b128 v[162:165], v160 offset:16384
	ds_read_b128 v[166:169], v160 offset:17408
	ds_read_b128 v[170:173], v160 offset:18432
	ds_read_b128 v[174:177], v160 offset:19456
	ds_read_b128 v[182:185], v160 offset:20480
	ds_read_b128 v[186:189], v160 offset:21504
	ds_read_b128 v[190:193], v160 offset:22528
	ds_read_b128 v[194:197], v160 offset:23552
	global_load_lds_dwordx4 v[238:239], off
	v_lshl_add_u64 v[240:241], s[46:47], 0, v[146:147]
	s_mov_b32 m0, s50
	s_nop 0
	global_load_lds_dwordx4 v[240:241], off
	s_barrier
	s_waitcnt lgkmcnt(0)
	v_mfma_f32_16x16x32_bf16 v[62:65], v[134:137], v[162:165], v[62:65]
	v_mfma_f32_16x16x32_bf16 v[58:61], v[142:145], v[162:165], v[58:61]
	v_mfma_f32_16x16x32_bf16 v[54:57], v[134:137], v[170:173], v[54:57]
	v_mfma_f32_16x16x32_bf16 v[50:53], v[142:145], v[170:173], v[50:53]
	v_mfma_f32_16x16x32_bf16 v[46:49], v[134:137], v[182:185], v[46:49]
	v_mfma_f32_16x16x32_bf16 v[42:45], v[142:145], v[182:185], v[42:45]
	v_mfma_f32_16x16x32_bf16 v[38:41], v[134:137], v[190:193], v[38:41]
	v_mfma_f32_16x16x32_bf16 v[34:37], v[142:145], v[190:193], v[34:37]
	v_mfma_f32_16x16x32_bf16 v[62:65], v[138:141], v[166:169], v[62:65]
	v_mfma_f32_16x16x32_bf16 v[58:61], v[152:155], v[166:169], v[58:61]
	v_mfma_f32_16x16x32_bf16 v[54:57], v[138:141], v[174:177], v[54:57]
	v_mfma_f32_16x16x32_bf16 v[50:53], v[152:155], v[174:177], v[50:53]
	v_mfma_f32_16x16x32_bf16 v[46:49], v[138:141], v[186:189], v[46:49]
	v_mfma_f32_16x16x32_bf16 v[42:45], v[152:155], v[186:189], v[42:45]
	v_mfma_f32_16x16x32_bf16 v[38:41], v[138:141], v[194:197], v[38:41]
	v_mfma_f32_16x16x32_bf16 v[34:37], v[152:155], v[194:197], v[34:37]
	s_barrier
; #define PG8_STAGE(bufoff, gbase, voff) do { _Pragma("unroll") for (int _i = 0; _i < 2; ++_i) \
;         __builtin_amdgcn_global_load_lds((const unsigned*)((const char*)(gbase) + (voff)[_i]), (LAS unsigned*)(lds + (bufoff) + ldsw + _i * 8192), 16, 0, 0); } while (0)
; #define PG8_LDA(dst, b, h) do { _Pragma("unroll") for (int m = 0; m < 4; ++m) _Pragma("unroll") for (int k = 0; k < 2; ++k) dst[m][k] = *(const LAS bf16x8*)(lds + PG8_SA(b, h) + aoff + m * 2048 + k * 1024); } while (0)
; #define PG8_LDB(dst, b, h) do { _Pragma("unroll") for (int n = 0; n < 2; ++n) _Pragma("unroll") for (int k = 0; k < 2; ++k) dst[n][k] = *(const LAS bf16x8*)(lds + PG8_SB(b, h) + boff + n * 2048 + k * 1024); } while (0)
; #define PG8_MMA(ai, bj, At, Bt) do { __builtin_amdgcn_s_setprio(1); _Pragma("unroll") for (int m = 0; m < 4; ++m) _Pragma("unroll") for (int n = 0; n < 2; ++n) _Pragma("unroll") for (int k = 0; k < 2; ++k) \
;         acc[ai][bj][m][n] = __builtin_amdgcn_mfma_f32_16x16x32_bf16(Bt[n][k], At[m][k], acc[ai][bj][m][n], 0, 0, 0); __builtin_amdgcn_s_setprio(0); } while (0)
; #define PG8_WAIT_V(n) asm volatile("s_waitcnt vmcnt(" #n ")" ::: "memory")
; #define PG8_WAIT_L(n) asm volatile("s_waitcnt lgkmcnt(" #n ")" ::: "memory")
; #define PG8_BAR __builtin_amdgcn_s_barrier()
; #define PG8_SCHED __builtin_amdgcn_sched_barrier(0)
; template <int MODE, class EpiT, class Sched>
; __device__ __forceinline__ void gemm_phase(LAS unsigned char* lds, const Gemm g, const Sched& S, const EpiT& E) {
;     ...
;             PG8_STAGE(PG8_SB(0, 1), b2 + hstep, voffB);
;             PG8_WAIT_V(6); PG8_BAR; PG8_MMA(1, 1, At, B1); PG8_BAR;
;             PG8_LDB(B0, 1, 0); PG8_SCHED; PG8_LDA(At, 1, 0); PG8_STAGE(PG8_SA(0, 1), a2 + hstep, voffA);
;             PG8_WAIT_L(8); PG8_BAR; PG8_WAIT_L(0); PG8_MMA(0, 0, At, B0); PG8_BAR; PG8_SCHED;
;             PG8_LDB(B1, 1, 1); PG8_STAGE(PG8_SB(1, 0), b3, voffB);
;             PG8_BAR; PG8_WAIT_L(0); PG8_MMA(0, 1, At, B1); PG8_BAR;
;             PG8_LDA(At, 1, 1); PG8_STAGE(PG8_SA(1, 0), a3, voffA);
;             PG8_BAR; PG8_WAIT_L(0); PG8_MMA(1, 0, At, B0); PG8_BAR; PG8_SCHED;
	s_add_u32 s52, s52, s22
	s_addc_u32 s53, s53, 0
	s_add_i32 s58, s58, s24
	v_lshl_add_u64 v[242:243], s[52:53], 0, v[0:1]
	s_mov_b32 m0, s58
	v_lshl_add_u64 v[244:245], s[52:53], 0, v[146:147]
	global_load_lds_dwordx4 v[242:243], off
	s_add_i32 m0, s58, 0x2000
	s_nop 0
	global_load_lds_dwordx4 v[244:245], off
	s_waitcnt vmcnt(6)
	s_barrier
	v_mfma_f32_16x16x32_bf16 v[30:33], v[220:223], v[162:165], v[30:33]
	v_mfma_f32_16x16x32_bf16 v[26:29], v[228:231], v[162:165], v[26:29]
	v_mfma_f32_16x16x32_bf16 v[22:25], v[220:223], v[170:173], v[22:25]
	v_mfma_f32_16x16x32_bf16 v[18:21], v[228:231], v[170:173], v[18:21]
	v_mfma_f32_16x16x32_bf16 v[14:17], v[220:223], v[182:185], v[14:17]
	v_mfma_f32_16x16x32_bf16 v[10:13], v[228:231], v[182:185], v[10:13]
	v_mfma_f32_16x16x32_bf16 v[6:9], v[220:223], v[190:193], v[6:9]
	v_mfma_f32_16x16x32_bf16 v[2:5], v[228:231], v[190:193], v[2:5]
	v_mfma_f32_16x16x32_bf16 v[30:33], v[224:227], v[166:169], v[30:33]
	v_mfma_f32_16x16x32_bf16 v[26:29], v[232:235], v[166:169], v[26:29]
	v_mfma_f32_16x16x32_bf16 v[22:25], v[224:227], v[174:177], v[22:25]
	v_mfma_f32_16x16x32_bf16 v[18:21], v[232:235], v[174:177], v[18:21]
	v_mfma_f32_16x16x32_bf16 v[14:17], v[224:227], v[186:189], v[14:17]
	v_mfma_f32_16x16x32_bf16 v[10:13], v[232:235], v[186:189], v[10:13]
	v_mfma_f32_16x16x32_bf16 v[6:9], v[224:227], v[194:197], v[6:9]
	v_mfma_f32_16x16x32_bf16 v[2:5], v[232:235], v[194:197], v[2:5]
	s_barrier
	s_add_i32 s52, 0, 0x18000
	v_add_u32_e32 v152, s52, v157
	ds_read_b128 v[134:137], v152
	ds_read_b128 v[138:141], v152 offset:1024
	ds_read_b128 v[142:145], v152 offset:2048
	ds_read_b128 v[152:155], v152 offset:3072
	ds_read_b128 v[162:165], v160 offset:32768
	ds_read_b128 v[166:169], v160 offset:33792
	ds_read_b128 v[170:173], v160 offset:34816
	ds_read_b128 v[174:177], v160 offset:35840
	ds_read_b128 v[182:185], v160 offset:36864
	ds_read_b128 v[186:189], v160 offset:37888
	ds_read_b128 v[190:193], v160 offset:38912
	ds_read_b128 v[194:197], v160 offset:39936
	s_add_u32 s46, s46, s22
	s_addc_u32 s47, s47, 0
	s_mov_b32 m0, s51
	v_lshl_add_u64 v[220:221], s[46:47], 0, v[0:1]
	global_load_lds_dwordx4 v[220:221], off
	v_lshl_add_u64 v[220:221], s[46:47], 0, v[146:147]
	s_mov_b32 m0, s54
	s_nop 0
	global_load_lds_dwordx4 v[220:221], off
	s_waitcnt lgkmcnt(8)
	s_barrier
	s_waitcnt lgkmcnt(0)
	v_mfma_f32_16x16x32_bf16 v[126:129], v[134:137], v[162:165], v[126:129]
	v_mfma_f32_16x16x32_bf16 v[122:125], v[142:145], v[162:165], v[122:125]
	v_mfma_f32_16x16x32_bf16 v[118:121], v[134:137], v[170:173], v[118:121]
	v_mfma_f32_16x16x32_bf16 v[114:117], v[142:145], v[170:173], v[114:117]
	v_mfma_f32_16x16x32_bf16 v[110:113], v[134:137], v[182:185], v[110:113]
	v_mfma_f32_16x16x32_bf16 v[106:109], v[142:145], v[182:185], v[106:109]
	v_mfma_f32_16x16x32_bf16 v[102:105], v[134:137], v[190:193], v[102:105]
	v_mfma_f32_16x16x32_bf16 v[98:101], v[142:145], v[190:193], v[98:101]
	v_mfma_f32_16x16x32_bf16 v[126:129], v[138:141], v[166:169], v[126:129]
	v_mfma_f32_16x16x32_bf16 v[122:125], v[152:155], v[166:169], v[122:125]
	v_mfma_f32_16x16x32_bf16 v[118:121], v[138:141], v[174:177], v[118:121]
	v_mfma_f32_16x16x32_bf16 v[114:117], v[152:155], v[174:177], v[114:117]
	v_mfma_f32_16x16x32_bf16 v[110:113], v[138:141], v[186:189], v[110:113]
	v_mfma_f32_16x16x32_bf16 v[106:109], v[152:155], v[186:189], v[106:109]
	v_mfma_f32_16x16x32_bf16 v[102:105], v[138:141], v[194:197], v[102:105]
	v_mfma_f32_16x16x32_bf16 v[98:101], v[152:155], v[194:197], v[98:101]
	s_barrier
	s_add_i32 s46, 0, 0x1c000
	s_add_i32 s47, s52, s24
	v_add_u32_e32 v161, s46, v157
	v_lshl_add_u64 v[198:199], v[198:199], 0, s[76:77]
	s_mov_b32 m0, s47
	ds_read_b128 v[220:223], v161
	ds_read_b128 v[224:227], v161 offset:1024
	ds_read_b128 v[228:231], v161 offset:2048
	ds_read_b128 v[232:235], v161 offset:3072
	global_load_lds_dwordx4 v[198:199], off
	v_lshl_add_u64 v[198:199], v[236:237], 0, s[76:77]
	s_add_i32 m0, s47, 0x2000
	s_nop 0
	global_load_lds_dwordx4 v[198:199], off
	s_barrier
; #define PG8_STAGE(bufoff, gbase, voff) do { _Pragma("unroll") for (int _i = 0; _i < 2; ++_i) \
;         __builtin_amdgcn_global_load_lds((const unsigned*)((const char*)(gbase) + (voff)[_i]), (LAS unsigned*)(lds + (bufoff) + ldsw + _i * 8192), 16, 0, 0); } while (0)
; #define PG8_LDA(dst, b, h) do { _Pragma("unroll") for (int m = 0; m < 4; ++m) _Pragma("unroll") for (int k = 0; k < 2; ++k) dst[m][k] = *(const LAS bf16x8*)(lds + PG8_SA(b, h) + aoff + m * 2048 + k * 1024); } while (0)
; #define PG8_LDB(dst, b, h) do { _Pragma("unroll") for (int n = 0; n < 2; ++n) _Pragma("unroll") for (int k = 0; k < 2; ++k) dst[n][k] = *(const LAS bf16x8*)(lds + PG8_SB(b, h) + boff + n * 2048 + k * 1024); } while (0)
; #define PG8_WAIT_V(n) asm volatile("s_waitcnt vmcnt(" #n ")" ::: "memory")
; #define PG8_WAIT_L(n) asm volatile("s_waitcnt lgkmcnt(" #n ")" ::: "memory")
; #define PG8_BAR __builtin_amdgcn_s_barrier()
; #define PG8_SCHED __builtin_amdgcn_sched_barrier(0)
;     template <int mode> __device__ __forceinline__ void run(const f32x4 (&acc)[2][2][4][2], const Unit& u, int wr, int wc, int fr, int fq, const LAS float* sc) const {
;     ...
;             const int col0 = u.pn * BM + wc * 32 + 8 * fq;
;             f32x4 bv[2][2];
; #pragma unroll
;             for (int bj = 0; bj < 2; ++bj)
; #pragma unroll
;                 for (int n = 0; n < 2; ++n) bv[bj][n] = bias ? *(const f32x4*)(bias + col0 + bj * HALF + 4 * n) : (f32x4){0.f, 0.f, 0.f, 0.f};
; template <int MODE, class EpiT, class Sched>
; __device__ __forceinline__ void gemm_phase(LAS unsigned char* lds, const Gemm g, const Sched& S, const EpiT& E) {
;     ...
;             PG8_WAIT_V(6); PG8_BAR; PG8_MMA(1, 1, At, B1); PG8_BAR;
;             PG8_LDB(B0, 1, 0); PG8_SCHED; PG8_LDA(At, 1, 0); PG8_STAGE(PG8_SA(0, 1), a2 + hstep, voffA);
;             PG8_WAIT_L(8); PG8_BAR; PG8_WAIT_L(0); PG8_MMA(0, 0, At, B0); PG8_BAR; PG8_SCHED;
;             PG8_LDB(B1, 1, 1); PG8_STAGE(PG8_SB(1, 0), b3, voffB);
;             PG8_BAR; PG8_WAIT_L(0); PG8_MMA(0, 1, At, B1); PG8_BAR;
;             PG8_LDA(At, 1, 1); PG8_STAGE(PG8_SA(1, 0), a3, voffA);
;             PG8_BAR; PG8_WAIT_L(0); PG8_MMA(1, 0, At, B0); PG8_BAR; PG8_SCHED;
;             PG8_STAGE(PG8_SB(1, 1), b3 + hstep, voffB);
;             PG8_WAIT_V(6); PG8_BAR; PG8_MMA(1, 1, At, B1); PG8_BAR;
;         }
	s_waitcnt lgkmcnt(0)
	v_mfma_f32_16x16x32_bf16 v[94:97], v[220:223], v[162:165], v[94:97]
	v_mfma_f32_16x16x32_bf16 v[90:93], v[228:231], v[162:165], v[90:93]
	v_mfma_f32_16x16x32_bf16 v[86:89], v[220:223], v[170:173], v[86:89]
	v_mfma_f32_16x16x32_bf16 v[82:85], v[228:231], v[170:173], v[82:85]
	v_mfma_f32_16x16x32_bf16 v[78:81], v[220:223], v[182:185], v[78:81]
	v_mfma_f32_16x16x32_bf16 v[74:77], v[228:231], v[182:185], v[74:77]
	v_mfma_f32_16x16x32_bf16 v[70:73], v[220:223], v[190:193], v[70:73]
	v_mfma_f32_16x16x32_bf16 v[66:69], v[228:231], v[190:193], v[66:69]
	v_mfma_f32_16x16x32_bf16 v[94:97], v[224:227], v[166:169], v[94:97]
	v_mfma_f32_16x16x32_bf16 v[90:93], v[232:235], v[166:169], v[90:93]
	v_mfma_f32_16x16x32_bf16 v[86:89], v[224:227], v[174:177], v[86:89]
	v_mfma_f32_16x16x32_bf16 v[82:85], v[232:235], v[174:177], v[82:85]
	v_mfma_f32_16x16x32_bf16 v[78:81], v[224:227], v[186:189], v[78:81]
	v_mfma_f32_16x16x32_bf16 v[74:77], v[232:235], v[186:189], v[74:77]
	v_mfma_f32_16x16x32_bf16 v[70:73], v[224:227], v[194:197], v[70:73]
	v_mfma_f32_16x16x32_bf16 v[66:69], v[232:235], v[194:197], v[66:69]
	s_barrier
	s_mov_b32 m0, s56
	v_lshl_add_u64 v[198:199], v[238:239], 0, s[76:77]
	ds_read_b128 v[162:165], v160 offset:49152
	ds_read_b128 v[166:169], v160 offset:50176
	ds_read_b128 v[170:173], v160 offset:51200
	ds_read_b128 v[174:177], v160 offset:52224
	ds_read_b128 v[182:185], v160 offset:53248
	ds_read_b128 v[186:189], v160 offset:54272
	ds_read_b128 v[190:193], v160 offset:55296
	ds_read_b128 v[194:197], v160 offset:56320
	global_load_lds_dwordx4 v[198:199], off
	v_lshl_add_u64 v[198:199], v[240:241], 0, s[76:77]
	s_mov_b32 m0, s57
	s_nop 0
	global_load_lds_dwordx4 v[198:199], off
	s_barrier
	s_waitcnt lgkmcnt(0)
	v_mfma_f32_16x16x32_bf16 v[62:65], v[134:137], v[162:165], v[62:65]
	v_mfma_f32_16x16x32_bf16 v[58:61], v[142:145], v[162:165], v[58:61]
	v_mfma_f32_16x16x32_bf16 v[54:57], v[134:137], v[170:173], v[54:57]
	v_mfma_f32_16x16x32_bf16 v[50:53], v[142:145], v[170:173], v[50:53]
	v_mfma_f32_16x16x32_bf16 v[46:49], v[134:137], v[182:185], v[46:49]
	v_mfma_f32_16x16x32_bf16 v[42:45], v[142:145], v[182:185], v[42:45]
	v_mfma_f32_16x16x32_bf16 v[38:41], v[134:137], v[190:193], v[38:41]
	v_mfma_f32_16x16x32_bf16 v[34:37], v[142:145], v[190:193], v[34:37]
	v_mfma_f32_16x16x32_bf16 v[62:65], v[138:141], v[166:169], v[62:65]
	v_mfma_f32_16x16x32_bf16 v[58:61], v[152:155], v[166:169], v[58:61]
	v_mfma_f32_16x16x32_bf16 v[54:57], v[138:141], v[174:177], v[54:57]
	v_mfma_f32_16x16x32_bf16 v[50:53], v[152:155], v[174:177], v[50:53]
	v_mfma_f32_16x16x32_bf16 v[46:49], v[138:141], v[186:189], v[46:49]
	v_mfma_f32_16x16x32_bf16 v[42:45], v[152:155], v[186:189], v[42:45]
	v_mfma_f32_16x16x32_bf16 v[38:41], v[138:141], v[194:197], v[38:41]
	v_mfma_f32_16x16x32_bf16 v[34:37], v[152:155], v[194:197], v[34:37]
	s_barrier
	s_add_i32 s46, s46, s24
	v_lshl_add_u64 v[134:135], v[242:243], 0, s[76:77]
	s_mov_b32 m0, s46
	s_nop 0
	global_load_lds_dwordx4 v[134:135], off
	v_lshl_add_u64 v[134:135], v[244:245], 0, s[76:77]
	s_add_i32 m0, s46, 0x2000
	s_nop 0
	global_load_lds_dwordx4 v[134:135], off
	s_waitcnt vmcnt(6)
	s_barrier
	v_mfma_f32_16x16x32_bf16 v[30:33], v[220:223], v[162:165], v[30:33]
	v_mfma_f32_16x16x32_bf16 v[26:29], v[228:231], v[162:165], v[26:29]
	v_mfma_f32_16x16x32_bf16 v[22:25], v[220:223], v[170:173], v[22:25]
	v_mfma_f32_16x16x32_bf16 v[18:21], v[228:231], v[170:173], v[18:21]
	v_mfma_f32_16x16x32_bf16 v[14:17], v[220:223], v[182:185], v[14:17]
	v_mfma_f32_16x16x32_bf16 v[10:13], v[228:231], v[182:185], v[10:13]
	v_mfma_f32_16x16x32_bf16 v[6:9], v[220:223], v[190:193], v[6:9]
	v_mfma_f32_16x16x32_bf16 v[2:5], v[228:231], v[190:193], v[2:5]
	v_mfma_f32_16x16x32_bf16 v[30:33], v[224:227], v[166:169], v[30:33]
	v_mfma_f32_16x16x32_bf16 v[26:29], v[232:235], v[166:169], v[26:29]
	v_mfma_f32_16x16x32_bf16 v[22:25], v[224:227], v[174:177], v[22:25]
	v_mfma_f32_16x16x32_bf16 v[18:21], v[232:235], v[174:177], v[18:21]
	v_mfma_f32_16x16x32_bf16 v[14:17], v[224:227], v[186:189], v[14:17]
	v_mfma_f32_16x16x32_bf16 v[10:13], v[232:235], v[186:189], v[10:13]
	v_mfma_f32_16x16x32_bf16 v[6:9], v[224:227], v[194:197], v[6:9]
	v_mfma_f32_16x16x32_bf16 v[2:5], v[232:235], v[194:197], v[2:5]
	s_barrier
	s_add_u32 s44, s44, 0x100
	s_addc_u32 s45, s45, 0
	v_lshl_add_u64 v[132:133], v[132:133], 0, s[80:81]
	v_lshl_add_u64 v[130:131], v[130:131], 0, s[80:81]
	s_cmp_ge_u32 s68, s55
	s_mov_b32 s46, s68
	s_cbranch_scc0 .LBB0_280
	v_lshl_or_b32 v152, s3, 8, v159
	v_ashrrev_i32_e32 v153, 31, v152
	v_cndmask_b32_e64 v131, 0, 1, s[28:29]
	v_lshl_add_u64 v[154:155], v[152:153], 2, s[12:13]
	v_mov_b32_e32 v130, 0
	v_cmp_ne_u32_e64 s[44:45], 1, v131
	s_andn2_b64 vcc, exec, s[28:29]
	v_mov_b32_e32 v134, 0
	v_mov_b32_e32 v135, 0
	v_mov_b32_e32 v136, 0
	v_mov_b32_e32 v137, 0
	s_cbranch_vccnz .LBB0_283
	global_load_dwordx4 v[134:137], v[154:155], off

; #define PG8_STAGE(bufoff, gbase, voff) do { _Pragma("unroll") for (int _i = 0; _i < 2; ++_i) \
;         __builtin_amdgcn_global_load_lds((const unsigned*)((const char*)(gbase) + (voff)[_i]), (LAS unsigned*)(lds + (bufoff) + ldsw + _i * 8192), 16, 0, 0); } while (0)
; #define PG8_LDA(dst, b, h) do { _Pragma("unroll") for (int m = 0; m < 4; ++m) _Pragma("unroll") for (int k = 0; k < 2; ++k) dst[m][k] = *(const LAS bf16x8*)(lds + PG8_SA(b, h) + aoff + m * 2048 + k * 1024); } while (0)
; #define PG8_LDB(dst, b, h) do { _Pragma("unroll") for (int n = 0; n < 2; ++n) _Pragma("unroll") for (int k = 0; k < 2; ++k) dst[n][k] = *(const LAS bf16x8*)(lds + PG8_SB(b, h) + boff + n * 2048 + k * 1024); } while (0)
; #define PG8_MMA(ai, bj, At, Bt) do { __builtin_amdgcn_s_setprio(1); _Pragma("unroll") for (int m = 0; m < 4; ++m) _Pragma("unroll") for (int n = 0; n < 2; ++n) _Pragma("unroll") for (int k = 0; k < 2; ++k) \
;         acc[ai][bj][m][n] = __builtin_amdgcn_mfma_f32_16x16x32_bf16(Bt[n][k], At[m][k], acc[ai][bj][m][n], 0, 0, 0); __builtin_amdgcn_s_setprio(0); } while (0)
; #define PG8_WAIT_L(n) asm volatile("s_waitcnt lgkmcnt(" #n ")" ::: "memory")
; template <int MODE, class EpiT, class Sched>
; __device__ __forceinline__ void gemm_phase(LAS unsigned char* lds, const Gemm g, const Sched& S, const EpiT& E) {
;     ...
;         const bool has_next = S.next(ui + 1, nxt);
;         const char* nA = has_next ? (const char*)g.A + (size_t)nxt.pm * tstep : cA; const char* nB = has_next ? (const char*)g.Bt + (size_t)nxt.pn * tstep : cB;
;         for (int t = 0; t < nt; t += 2) {
;             const bool last = (t == nt - 2);
;             const char* a1 = cA + (size_t)(t + 1) * kstep;
;             const char* a2 = last ? nA : cA + (size_t)(t + 2) * kstep; const char* b2 = last ? nB : cB + (size_t)(t + 2) * kstep;
;             const char* a3 = a2 + kstep; const char* b3 = b2 + kstep;
;             PG8_LDB(B0, 0, 0); PG8_SCHED; PG8_LDA(At, 0, 0); PG8_STAGE(PG8_SA(1, 1), a1 + hstep, voffA);
;             PG8_WAIT_L(8); PG8_BAR; PG8_WAIT_L(0); PG8_MMA(0, 0, At, B0); PG8_BAR; PG8_SCHED;
;             PG8_LDB(B1, 0, 1); PG8_STAGE(PG8_SB(0, 0), b2, voffB);
;             PG8_BAR; PG8_WAIT_L(0); PG8_MMA(0, 1, At, B1); PG8_BAR;
;             PG8_LDA(At, 0, 1); PG8_STAGE(PG8_SA(0, 0), a2, voffA);
;             PG8_BAR; PG8_WAIT_L(0); PG8_MMA(1, 0, At, B0); PG8_BAR; PG8_SCHED;
.LBB0_332:
	s_add_i32 s23, s22, 2
	s_add_u32 s30, s12, s4
	s_addc_u32 s38, s13, s5
	s_add_u32 s44, s10, s4
	s_addc_u32 s45, s11, s5
	s_add_i32 s58, 0, 0x10000
	v_add_u32_e32 v145, s58, v141
	ds_read_b128 v[146:149], v145
	ds_read_b128 v[150:153], v145 offset:1024
	ds_read_b128 v[154:157], v145 offset:2048
	ds_read_b128 v[158:161], v145 offset:3072
	ds_read_b128 v[162:165], v144
	ds_read_b128 v[166:169], v144 offset:1024
	ds_read_b128 v[170:173], v144 offset:2048
	ds_read_b128 v[174:177], v144 offset:3072
	ds_read_b128 v[182:185], v144 offset:4096
	ds_read_b128 v[186:189], v144 offset:5120
	ds_read_b128 v[190:193], v144 offset:6144
	ds_read_b128 v[194:197], v144 offset:7168
	s_cmp_eq_u32 s55, s22
	s_cselect_b32 s39, s29, s38
	s_cselect_b32 s38, s28, s30
	s_cselect_b32 s45, s35, s45
	s_cselect_b32 s44, s34, s44
	s_add_i32 m0, s47, 0xc000
	v_lshl_add_u64 v[198:199], s[12:13], 0, v[138:139]
	global_load_lds_dwordx4 v[198:199], off
	v_lshl_add_u64 v[198:199], s[12:13], 0, v[136:137]
	s_add_i32 m0, s47, 0xe000
	s_nop 0
	global_load_lds_dwordx4 v[198:199], off
	s_waitcnt lgkmcnt(8)
	s_barrier
	s_waitcnt lgkmcnt(0)
	v_mfma_f32_16x16x32_bf16 v[126:129], v[146:149], v[162:165], v[126:129]
	v_mfma_f32_16x16x32_bf16 v[122:125], v[154:157], v[162:165], v[122:125]
	v_mfma_f32_16x16x32_bf16 v[118:121], v[146:149], v[170:173], v[118:121]
	v_mfma_f32_16x16x32_bf16 v[114:117], v[154:157], v[170:173], v[114:117]
	v_mfma_f32_16x16x32_bf16 v[110:113], v[146:149], v[182:185], v[110:113]
	v_mfma_f32_16x16x32_bf16 v[106:109], v[154:157], v[182:185], v[106:109]
	v_mfma_f32_16x16x32_bf16 v[102:105], v[146:149], v[190:193], v[102:105]
	v_mfma_f32_16x16x32_bf16 v[98:101], v[154:157], v[190:193], v[98:101]
	v_mfma_f32_16x16x32_bf16 v[126:129], v[150:153], v[166:169], v[126:129]
	v_mfma_f32_16x16x32_bf16 v[122:125], v[158:161], v[166:169], v[122:125]
	v_mfma_f32_16x16x32_bf16 v[118:121], v[150:153], v[174:177], v[118:121]
	v_mfma_f32_16x16x32_bf16 v[114:117], v[158:161], v[174:177], v[114:117]
	v_mfma_f32_16x16x32_bf16 v[110:113], v[150:153], v[186:189], v[110:113]
	v_mfma_f32_16x16x32_bf16 v[106:109], v[158:161], v[186:189], v[106:109]
	v_mfma_f32_16x16x32_bf16 v[102:105], v[150:153], v[194:197], v[102:105]
	v_mfma_f32_16x16x32_bf16 v[98:101], v[158:161], v[194:197], v[98:101]
	s_barrier
	s_add_i32 s22, 0, 0x14000
	s_add_i32 s30, s58, s46
	v_add_u32_e32 v145, s22, v141
	v_lshl_add_u64 v[198:199], s[44:45], 0, v[0:1]
	s_mov_b32 m0, s30
	ds_read_b128 v[220:223], v145
	ds_read_b128 v[224:227], v145 offset:1024
	ds_read_b128 v[228:231], v145 offset:2048
	ds_read_b128 v[232:235], v145 offset:3072
	global_load_lds_dwordx4 v[198:199], off
	v_lshl_add_u64 v[236:237], s[44:45], 0, v[130:131]
	s_add_i32 m0, s30, 0x2000
	s_nop 0
	global_load_lds_dwordx4 v[236:237], off
	s_barrier
	s_waitcnt lgkmcnt(0)
	v_mfma_f32_16x16x32_bf16 v[94:97], v[220:223], v[162:165], v[94:97]
	v_mfma_f32_16x16x32_bf16 v[90:93], v[228:231], v[162:165], v[90:93]
	v_mfma_f32_16x16x32_bf16 v[86:89], v[220:223], v[170:173], v[86:89]
	v_mfma_f32_16x16x32_bf16 v[82:85], v[228:231], v[170:173], v[82:85]
	v_mfma_f32_16x16x32_bf16 v[78:81], v[220:223], v[182:185], v[78:81]
	v_mfma_f32_16x16x32_bf16 v[74:77], v[228:231], v[182:185], v[74:77]
	v_mfma_f32_16x16x32_bf16 v[70:73], v[220:223], v[190:193], v[70:73]
	v_mfma_f32_16x16x32_bf16 v[66:69], v[228:231], v[190:193], v[66:69]
	v_mfma_f32_16x16x32_bf16 v[94:97], v[224:227], v[166:169], v[94:97]
	v_mfma_f32_16x16x32_bf16 v[90:93], v[232:235], v[166:169], v[90:93]
	v_mfma_f32_16x16x32_bf16 v[86:89], v[224:227], v[174:177], v[86:89]
	v_mfma_f32_16x16x32_bf16 v[82:85], v[232:235], v[174:177], v[82:85]
	v_mfma_f32_16x16x32_bf16 v[78:81], v[224:227], v[186:189], v[78:81]
	v_mfma_f32_16x16x32_bf16 v[74:77], v[232:235], v[186:189], v[74:77]
	v_mfma_f32_16x16x32_bf16 v[70:73], v[224:227], v[194:197], v[70:73]
	v_mfma_f32_16x16x32_bf16 v[66:69], v[232:235], v[194:197], v[66:69]
	s_barrier
	s_mov_b32 m0, s47
	v_lshl_add_u64 v[238:239], s[38:39], 0, v[0:1]
	ds_read_b128 v[162:165], v144 offset:16384
	ds_read_b128 v[166:169], v144 offset:17408
	ds_read_b128 v[170:173], v144 offset:18432
	ds_read_b128 v[174:177], v144 offset:19456
	ds_read_b128 v[182:185], v144 offset:20480
	ds_read_b128 v[186:189], v144 offset:21504
	ds_read_b128 v[190:193], v144 offset:22528
	ds_read_b128 v[194:197], v144 offset:23552
	global_load_lds_dwordx4 v[238:239], off
	v_lshl_add_u64 v[240:241], s[38:39], 0, v[130:131]
	s_mov_b32 m0, s50
	s_nop 0
	global_load_lds_dwordx4 v[240:241], off
	s_barrier
	s_waitcnt lgkmcnt(0)
	v_mfma_f32_16x16x32_bf16 v[62:65], v[146:149], v[162:165], v[62:65]
	v_mfma_f32_16x16x32_bf16 v[58:61], v[154:157], v[162:165], v[58:61]
	v_mfma_f32_16x16x32_bf16 v[54:57], v[146:149], v[170:173], v[54:57]
	v_mfma_f32_16x16x32_bf16 v[50:53], v[154:157], v[170:173], v[50:53]
	v_mfma_f32_16x16x32_bf16 v[46:49], v[146:149], v[182:185], v[46:49]
	v_mfma_f32_16x16x32_bf16 v[42:45], v[154:157], v[182:185], v[42:45]
	v_mfma_f32_16x16x32_bf16 v[38:41], v[146:149], v[190:193], v[38:41]
	v_mfma_f32_16x16x32_bf16 v[34:37], v[154:157], v[190:193], v[34:37]
	v_mfma_f32_16x16x32_bf16 v[62:65], v[150:153], v[166:169], v[62:65]
	v_mfma_f32_16x16x32_bf16 v[58:61], v[158:161], v[166:169], v[58:61]
	v_mfma_f32_16x16x32_bf16 v[54:57], v[150:153], v[174:177], v[54:57]
	v_mfma_f32_16x16x32_bf16 v[50:53], v[158:161], v[174:177], v[50:53]
	v_mfma_f32_16x16x32_bf16 v[46:49], v[150:153], v[186:189], v[46:49]
	v_mfma_f32_16x16x32_bf16 v[42:45], v[158:161], v[186:189], v[42:45]
	v_mfma_f32_16x16x32_bf16 v[38:41], v[150:153], v[194:197], v[38:41]
	v_mfma_f32_16x16x32_bf16 v[34:37], v[158:161], v[194:197], v[34:37]
	s_barrier
; #define PG8_STAGE(bufoff, gbase, voff) do { _Pragma("unroll") for (int _i = 0; _i < 2; ++_i) \
;         __builtin_amdgcn_global_load_lds((const unsigned*)((const char*)(gbase) + (voff)[_i]), (LAS unsigned*)(lds + (bufoff) + ldsw + _i * 8192), 16, 0, 0); } while (0)
; #define PG8_LDA(dst, b, h) do { _Pragma("unroll") for (int m = 0; m < 4; ++m) _Pragma("unroll") for (int k = 0; k < 2; ++k) dst[m][k] = *(const LAS bf16x8*)(lds + PG8_SA(b, h) + aoff + m * 2048 + k * 1024); } while (0)
; #define PG8_LDB(dst, b, h) do { _Pragma("unroll") for (int n = 0; n < 2; ++n) _Pragma("unroll") for (int k = 0; k < 2; ++k) dst[n][k] = *(const LAS bf16x8*)(lds + PG8_SB(b, h) + boff + n * 2048 + k * 1024); } while (0)
; #define PG8_MMA(ai, bj, At, Bt) do { __builtin_amdgcn_s_setprio(1); _Pragma("unroll") for (int m = 0; m < 4; ++m) _Pragma("unroll") for (int n = 0; n < 2; ++n) _Pragma("unroll") for (int k = 0; k < 2; ++k) \
;         acc[ai][bj][m][n] = __builtin_amdgcn_mfma_f32_16x16x32_bf16(Bt[n][k], At[m][k], acc[ai][bj][m][n], 0, 0, 0); __builtin_amdgcn_s_setprio(0); } while (0)
; #define PG8_WAIT_V(n) asm volatile("s_waitcnt vmcnt(" #n ")" ::: "memory")
; #define PG8_WAIT_L(n) asm volatile("s_waitcnt lgkmcnt(" #n ")" ::: "memory")
; #define PG8_BAR __builtin_amdgcn_s_barrier()
; #define PG8_SCHED __builtin_amdgcn_sched_barrier(0)
; template <int MODE, class EpiT, class Sched>
; __device__ __forceinline__ void gemm_phase(LAS unsigned char* lds, const Gemm g, const Sched& S, const EpiT& E) {
;     ...
;             PG8_STAGE(PG8_SB(0, 1), b2 + hstep, voffB);
;             PG8_WAIT_V(6); PG8_BAR; PG8_MMA(1, 1, At, B1); PG8_BAR;
;             PG8_LDB(B0, 1, 0); PG8_SCHED; PG8_LDA(At, 1, 0); PG8_STAGE(PG8_SA(0, 1), a2 + hstep, voffA);
;             PG8_WAIT_L(8); PG8_BAR; PG8_WAIT_L(0); PG8_MMA(0, 0, At, B0); PG8_BAR; PG8_SCHED;
;             PG8_LDB(B1, 1, 1); PG8_STAGE(PG8_SB(1, 0), b3, voffB);
;             PG8_BAR; PG8_WAIT_L(0); PG8_MMA(0, 1, At, B1); PG8_BAR;
;             PG8_LDA(At, 1, 1); PG8_STAGE(PG8_SA(1, 0), a3, voffA);
;             PG8_BAR; PG8_WAIT_L(0); PG8_MMA(1, 0, At, B0); PG8_BAR; PG8_SCHED;
	s_add_u32 s44, s44, s21
	s_addc_u32 s45, s45, 0
	s_add_i32 s22, s22, s46
	v_lshl_add_u64 v[242:243], s[44:45], 0, v[0:1]
	s_mov_b32 m0, s22
	v_lshl_add_u64 v[244:245], s[44:45], 0, v[130:131]
	global_load_lds_dwordx4 v[242:243], off
	s_add_i32 m0, s22, 0x2000
	s_nop 0
	global_load_lds_dwordx4 v[244:245], off
	s_waitcnt vmcnt(6)
	s_barrier
	v_mfma_f32_16x16x32_bf16 v[30:33], v[220:223], v[162:165], v[30:33]
	v_mfma_f32_16x16x32_bf16 v[26:29], v[228:231], v[162:165], v[26:29]
	v_mfma_f32_16x16x32_bf16 v[22:25], v[220:223], v[170:173], v[22:25]
	v_mfma_f32_16x16x32_bf16 v[18:21], v[228:231], v[170:173], v[18:21]
	v_mfma_f32_16x16x32_bf16 v[14:17], v[220:223], v[182:185], v[14:17]
	v_mfma_f32_16x16x32_bf16 v[10:13], v[228:231], v[182:185], v[10:13]
	v_mfma_f32_16x16x32_bf16 v[6:9], v[220:223], v[190:193], v[6:9]
	v_mfma_f32_16x16x32_bf16 v[2:5], v[228:231], v[190:193], v[2:5]
	v_mfma_f32_16x16x32_bf16 v[30:33], v[224:227], v[166:169], v[30:33]
	v_mfma_f32_16x16x32_bf16 v[26:29], v[232:235], v[166:169], v[26:29]
	v_mfma_f32_16x16x32_bf16 v[22:25], v[224:227], v[174:177], v[22:25]
	v_mfma_f32_16x16x32_bf16 v[18:21], v[232:235], v[174:177], v[18:21]
	v_mfma_f32_16x16x32_bf16 v[14:17], v[224:227], v[186:189], v[14:17]
	v_mfma_f32_16x16x32_bf16 v[10:13], v[232:235], v[186:189], v[10:13]
	v_mfma_f32_16x16x32_bf16 v[6:9], v[224:227], v[194:197], v[6:9]
	v_mfma_f32_16x16x32_bf16 v[2:5], v[232:235], v[194:197], v[2:5]
	s_barrier
	s_add_i32 s22, 0, 0x18000
	v_add_u32_e32 v145, s22, v141
	ds_read_b128 v[146:149], v145
	ds_read_b128 v[150:153], v145 offset:1024
	ds_read_b128 v[154:157], v145 offset:2048
	ds_read_b128 v[158:161], v145 offset:3072
	ds_read_b128 v[162:165], v144 offset:32768
	ds_read_b128 v[166:169], v144 offset:33792
	ds_read_b128 v[170:173], v144 offset:34816
	ds_read_b128 v[174:177], v144 offset:35840
	ds_read_b128 v[182:185], v144 offset:36864
	ds_read_b128 v[186:189], v144 offset:37888
	ds_read_b128 v[190:193], v144 offset:38912
	ds_read_b128 v[194:197], v144 offset:39936
	s_add_u32 s38, s38, s21
	s_addc_u32 s39, s39, 0
	s_mov_b32 m0, s51
	v_lshl_add_u64 v[220:221], s[38:39], 0, v[0:1]
	global_load_lds_dwordx4 v[220:221], off
	v_lshl_add_u64 v[220:221], s[38:39], 0, v[130:131]
	s_mov_b32 m0, s52
	s_nop 0
	global_load_lds_dwordx4 v[220:221], off
	s_waitcnt lgkmcnt(8)
	s_barrier
	s_waitcnt lgkmcnt(0)
	v_mfma_f32_16x16x32_bf16 v[126:129], v[146:149], v[162:165], v[126:129]
	v_mfma_f32_16x16x32_bf16 v[122:125], v[154:157], v[162:165], v[122:125]
	v_mfma_f32_16x16x32_bf16 v[118:121], v[146:149], v[170:173], v[118:121]
	v_mfma_f32_16x16x32_bf16 v[114:117], v[154:157], v[170:173], v[114:117]
	v_mfma_f32_16x16x32_bf16 v[110:113], v[146:149], v[182:185], v[110:113]
	v_mfma_f32_16x16x32_bf16 v[106:109], v[154:157], v[182:185], v[106:109]
	v_mfma_f32_16x16x32_bf16 v[102:105], v[146:149], v[190:193], v[102:105]
	v_mfma_f32_16x16x32_bf16 v[98:101], v[154:157], v[190:193], v[98:101]
	v_mfma_f32_16x16x32_bf16 v[126:129], v[150:153], v[166:169], v[126:129]
	v_mfma_f32_16x16x32_bf16 v[122:125], v[158:161], v[166:169], v[122:125]
	v_mfma_f32_16x16x32_bf16 v[118:121], v[150:153], v[174:177], v[118:121]
	v_mfma_f32_16x16x32_bf16 v[114:117], v[158:161], v[174:177], v[114:117]
	v_mfma_f32_16x16x32_bf16 v[110:113], v[150:153], v[186:189], v[110:113]
	v_mfma_f32_16x16x32_bf16 v[106:109], v[158:161], v[186:189], v[106:109]
	v_mfma_f32_16x16x32_bf16 v[102:105], v[150:153], v[194:197], v[102:105]
	v_mfma_f32_16x16x32_bf16 v[98:101], v[158:161], v[194:197], v[98:101]
	s_barrier
	s_add_i32 s30, 0, 0x1c000
	s_add_i32 s22, s22, s46
	v_add_u32_e32 v145, s30, v141
	v_lshl_add_u64 v[198:199], v[198:199], 0, s[76:77]
	s_mov_b32 m0, s22
	ds_read_b128 v[220:223], v145
	ds_read_b128 v[224:227], v145 offset:1024
	ds_read_b128 v[228:231], v145 offset:2048
	ds_read_b128 v[232:235], v145 offset:3072
	global_load_lds_dwordx4 v[198:199], off
	v_lshl_add_u64 v[198:199], v[236:237], 0, s[76:77]
	s_add_i32 m0, s22, 0x2000
	s_nop 0
	global_load_lds_dwordx4 v[198:199], off
	s_barrier
	s_waitcnt lgkmcnt(0)
	v_mfma_f32_16x16x32_bf16 v[94:97], v[220:223], v[162:165], v[94:97]
	v_mfma_f32_16x16x32_bf16 v[90:93], v[228:231], v[162:165], v[90:93]
	v_mfma_f32_16x16x32_bf16 v[86:89], v[220:223], v[170:173], v[86:89]
	v_mfma_f32_16x16x32_bf16 v[82:85], v[228:231], v[170:173], v[82:85]
	v_mfma_f32_16x16x32_bf16 v[78:81], v[220:223], v[182:185], v[78:81]
	v_mfma_f32_16x16x32_bf16 v[74:77], v[228:231], v[182:185], v[74:77]
	v_mfma_f32_16x16x32_bf16 v[70:73], v[220:223], v[190:193], v[70:73]
	v_mfma_f32_16x16x32_bf16 v[66:69], v[228:231], v[190:193], v[66:69]
	v_mfma_f32_16x16x32_bf16 v[94:97], v[224:227], v[166:169], v[94:97]
	v_mfma_f32_16x16x32_bf16 v[90:93], v[232:235], v[166:169], v[90:93]
	v_mfma_f32_16x16x32_bf16 v[86:89], v[224:227], v[174:177], v[86:89]
	v_mfma_f32_16x16x32_bf16 v[82:85], v[232:235], v[174:177], v[82:85]
	v_mfma_f32_16x16x32_bf16 v[78:81], v[224:227], v[186:189], v[78:81]
	v_mfma_f32_16x16x32_bf16 v[74:77], v[232:235], v[186:189], v[74:77]
	v_mfma_f32_16x16x32_bf16 v[70:73], v[224:227], v[194:197], v[70:73]
	v_mfma_f32_16x16x32_bf16 v[66:69], v[232:235], v[194:197], v[66:69]
	s_barrier
	s_mov_b32 m0, s53
	v_lshl_add_u64 v[198:199], v[238:239], 0, s[76:77]
	ds_read_b128 v[162:165], v144 offset:49152
	ds_read_b128 v[166:169], v144 offset:50176
	ds_read_b128 v[170:173], v144 offset:51200
	ds_read_b128 v[174:177], v144 offset:52224
	ds_read_b128 v[182:185], v144 offset:53248
	ds_read_b128 v[186:189], v144 offset:54272
	ds_read_b128 v[190:193], v144 offset:55296
	ds_read_b128 v[194:197], v144 offset:56320
	global_load_lds_dwordx4 v[198:199], off
	v_lshl_add_u64 v[198:199], v[240:241], 0, s[76:77]
	s_mov_b32 m0, s54
	s_nop 0
	global_load_lds_dwordx4 v[198:199], off
	s_barrier
; __device__ __forceinline__ unsigned pk2(float lo, float hi) { unsigned r; asm volatile("v_cvt_pk_bf16_f32 %0, %1, %2" : "=v"(r) : "v"(lo), "v"(hi)); return r; }
; __device__ __forceinline__ float siluf_(float x) { return x * __builtin_amdgcn_rcpf(1.0f + __expf(-x)); }
; #define PG8_STAGE(bufoff, gbase, voff) do { _Pragma("unroll") for (int _i = 0; _i < 2; ++_i) \
;         __builtin_amdgcn_global_load_lds((const unsigned*)((const char*)(gbase) + (voff)[_i]), (LAS unsigned*)(lds + (bufoff) + ldsw + _i * 8192), 16, 0, 0); } while (0)
; #define PG8_MMA(ai, bj, At, Bt) do { __builtin_amdgcn_s_setprio(1); _Pragma("unroll") for (int m = 0; m < 4; ++m) _Pragma("unroll") for (int n = 0; n < 2; ++n) _Pragma("unroll") for (int k = 0; k < 2; ++k) \
;         acc[ai][bj][m][n] = __builtin_amdgcn_mfma_f32_16x16x32_bf16(Bt[n][k], At[m][k], acc[ai][bj][m][n], 0, 0, 0); __builtin_amdgcn_s_setprio(0); } while (0)
; #define PG8_BAR __builtin_amdgcn_s_barrier()
;     template <int mode> __device__ __forceinline__ void run(const f32x4 (&acc)[2][2][4][2], const Unit& u, int wr, int wc, int fr, int fq, const LAS float* sc) const {
;     ...
;         if (mode == 0) {
;             const int col0 = u.pn * HALF + wc * 32 + 8 * fq;
; #pragma unroll
;             for (int ai = 0; ai < 2; ++ai)
; #pragma unroll
;                 for (int m = 0; m < 4; ++m) {
;                     const int row = row0 + ai * HALF + m * 16;
;                     const float s = sc[ai * HALF + wr * 64 + m * 16 + fr];
;                     const f32x4 g0 = acc[ai][0][m][0] * s, u0 = acc[ai][1][m][0] * s, g1 = acc[ai][0][m][1] * s, u1 = acc[ai][1][m][1] * s;
;                     u32x4 w;
;                     w.x = pk2(siluf_(g0[0]) * u0[0], siluf_(g0[1]) * u0[1]); w.y = pk2(siluf_(g0[2]) * u0[2], siluf_(g0[3]) * u0[3]);
;                     w.z = pk2(siluf_(g1[0]) * u1[0], siluf_(g1[1]) * u1[1]); w.w = pk2(siluf_(g1[2]) * u1[2], siluf_(g1[3]) * u1[3]);
;                     *(u32x4*)(ob + (size_t)row * FF + col0) = w;
; template <int MODE, class EpiT, class Sched>
; __device__ __forceinline__ void gemm_phase(LAS unsigned char* lds, const Gemm g, const Sched& S, const EpiT& E) {
;     ...
;             PG8_BAR; PG8_WAIT_L(0); PG8_MMA(1, 0, At, B0); PG8_BAR; PG8_SCHED;
;             PG8_STAGE(PG8_SB(1, 1), b3 + hstep, voffB);
;             PG8_WAIT_V(6); PG8_BAR; PG8_MMA(1, 1, At, B1); PG8_BAR;
;         }
	s_waitcnt lgkmcnt(0)
	v_mfma_f32_16x16x32_bf16 v[62:65], v[146:149], v[162:165], v[62:65]
	v_mfma_f32_16x16x32_bf16 v[58:61], v[154:157], v[162:165], v[58:61]
	v_mfma_f32_16x16x32_bf16 v[54:57], v[146:149], v[170:173], v[54:57]
	v_mfma_f32_16x16x32_bf16 v[50:53], v[154:157], v[170:173], v[50:53]
	v_mfma_f32_16x16x32_bf16 v[46:49], v[146:149], v[182:185], v[46:49]
	v_mfma_f32_16x16x32_bf16 v[42:45], v[154:157], v[182:185], v[42:45]
	v_mfma_f32_16x16x32_bf16 v[38:41], v[146:149], v[190:193], v[38:41]
	v_mfma_f32_16x16x32_bf16 v[34:37], v[154:157], v[190:193], v[34:37]
	v_mfma_f32_16x16x32_bf16 v[62:65], v[150:153], v[166:169], v[62:65]
	v_mfma_f32_16x16x32_bf16 v[58:61], v[158:161], v[166:169], v[58:61]
	v_mfma_f32_16x16x32_bf16 v[54:57], v[150:153], v[174:177], v[54:57]
	v_mfma_f32_16x16x32_bf16 v[50:53], v[158:161], v[174:177], v[50:53]
	v_mfma_f32_16x16x32_bf16 v[46:49], v[150:153], v[186:189], v[46:49]
	v_mfma_f32_16x16x32_bf16 v[42:45], v[158:161], v[186:189], v[42:45]
	v_mfma_f32_16x16x32_bf16 v[38:41], v[150:153], v[194:197], v[38:41]
	v_mfma_f32_16x16x32_bf16 v[34:37], v[158:161], v[194:197], v[34:37]
	s_barrier
	s_add_i32 s22, s30, s46
	v_lshl_add_u64 v[146:147], v[242:243], 0, s[76:77]
	s_mov_b32 m0, s22
	s_nop 0
	global_load_lds_dwordx4 v[146:147], off
	v_lshl_add_u64 v[146:147], v[244:245], 0, s[76:77]
	s_add_i32 m0, s22, 0x2000
	s_nop 0
	global_load_lds_dwordx4 v[146:147], off
	s_waitcnt vmcnt(6)
	s_barrier
	v_mfma_f32_16x16x32_bf16 v[30:33], v[220:223], v[162:165], v[30:33]
	v_mfma_f32_16x16x32_bf16 v[26:29], v[228:231], v[162:165], v[26:29]
	v_mfma_f32_16x16x32_bf16 v[22:25], v[220:223], v[170:173], v[22:25]
	v_mfma_f32_16x16x32_bf16 v[18:21], v[228:231], v[170:173], v[18:21]
	v_mfma_f32_16x16x32_bf16 v[14:17], v[220:223], v[182:185], v[14:17]
	v_mfma_f32_16x16x32_bf16 v[10:13], v[228:231], v[182:185], v[10:13]
	v_mfma_f32_16x16x32_bf16 v[6:9], v[220:223], v[190:193], v[6:9]
	v_mfma_f32_16x16x32_bf16 v[2:5], v[228:231], v[190:193], v[2:5]
	v_mfma_f32_16x16x32_bf16 v[30:33], v[224:227], v[166:169], v[30:33]
	v_mfma_f32_16x16x32_bf16 v[26:29], v[232:235], v[166:169], v[26:29]
	v_mfma_f32_16x16x32_bf16 v[22:25], v[224:227], v[174:177], v[22:25]
	v_mfma_f32_16x16x32_bf16 v[18:21], v[232:235], v[174:177], v[18:21]
	v_mfma_f32_16x16x32_bf16 v[14:17], v[224:227], v[186:189], v[14:17]
	v_mfma_f32_16x16x32_bf16 v[10:13], v[232:235], v[186:189], v[10:13]
	v_mfma_f32_16x16x32_bf16 v[6:9], v[224:227], v[194:197], v[6:9]
	v_mfma_f32_16x16x32_bf16 v[2:5], v[232:235], v[194:197], v[2:5]
	s_barrier
	s_add_u32 s4, s4, 0x100
	s_addc_u32 s5, s5, 0
	v_lshl_add_u64 v[138:139], v[138:139], 0, s[80:81]
	v_lshl_add_u64 v[136:137], v[136:137], 0, s[80:81]
	s_cmp_ge_u32 s23, s16
	s_mov_b32 s22, s23
	s_cbranch_scc0 .LBB0_332
	v_lshl_add_u32 v145, s57, 10, v142
	ds_read_b32 v136, v145
	v_lshl_or_b32 v138, s8, 7, v143
	v_lshl_add_u32 v146, s9, 8, v140
	v_ashrrev_i32_e32 v139, 31, v138
	v_lshlrev_b64 v[138:139], 1, v[138:139]
	s_waitcnt lgkmcnt(0)
	v_pk_mul_f32 v[148:149], v[126:127], v[136:137] op_sel_hi:[1,0]
	v_pk_mul_f32 v[154:155], v[94:95], v[136:137] op_sel_hi:[1,0]
	v_mul_f32_e32 v147, 0xbfb8aa3b, v148
	v_exp_f32_e32 v147, v147
	v_pk_mul_f32 v[150:151], v[128:129], v[136:137] op_sel_hi:[1,0]
	v_pk_mul_f32 v[152:153], v[96:97], v[136:137] op_sel_hi:[1,0]
	v_pk_mul_f32 v[158:159], v[122:123], v[136:137] op_sel_hi:[1,0]
	v_add_f32_e32 v147, 1.0, v147
	v_rcp_f32_e32 v147, v147
	v_pk_mul_f32 v[156:157], v[124:125], v[136:137] op_sel_hi:[1,0]
	v_pk_mul_f32 v[160:161], v[92:93], v[136:137] op_sel_hi:[1,0]
	v_pk_mul_f32 v[136:137], v[90:91], v[136:137] op_sel_hi:[1,0]
	v_mul_f32_e32 v147, v148, v147
	v_mul_f32_e32 v148, 0xbfb8aa3b, v149
	v_exp_f32_e32 v148, v148
	v_mul_f32_e32 v147, v154, v147
	s_and_b64 vcc, exec, s[42:43]
	v_add_f32_e32 v148, 1.0, v148
	v_rcp_f32_e32 v148, v148
	s_nop 0
	v_mul_f32_e32 v148, v149, v148
	v_mul_f32_e32 v148, v155, v148
	v_cvt_pk_bf16_f32 v148, v147, v148
	v_mul_f32_e32 v147, 0xbfb8aa3b, v150
	v_mul_f32_e32 v149, 0xbfb8aa3b, v151
	v_exp_f32_e32 v147, v147
	v_exp_f32_e32 v149, v149
	v_add_f32_e32 v147, 1.0, v147
	v_add_f32_e32 v149, 1.0, v149
	v_rcp_f32_e32 v147, v147
	v_rcp_f32_e32 v149, v149
	v_mul_f32_e32 v147, v150, v147
	v_mul_f32_e32 v149, v151, v149
	v_mul_f32_e32 v147, v152, v147
	v_mul_f32_e32 v149, v153, v149
	v_cvt_pk_bf16_f32 v149, v147, v149
	v_mul_f32_e32 v147, 0xbfb8aa3b, v158
	v_exp_f32_e32 v147, v147
	s_nop 0
	v_add_f32_e32 v147, 1.0, v147
	v_rcp_f32_e32 v147, v147
	s_nop 0
	v_mul_f32_e32 v147, v158, v147
	v_mul_f32_e32 v136, v136, v147
	v_mul_f32_e32 v147, 0xbfb8aa3b, v159
	v_exp_f32_e32 v147, v147
	s_nop 0
	v_add_f32_e32 v147, 1.0, v147
	v_rcp_f32_e32 v147, v147
	s_nop 0
	v_mul_f32_e32 v147, v159, v147
	v_mul_f32_e32 v137, v137, v147
	v_cvt_pk_bf16_f32 v150, v136, v137
	v_mul_f32_e32 v136, 0xbfb8aa3b, v156
	v_mul_f32_e32 v137, 0xbfb8aa3b, v157
	v_exp_f32_e32 v136, v136
	v_exp_f32_e32 v137, v137
	v_or_b32_e32 v147, 16, v146
	v_add_f32_e32 v136, 1.0, v136
	v_add_f32_e32 v137, 1.0, v137
	v_rcp_f32_e32 v136, v136
	v_rcp_f32_e32 v137, v137
	v_mul_f32_e32 v136, v156, v136
	v_mul_f32_e32 v137, v157, v137
	v_mul_f32_e32 v136, v160, v136
	v_mul_f32_e32 v137, v161, v137
	v_cvt_pk_bf16_f32 v151, v136, v137
	v_mov_b64_e32 v[136:137], s[6:7]
	v_mad_i64_i32 v[152:153], s[4:5], v146, s33, v[136:137]
	v_lshl_add_u64 v[152:153], v[152:153], 0, v[138:139]
	global_store_dwordx4 v[152:153], v[148:151], off
	ds_read_b32 v148, v145 offset:64
	s_waitcnt lgkmcnt(0)
; __device__ __forceinline__ unsigned pk2(float lo, float hi) { unsigned r; asm volatile("v_cvt_pk_bf16_f32 %0, %1, %2" : "=v"(r) : "v"(lo), "v"(hi)); return r; }
; __device__ __forceinline__ float siluf_(float x) { return x * __builtin_amdgcn_rcpf(1.0f + __expf(-x)); }
;     template <int mode> __device__ __forceinline__ void run(const f32x4 (&acc)[2][2][4][2], const Unit& u, int wr, int wc, int fr, int fq, const LAS float* sc) const {
;     ...
;         if (mode == 0) {
;             const int col0 = u.pn * HALF + wc * 32 + 8 * fq;
; #pragma unroll
;             for (int ai = 0; ai < 2; ++ai)
; #pragma unroll
;                 for (int m = 0; m < 4; ++m) {
;                     const int row = row0 + ai * HALF + m * 16;
;                     const float s = sc[ai * HALF + wr * 64 + m * 16 + fr];
;                     const f32x4 g0 = acc[ai][0][m][0] * s, u0 = acc[ai][1][m][0] * s, g1 = acc[ai][0][m][1] * s, u1 = acc[ai][1][m][1] * s;
;                     u32x4 w;
;                     w.x = pk2(siluf_(g0[0]) * u0[0], siluf_(g0[1]) * u0[1]); w.y = pk2(siluf_(g0[2]) * u0[2], siluf_(g0[3]) * u0[3]);
;                     w.z = pk2(siluf_(g1[0]) * u1[0], siluf_(g1[1]) * u1[1]); w.w = pk2(siluf_(g1[2]) * u1[2], siluf_(g1[3]) * u1[3]);
;                     *(u32x4*)(ob + (size_t)row * FF + col0) = w;
;                 }
	v_pk_mul_f32 v[152:153], v[118:119], v[148:149] op_sel_hi:[1,0]
	v_pk_mul_f32 v[150:151], v[120:121], v[148:149] op_sel_hi:[1,0]
	v_pk_mul_f32 v[154:155], v[88:89], v[148:149] op_sel_hi:[1,0]
	v_pk_mul_f32 v[156:157], v[86:87], v[148:149] op_sel_hi:[1,0]
	v_pk_mul_f32 v[158:159], v[116:117], v[148:149] op_sel_hi:[1,0]
	v_pk_mul_f32 v[160:161], v[114:115], v[148:149] op_sel_hi:[1,0]
	v_pk_mul_f32 v[162:163], v[84:85], v[148:149] op_sel_hi:[1,0]
	v_pk_mul_f32 v[164:165], v[82:83], v[148:149] op_sel_hi:[1,0]
	v_mul_f32_e32 v148, 0xbfb8aa3b, v152
	v_mul_f32_e32 v149, 0xbfb8aa3b, v153
	v_exp_f32_e32 v148, v148
	v_exp_f32_e32 v149, v149
	v_add_f32_e32 v148, 1.0, v148
	v_add_f32_e32 v149, 1.0, v149
	v_rcp_f32_e32 v148, v148
	v_rcp_f32_e32 v149, v149
	v_mul_f32_e32 v148, v152, v148
	v_mul_f32_e32 v149, v153, v149
	v_mul_f32_e32 v148, v156, v148
	v_mul_f32_e32 v149, v157, v149
	v_cvt_pk_bf16_f32 v148, v148, v149
	v_mul_f32_e32 v149, 0xbfb8aa3b, v150
	v_exp_f32_e32 v149, v149
	v_mul_f32_e32 v152, 0xbfb8aa3b, v159
	v_exp_f32_e32 v152, v152
	v_add_f32_e32 v149, 1.0, v149
	v_rcp_f32_e32 v149, v149
	v_add_f32_e32 v152, 1.0, v152
	v_rcp_f32_e32 v152, v152
	v_mul_f32_e32 v149, v150, v149
	v_mul_f32_e32 v150, 0xbfb8aa3b, v151
	v_exp_f32_e32 v150, v150
	v_mul_f32_e32 v149, v154, v149
	v_mul_f32_e32 v152, v159, v152
	v_mul_f32_e32 v152, v163, v152
	v_add_f32_e32 v150, 1.0, v150
	v_rcp_f32_e32 v150, v150
	s_nop 0
	v_mul_f32_e32 v150, v151, v150
	v_mul_f32_e32 v150, v155, v150
	v_cvt_pk_bf16_f32 v149, v149, v150
	v_mul_f32_e32 v150, 0xbfb8aa3b, v160
	v_mul_f32_e32 v151, 0xbfb8aa3b, v161
	v_exp_f32_e32 v150, v150
	v_exp_f32_e32 v151, v151
	v_add_f32_e32 v150, 1.0, v150
	v_add_f32_e32 v151, 1.0, v151
	v_rcp_f32_e32 v150, v150
	v_rcp_f32_e32 v151, v151
	v_mul_f32_e32 v150, v160, v150
	v_mul_f32_e32 v151, v161, v151
	v_mul_f32_e32 v150, v164, v150
	v_mul_f32_e32 v151, v165, v151
	v_cvt_pk_bf16_f32 v150, v150, v151
	v_mul_f32_e32 v151, 0xbfb8aa3b, v158
	v_exp_f32_e32 v151, v151
	s_nop 0
	v_add_f32_e32 v151, 1.0, v151
	v_rcp_f32_e32 v151, v151
	s_nop 0
	v_mul_f32_e32 v151, v158, v151
	v_mul_f32_e32 v151, v162, v151
	v_cvt_pk_bf16_f32 v151, v151, v152
	v_mad_i64_i32 v[152:153], s[4:5], v147, s33, v[136:137]
	v_lshl_add_u64 v[152:153], v[152:153], 0, v[138:139]
	global_store_dwordx4 v[152:153], v[148:151], off
	ds_read_b32 v148, v145 offset:128
	v_or_b32_e32 v147, 32, v146
	s_waitcnt lgkmcnt(0)
	v_pk_mul_f32 v[152:153], v[110:111], v[148:149] op_sel_hi:[1,0]
	v_pk_mul_f32 v[150:151], v[112:113], v[148:149] op_sel_hi:[1,0]
	v_pk_mul_f32 v[154:155], v[80:81], v[148:149] op_sel_hi:[1,0]
	v_pk_mul_f32 v[156:157], v[78:79], v[148:149] op_sel_hi:[1,0]
	v_pk_mul_f32 v[158:159], v[108:109], v[148:149] op_sel_hi:[1,0]
	v_pk_mul_f32 v[160:161], v[106:107], v[148:149] op_sel_hi:[1,0]
	v_pk_mul_f32 v[162:163], v[76:77], v[148:149] op_sel_hi:[1,0]
	v_pk_mul_f32 v[164:165], v[74:75], v[148:149] op_sel_hi:[1,0]
	v_mul_f32_e32 v148, 0xbfb8aa3b, v152
	v_mul_f32_e32 v149, 0xbfb8aa3b, v153
	v_exp_f32_e32 v148, v148
	v_exp_f32_e32 v149, v149
	v_add_f32_e32 v148, 1.0, v148
	v_add_f32_e32 v149, 1.0, v149
	v_rcp_f32_e32 v148, v148
	v_rcp_f32_e32 v149, v149
	v_mul_f32_e32 v148, v152, v148
	v_mul_f32_e32 v149, v153, v149
	v_mul_f32_e32 v148, v156, v148
	v_mul_f32_e32 v149, v157, v149
	v_cvt_pk_bf16_f32 v148, v148, v149
	v_mul_f32_e32 v149, 0xbfb8aa3b, v150
	v_exp_f32_e32 v149, v149
	v_mul_f32_e32 v152, 0xbfb8aa3b, v159
	v_exp_f32_e32 v152, v152
	v_add_f32_e32 v149, 1.0, v149
	v_rcp_f32_e32 v149, v149
	v_add_f32_e32 v152, 1.0, v152
	v_rcp_f32_e32 v152, v152
	v_mul_f32_e32 v149, v150, v149
	v_mul_f32_e32 v150, 0xbfb8aa3b, v151
	v_exp_f32_e32 v150, v150
	v_mul_f32_e32 v149, v154, v149
	v_mul_f32_e32 v152, v159, v152
	v_mul_f32_e32 v152, v163, v152
	v_add_f32_e32 v150, 1.0, v150
	v_rcp_f32_e32 v150, v150
	s_nop 0
	v_mul_f32_e32 v150, v151, v150
	v_mul_f32_e32 v150, v155, v150
	v_cvt_pk_bf16_f32 v149, v149, v150
	v_mul_f32_e32 v150, 0xbfb8aa3b, v160
	v_mul_f32_e32 v151, 0xbfb8aa3b, v161
	v_exp_f32_e32 v150, v150
	v_exp_f32_e32 v151, v151
	v_add_f32_e32 v150, 1.0, v150
	v_add_f32_e32 v151, 1.0, v151
	v_rcp_f32_e32 v150, v150
	v_rcp_f32_e32 v151, v151
	v_mul_f32_e32 v150, v160, v150
	v_mul_f32_e32 v151, v161, v151
	v_mul_f32_e32 v150, v164, v150
	v_mul_f32_e32 v151, v165, v151
	v_cvt_pk_bf16_f32 v150, v150, v151
	v_mul_f32_e32 v151, 0xbfb8aa3b, v158
	v_exp_f32_e32 v151, v151
	s_nop 0
	v_add_f32_e32 v151, 1.0, v151
	v_rcp_f32_e32 v151, v151
	s_nop 0
	v_mul_f32_e32 v151, v158, v151
	v_mul_f32_e32 v151, v162, v151
	v_cvt_pk_bf16_f32 v151, v151, v152
	v_mad_i64_i32 v[152:153], s[4:5], v147, s33, v[136:137]
	v_lshl_add_u64 v[152:153], v[152:153], 0, v[138:139]
	global_store_dwordx4 v[152:153], v[148:151], off
	ds_read_b32 v148, v145 offset:192
	v_or_b32_e32 v147, 48, v146
	s_waitcnt lgkmcnt(0)
; __device__ __forceinline__ unsigned pk2(float lo, float hi) { unsigned r; asm volatile("v_cvt_pk_bf16_f32 %0, %1, %2" : "=v"(r) : "v"(lo), "v"(hi)); return r; }
; __device__ __forceinline__ float siluf_(float x) { return x * __builtin_amdgcn_rcpf(1.0f + __expf(-x)); }
;     template <int mode> __device__ __forceinline__ void run(const f32x4 (&acc)[2][2][4][2], const Unit& u, int wr, int wc, int fr, int fq, const LAS float* sc) const {
;     ...
;         if (mode == 0) {
;             const int col0 = u.pn * HALF + wc * 32 + 8 * fq;
; #pragma unroll
;             for (int ai = 0; ai < 2; ++ai)
; #pragma unroll
;                 for (int m = 0; m < 4; ++m) {
;                     const int row = row0 + ai * HALF + m * 16;
;                     const float s = sc[ai * HALF + wr * 64 + m * 16 + fr];
;                     const f32x4 g0 = acc[ai][0][m][0] * s, u0 = acc[ai][1][m][0] * s, g1 = acc[ai][0][m][1] * s, u1 = acc[ai][1][m][1] * s;
;                     u32x4 w;
;                     w.x = pk2(siluf_(g0[0]) * u0[0], siluf_(g0[1]) * u0[1]); w.y = pk2(siluf_(g0[2]) * u0[2], siluf_(g0[3]) * u0[3]);
;                     w.z = pk2(siluf_(g1[0]) * u1[0], siluf_(g1[1]) * u1[1]); w.w = pk2(siluf_(g1[2]) * u1[2], siluf_(g1[3]) * u1[3]);
;                     *(u32x4*)(ob + (size_t)row * FF + col0) = w;
;                 }
	v_pk_mul_f32 v[152:153], v[102:103], v[148:149] op_sel_hi:[1,0]
	v_pk_mul_f32 v[150:151], v[104:105], v[148:149] op_sel_hi:[1,0]
	v_pk_mul_f32 v[154:155], v[72:73], v[148:149] op_sel_hi:[1,0]
	v_pk_mul_f32 v[156:157], v[70:71], v[148:149] op_sel_hi:[1,0]
	v_pk_mul_f32 v[158:159], v[100:101], v[148:149] op_sel_hi:[1,0]
	v_pk_mul_f32 v[160:161], v[98:99], v[148:149] op_sel_hi:[1,0]
	v_pk_mul_f32 v[162:163], v[68:69], v[148:149] op_sel_hi:[1,0]
	v_pk_mul_f32 v[164:165], v[66:67], v[148:149] op_sel_hi:[1,0]
	v_mul_f32_e32 v148, 0xbfb8aa3b, v152
	v_mul_f32_e32 v149, 0xbfb8aa3b, v153
	v_exp_f32_e32 v148, v148
	v_exp_f32_e32 v149, v149
	v_add_f32_e32 v148, 1.0, v148
	v_add_f32_e32 v149, 1.0, v149
	v_rcp_f32_e32 v148, v148
	v_rcp_f32_e32 v149, v149
	v_mul_f32_e32 v148, v152, v148
	v_mul_f32_e32 v149, v153, v149
	v_mul_f32_e32 v148, v156, v148
	v_mul_f32_e32 v149, v157, v149
	v_cvt_pk_bf16_f32 v148, v148, v149
	v_mul_f32_e32 v149, 0xbfb8aa3b, v150
	v_exp_f32_e32 v149, v149
	v_mul_f32_e32 v152, 0xbfb8aa3b, v159
	v_exp_f32_e32 v152, v152
	v_add_f32_e32 v149, 1.0, v149
	v_rcp_f32_e32 v149, v149
	v_add_f32_e32 v152, 1.0, v152
	v_rcp_f32_e32 v152, v152
	v_mul_f32_e32 v149, v150, v149
	v_mul_f32_e32 v150, 0xbfb8aa3b, v151
	v_exp_f32_e32 v150, v150
	v_mul_f32_e32 v149, v154, v149
	v_mul_f32_e32 v152, v159, v152
	v_mul_f32_e32 v152, v163, v152
	v_add_f32_e32 v150, 1.0, v150
	v_rcp_f32_e32 v150, v150
	s_nop 0
	v_mul_f32_e32 v150, v151, v150
	v_mul_f32_e32 v150, v155, v150
	v_cvt_pk_bf16_f32 v149, v149, v150
	v_mul_f32_e32 v150, 0xbfb8aa3b, v160
	v_mul_f32_e32 v151, 0xbfb8aa3b, v161
	v_exp_f32_e32 v150, v150
	v_exp_f32_e32 v151, v151
	v_add_f32_e32 v150, 1.0, v150
	v_add_f32_e32 v151, 1.0, v151
	v_rcp_f32_e32 v150, v150
	v_rcp_f32_e32 v151, v151
	v_mul_f32_e32 v150, v160, v150
	v_mul_f32_e32 v151, v161, v151
	v_mul_f32_e32 v150, v164, v150
	v_mul_f32_e32 v151, v165, v151
	v_cvt_pk_bf16_f32 v150, v150, v151
	v_mul_f32_e32 v151, 0xbfb8aa3b, v158
	v_exp_f32_e32 v151, v151
	s_nop 0
	v_add_f32_e32 v151, 1.0, v151
	v_rcp_f32_e32 v151, v151
	s_nop 0
	v_mul_f32_e32 v151, v158, v151
	v_mul_f32_e32 v151, v162, v151
	v_cvt_pk_bf16_f32 v151, v151, v152
	v_mad_i64_i32 v[152:153], s[4:5], v147, s33, v[136:137]
	v_lshl_add_u64 v[152:153], v[152:153], 0, v[138:139]
	global_store_dwordx4 v[152:153], v[148:151], off
	ds_read_b32 v148, v145 offset:512
	v_add_u32_e32 v147, 0x80, v146
	s_waitcnt lgkmcnt(0)
	v_pk_mul_f32 v[152:153], v[62:63], v[148:149] op_sel_hi:[1,0]
	v_pk_mul_f32 v[150:151], v[64:65], v[148:149] op_sel_hi:[1,0]
	v_pk_mul_f32 v[154:155], v[32:33], v[148:149] op_sel_hi:[1,0]
	v_pk_mul_f32 v[156:157], v[30:31], v[148:149] op_sel_hi:[1,0]
	v_pk_mul_f32 v[158:159], v[60:61], v[148:149] op_sel_hi:[1,0]
	v_pk_mul_f32 v[160:161], v[58:59], v[148:149] op_sel_hi:[1,0]
	v_pk_mul_f32 v[162:163], v[28:29], v[148:149] op_sel_hi:[1,0]
	v_pk_mul_f32 v[164:165], v[26:27], v[148:149] op_sel_hi:[1,0]
	v_mul_f32_e32 v148, 0xbfb8aa3b, v152
	v_mul_f32_e32 v149, 0xbfb8aa3b, v153
	v_exp_f32_e32 v148, v148
	v_exp_f32_e32 v149, v149
	v_add_f32_e32 v148, 1.0, v148
	v_add_f32_e32 v149, 1.0, v149
	v_rcp_f32_e32 v148, v148
	v_rcp_f32_e32 v149, v149
	v_mul_f32_e32 v148, v152, v148
	v_mul_f32_e32 v149, v153, v149
	v_mul_f32_e32 v148, v156, v148
	v_mul_f32_e32 v149, v157, v149
	v_cvt_pk_bf16_f32 v148, v148, v149
	v_mul_f32_e32 v149, 0xbfb8aa3b, v150
	v_exp_f32_e32 v149, v149
	v_mul_f32_e32 v152, 0xbfb8aa3b, v159
	v_exp_f32_e32 v152, v152
	v_add_f32_e32 v149, 1.0, v149
	v_rcp_f32_e32 v149, v149
	v_add_f32_e32 v152, 1.0, v152
	v_rcp_f32_e32 v152, v152
	v_mul_f32_e32 v149, v150, v149
	v_mul_f32_e32 v150, 0xbfb8aa3b, v151
	v_exp_f32_e32 v150, v150
	v_mul_f32_e32 v149, v154, v149
	v_mul_f32_e32 v152, v159, v152
	v_mul_f32_e32 v152, v163, v152
	v_add_f32_e32 v150, 1.0, v150
	v_rcp_f32_e32 v150, v150
	s_nop 0
	v_mul_f32_e32 v150, v151, v150
	v_mul_f32_e32 v150, v155, v150
	v_cvt_pk_bf16_f32 v149, v149, v150
	v_mul_f32_e32 v150, 0xbfb8aa3b, v160
	v_mul_f32_e32 v151, 0xbfb8aa3b, v161
	v_exp_f32_e32 v150, v150
	v_exp_f32_e32 v151, v151
	v_add_f32_e32 v150, 1.0, v150
	v_add_f32_e32 v151, 1.0, v151
	v_rcp_f32_e32 v150, v150
	v_rcp_f32_e32 v151, v151
	v_mul_f32_e32 v150, v160, v150
	v_mul_f32_e32 v151, v161, v151
	v_mul_f32_e32 v150, v164, v150
	v_mul_f32_e32 v151, v165, v151
	v_cvt_pk_bf16_f32 v150, v150, v151
	v_mul_f32_e32 v151, 0xbfb8aa3b, v158
	v_exp_f32_e32 v151, v151
	s_nop 0
	v_add_f32_e32 v151, 1.0, v151
	v_rcp_f32_e32 v151, v151
	s_nop 0
	v_mul_f32_e32 v151, v158, v151
	v_mul_f32_e32 v151, v162, v151
	v_cvt_pk_bf16_f32 v151, v151, v152
	v_mad_i64_i32 v[152:153], s[4:5], v147, s33, v[136:137]
	v_lshl_add_u64 v[152:153], v[152:153], 0, v[138:139]
	global_store_dwordx4 v[152:153], v[148:151], off
	ds_read_b32 v148, v145 offset:576
	v_add_u32_e32 v147, 0x90, v146
	s_waitcnt lgkmcnt(0)
; __device__ __forceinline__ unsigned pk2(float lo, float hi) { unsigned r; asm volatile("v_cvt_pk_bf16_f32 %0, %1, %2" : "=v"(r) : "v"(lo), "v"(hi)); return r; }
; __device__ __forceinline__ float siluf_(float x) { return x * __builtin_amdgcn_rcpf(1.0f + __expf(-x)); }
;     template <int mode> __device__ __forceinline__ void run(const f32x4 (&acc)[2][2][4][2], const Unit& u, int wr, int wc, int fr, int fq, const LAS float* sc) const {
;     ...
;         if (mode == 0) {
;             const int col0 = u.pn * HALF + wc * 32 + 8 * fq;
; #pragma unroll
;             for (int ai = 0; ai < 2; ++ai)
; #pragma unroll
;                 for (int m = 0; m < 4; ++m) {
;                     const int row = row0 + ai * HALF + m * 16;
;                     const float s = sc[ai * HALF + wr * 64 + m * 16 + fr];
;                     const f32x4 g0 = acc[ai][0][m][0] * s, u0 = acc[ai][1][m][0] * s, g1 = acc[ai][0][m][1] * s, u1 = acc[ai][1][m][1] * s;
;                     u32x4 w;
;                     w.x = pk2(siluf_(g0[0]) * u0[0], siluf_(g0[1]) * u0[1]); w.y = pk2(siluf_(g0[2]) * u0[2], siluf_(g0[3]) * u0[3]);
;                     w.z = pk2(siluf_(g1[0]) * u1[0], siluf_(g1[1]) * u1[1]); w.w = pk2(siluf_(g1[2]) * u1[2], siluf_(g1[3]) * u1[3]);
;                     *(u32x4*)(ob + (size_t)row * FF + col0) = w;
;                 }
	v_pk_mul_f32 v[152:153], v[54:55], v[148:149] op_sel_hi:[1,0]
	v_pk_mul_f32 v[150:151], v[56:57], v[148:149] op_sel_hi:[1,0]
	v_pk_mul_f32 v[154:155], v[24:25], v[148:149] op_sel_hi:[1,0]
	v_pk_mul_f32 v[156:157], v[22:23], v[148:149] op_sel_hi:[1,0]
	v_pk_mul_f32 v[158:159], v[52:53], v[148:149] op_sel_hi:[1,0]
	v_pk_mul_f32 v[160:161], v[50:51], v[148:149] op_sel_hi:[1,0]
	v_pk_mul_f32 v[162:163], v[20:21], v[148:149] op_sel_hi:[1,0]
	v_pk_mul_f32 v[164:165], v[18:19], v[148:149] op_sel_hi:[1,0]
	v_mul_f32_e32 v148, 0xbfb8aa3b, v152
	v_mul_f32_e32 v149, 0xbfb8aa3b, v153
	v_exp_f32_e32 v148, v148
	v_exp_f32_e32 v149, v149
	v_add_f32_e32 v148, 1.0, v148
	v_add_f32_e32 v149, 1.0, v149
	v_rcp_f32_e32 v148, v148
	v_rcp_f32_e32 v149, v149
	v_mul_f32_e32 v148, v152, v148
	v_mul_f32_e32 v149, v153, v149
	v_mul_f32_e32 v148, v156, v148
	v_mul_f32_e32 v149, v157, v149
	v_cvt_pk_bf16_f32 v148, v148, v149
	v_mul_f32_e32 v149, 0xbfb8aa3b, v150
	v_exp_f32_e32 v149, v149
	v_mul_f32_e32 v152, 0xbfb8aa3b, v159
	v_exp_f32_e32 v152, v152
	v_add_f32_e32 v149, 1.0, v149
	v_rcp_f32_e32 v149, v149
	v_add_f32_e32 v152, 1.0, v152
	v_rcp_f32_e32 v152, v152
	v_mul_f32_e32 v149, v150, v149
	v_mul_f32_e32 v150, 0xbfb8aa3b, v151
	v_exp_f32_e32 v150, v150
	v_mul_f32_e32 v149, v154, v149
	v_mul_f32_e32 v152, v159, v152
	v_mul_f32_e32 v152, v163, v152
	v_add_f32_e32 v150, 1.0, v150
	v_rcp_f32_e32 v150, v150
	s_nop 0
	v_mul_f32_e32 v150, v151, v150
	v_mul_f32_e32 v150, v155, v150
	v_cvt_pk_bf16_f32 v149, v149, v150
	v_mul_f32_e32 v150, 0xbfb8aa3b, v160
	v_mul_f32_e32 v151, 0xbfb8aa3b, v161
	v_exp_f32_e32 v150, v150
	v_exp_f32_e32 v151, v151
	v_add_f32_e32 v150, 1.0, v150
	v_add_f32_e32 v151, 1.0, v151
	v_rcp_f32_e32 v150, v150
	v_rcp_f32_e32 v151, v151
	v_mul_f32_e32 v150, v160, v150
	v_mul_f32_e32 v151, v161, v151
	v_mul_f32_e32 v150, v164, v150
	v_mul_f32_e32 v151, v165, v151
	v_cvt_pk_bf16_f32 v150, v150, v151
	v_mul_f32_e32 v151, 0xbfb8aa3b, v158
	v_exp_f32_e32 v151, v151
	s_nop 0
	v_add_f32_e32 v151, 1.0, v151
	v_rcp_f32_e32 v151, v151
	s_nop 0
	v_mul_f32_e32 v151, v158, v151
	v_mul_f32_e32 v151, v162, v151
	v_cvt_pk_bf16_f32 v151, v151, v152
	v_mad_i64_i32 v[152:153], s[4:5], v147, s33, v[136:137]
	v_lshl_add_u64 v[152:153], v[152:153], 0, v[138:139]
	global_store_dwordx4 v[152:153], v[148:151], off
	ds_read_b32 v148, v145 offset:640
	v_add_u32_e32 v147, 0xa0, v146
	s_waitcnt lgkmcnt(0)
	v_pk_mul_f32 v[152:153], v[46:47], v[148:149] op_sel_hi:[1,0]
	v_pk_mul_f32 v[150:151], v[48:49], v[148:149] op_sel_hi:[1,0]
	v_pk_mul_f32 v[154:155], v[16:17], v[148:149] op_sel_hi:[1,0]
	v_pk_mul_f32 v[156:157], v[14:15], v[148:149] op_sel_hi:[1,0]
	v_pk_mul_f32 v[158:159], v[44:45], v[148:149] op_sel_hi:[1,0]
	v_pk_mul_f32 v[160:161], v[42:43], v[148:149] op_sel_hi:[1,0]
	v_pk_mul_f32 v[162:163], v[12:13], v[148:149] op_sel_hi:[1,0]
	v_pk_mul_f32 v[164:165], v[10:11], v[148:149] op_sel_hi:[1,0]
	v_mul_f32_e32 v148, 0xbfb8aa3b, v152
	v_mul_f32_e32 v149, 0xbfb8aa3b, v153
	v_exp_f32_e32 v148, v148
	v_exp_f32_e32 v149, v149
	v_add_f32_e32 v148, 1.0, v148
	v_add_f32_e32 v149, 1.0, v149
	v_rcp_f32_e32 v148, v148
	v_rcp_f32_e32 v149, v149
	v_mul_f32_e32 v148, v152, v148
	v_mul_f32_e32 v149, v153, v149
	v_mul_f32_e32 v148, v156, v148
	v_mul_f32_e32 v149, v157, v149
	v_cvt_pk_bf16_f32 v148, v148, v149
	v_mul_f32_e32 v149, 0xbfb8aa3b, v150
	v_exp_f32_e32 v149, v149
	v_mul_f32_e32 v152, 0xbfb8aa3b, v159
	v_exp_f32_e32 v152, v152
	v_add_f32_e32 v149, 1.0, v149
	v_rcp_f32_e32 v149, v149
	v_add_f32_e32 v152, 1.0, v152
	v_rcp_f32_e32 v152, v152
	v_mul_f32_e32 v149, v150, v149
	v_mul_f32_e32 v150, 0xbfb8aa3b, v151
	v_exp_f32_e32 v150, v150
	v_mul_f32_e32 v149, v154, v149
	v_mul_f32_e32 v152, v159, v152
	v_mul_f32_e32 v152, v163, v152
	v_add_f32_e32 v150, 1.0, v150
	v_rcp_f32_e32 v150, v150
	s_nop 0
	v_mul_f32_e32 v150, v151, v150
	v_mul_f32_e32 v150, v155, v150
	v_cvt_pk_bf16_f32 v149, v149, v150
	v_mul_f32_e32 v150, 0xbfb8aa3b, v160
	v_mul_f32_e32 v151, 0xbfb8aa3b, v161
	v_exp_f32_e32 v150, v150
	v_exp_f32_e32 v151, v151
	v_add_f32_e32 v150, 1.0, v150
	v_add_f32_e32 v151, 1.0, v151
	v_rcp_f32_e32 v150, v150
	v_rcp_f32_e32 v151, v151
	v_mul_f32_e32 v150, v160, v150
	v_mul_f32_e32 v151, v161, v151
	v_mul_f32_e32 v150, v164, v150
	v_mul_f32_e32 v151, v165, v151
	v_cvt_pk_bf16_f32 v150, v150, v151
	v_mul_f32_e32 v151, 0xbfb8aa3b, v158
	v_exp_f32_e32 v151, v151
	v_add_u32_e32 v164, 0xb0, v146
	v_add_f32_e32 v151, 1.0, v151
	v_rcp_f32_e32 v151, v151
	s_nop 0
	v_mul_f32_e32 v151, v158, v151
	v_mul_f32_e32 v151, v162, v151
	v_cvt_pk_bf16_f32 v151, v151, v152
	ds_read_b32 v146, v145 offset:704
	v_mad_i64_i32 v[152:153], s[4:5], v147, s33, v[136:137]
	v_lshl_add_u64 v[152:153], v[152:153], 0, v[138:139]
	global_store_dwordx4 v[152:153], v[148:151], off
	s_waitcnt lgkmcnt(0)
; __device__ __forceinline__ unsigned pk2(float lo, float hi) { unsigned r; asm volatile("v_cvt_pk_bf16_f32 %0, %1, %2" : "=v"(r) : "v"(lo), "v"(hi)); return r; }
; __device__ __forceinline__ float siluf_(float x) { return x * __builtin_amdgcn_rcpf(1.0f + __expf(-x)); }
;     template <int mode> __device__ __forceinline__ void run(const f32x4 (&acc)[2][2][4][2], const Unit& u, int wr, int wc, int fr, int fq, const LAS float* sc) const {
;     ...
;         if (mode == 0) {
;             const int col0 = u.pn * HALF + wc * 32 + 8 * fq;
; #pragma unroll
;             for (int ai = 0; ai < 2; ++ai)
; #pragma unroll
;                 for (int m = 0; m < 4; ++m) {
;                     const int row = row0 + ai * HALF + m * 16;
;                     const float s = sc[ai * HALF + wr * 64 + m * 16 + fr];
;                     const f32x4 g0 = acc[ai][0][m][0] * s, u0 = acc[ai][1][m][0] * s, g1 = acc[ai][0][m][1] * s, u1 = acc[ai][1][m][1] * s;
;                     u32x4 w;
;                     w.x = pk2(siluf_(g0[0]) * u0[0], siluf_(g0[1]) * u0[1]); w.y = pk2(siluf_(g0[2]) * u0[2], siluf_(g0[3]) * u0[3]);
;                     w.z = pk2(siluf_(g1[0]) * u1[0], siluf_(g1[1]) * u1[1]); w.w = pk2(siluf_(g1[2]) * u1[2], siluf_(g1[3]) * u1[3]);
;                     *(u32x4*)(ob + (size_t)row * FF + col0) = w;
;                 }
; template <int MODE, class EpiT, class Sched>
; __device__ __forceinline__ void gemm_phase(LAS unsigned char* lds, const Gemm g, const Sched& S, const EpiT& E) {
;     ...
;         E.template run<MODE>(acc, cur, wr, wc, fr, fq, SC + ui * 256);
;         if (!has_next) break;
; #pragma unroll
;         for (int a = 0; a < 2; ++a)
; #pragma unroll
;             for (int b = 0; b < 2; ++b)
; #pragma unroll
;                 for (int m = 0; m < 4; ++m)
; #pragma unroll
;                     for (int n = 0; n < 2; ++n) acc[a][b][m][n] = (f32x4){0.f, 0.f, 0.f, 0.f};
;         cur = nxt; cA = nA; cB = nB; ++ui;
	v_pk_mul_f32 v[152:153], v[8:9], v[146:147] op_sel_hi:[1,0]
	v_pk_mul_f32 v[154:155], v[6:7], v[146:147] op_sel_hi:[1,0]
	v_pk_mul_f32 v[150:151], v[38:39], v[146:147] op_sel_hi:[1,0]
	v_pk_mul_f32 v[148:149], v[40:41], v[146:147] op_sel_hi:[1,0]
	v_pk_mul_f32 v[156:157], v[36:37], v[146:147] op_sel_hi:[1,0]
	v_pk_mul_f32 v[158:159], v[34:35], v[146:147] op_sel_hi:[1,0]
	v_pk_mul_f32 v[160:161], v[4:5], v[146:147] op_sel_hi:[1,0]
	v_pk_mul_f32 v[162:163], v[2:3], v[146:147] op_sel_hi:[1,0]
	v_mul_f32_e32 v145, 0xbfb8aa3b, v150
	v_mul_f32_e32 v146, 0xbfb8aa3b, v151
	v_exp_f32_e32 v145, v145
	v_exp_f32_e32 v146, v146
	v_mul_f32_e32 v147, 0xbfb8aa3b, v149
	v_exp_f32_e32 v147, v147
	v_add_f32_e32 v145, 1.0, v145
	v_add_f32_e32 v146, 1.0, v146
	v_rcp_f32_e32 v145, v145
	v_rcp_f32_e32 v146, v146
	v_add_f32_e32 v147, 1.0, v147
	v_rcp_f32_e32 v147, v147
	v_mul_f32_e32 v145, v150, v145
	v_mul_f32_e32 v146, v151, v146
	v_mul_f32_e32 v145, v154, v145
	v_mul_f32_e32 v146, v155, v146
	v_cvt_pk_bf16_f32 v146, v145, v146
	v_mul_f32_e32 v145, 0xbfb8aa3b, v148
	v_exp_f32_e32 v145, v145
	v_mul_f32_e32 v147, v149, v147
	v_mul_f32_e32 v147, v153, v147
	v_mul_f32_e32 v149, 0xbfb8aa3b, v157
	v_add_f32_e32 v145, 1.0, v145
	v_rcp_f32_e32 v145, v145
	v_exp_f32_e32 v149, v149
	v_mad_i64_i32 v[136:137], s[4:5], v164, s33, v[136:137]
	v_mul_f32_e32 v145, v148, v145
	v_mul_f32_e32 v145, v152, v145
	v_cvt_pk_bf16_f32 v147, v145, v147
	v_mul_f32_e32 v145, 0xbfb8aa3b, v158
	v_mul_f32_e32 v148, 0xbfb8aa3b, v159
	v_exp_f32_e32 v145, v145
	v_exp_f32_e32 v148, v148
	v_add_f32_e32 v149, 1.0, v149
	v_rcp_f32_e32 v149, v149
	v_add_f32_e32 v145, 1.0, v145
	v_add_f32_e32 v148, 1.0, v148
	v_rcp_f32_e32 v145, v145
	v_rcp_f32_e32 v148, v148
	v_mul_f32_e32 v149, v157, v149
	v_mul_f32_e32 v149, v161, v149
	v_mul_f32_e32 v145, v158, v145
	v_mul_f32_e32 v148, v159, v148
	v_mul_f32_e32 v145, v162, v145
	v_mul_f32_e32 v148, v163, v148
	v_cvt_pk_bf16_f32 v148, v145, v148
	v_mul_f32_e32 v145, 0xbfb8aa3b, v156
	v_exp_f32_e32 v145, v145
	v_lshl_add_u64 v[136:137], v[136:137], 0, v[138:139]
	v_add_f32_e32 v145, 1.0, v145
	v_rcp_f32_e32 v145, v145
	s_nop 0
	v_mul_f32_e32 v145, v156, v145
	v_mul_f32_e32 v145, v160, v145
	v_cvt_pk_bf16_f32 v149, v145, v149
	global_store_dwordx4 v[136:137], v[146:149], off
	s_cbranch_vccnz .LBB0_324
	v_mov_b32_e32 v2, 0
	s_mov_b32 s9, s61
	s_mov_b32 s8, s60
	s_mov_b64 s[12:13], s[28:29]
	s_mov_b64 s[10:11], s[34:35]
	s_mov_b32 s57, s2
	v_mov_b32_e32 v3, v2
	v_mov_b32_e32 v4, v2
	v_mov_b32_e32 v5, v2
	v_mov_b32_e32 v6, v2
	v_mov_b32_e32 v7, v2
	v_mov_b32_e32 v8, v2
	v_mov_b32_e32 v9, v2
	v_mov_b32_e32 v10, v2
	v_mov_b32_e32 v11, v2
	v_mov_b32_e32 v12, v2
	v_mov_b32_e32 v13, v2
	v_mov_b32_e32 v14, v2
	v_mov_b32_e32 v15, v2
	v_mov_b32_e32 v16, v2
	v_mov_b32_e32 v17, v2
	v_mov_b32_e32 v18, v2
	v_mov_b32_e32 v19, v2
	v_mov_b32_e32 v20, v2
	v_mov_b32_e32 v21, v2
	v_mov_b32_e32 v22, v2
	v_mov_b32_e32 v23, v2
	v_mov_b32_e32 v24, v2
	v_mov_b32_e32 v25, v2
	v_mov_b32_e32 v26, v2
	v_mov_b32_e32 v27, v2
	v_mov_b32_e32 v28, v2
	v_mov_b32_e32 v29, v2
	v_mov_b32_e32 v30, v2
	v_mov_b32_e32 v31, v2
	v_mov_b32_e32 v32, v2
	v_mov_b32_e32 v33, v2
	v_mov_b32_e32 v34, v2
	v_mov_b32_e32 v35, v2
	v_mov_b32_e32 v36, v2
	v_mov_b32_e32 v37, v2
	v_mov_b32_e32 v38, v2
	v_mov_b32_e32 v39, v2
	v_mov_b32_e32 v40, v2
	v_mov_b32_e32 v41, v2
	v_mov_b32_e32 v42, v2
	v_mov_b32_e32 v43, v2
	v_mov_b32_e32 v44, v2
	v_mov_b32_e32 v45, v2
	v_mov_b32_e32 v46, v2
	v_mov_b32_e32 v47, v2
	v_mov_b32_e32 v48, v2
	v_mov_b32_e32 v49, v2
	v_mov_b32_e32 v50, v2
	v_mov_b32_e32 v51, v2
	v_mov_b32_e32 v52, v2
	v_mov_b32_e32 v53, v2
	v_mov_b32_e32 v54, v2
	v_mov_b32_e32 v55, v2
	v_mov_b32_e32 v56, v2
	v_mov_b32_e32 v57, v2
	v_mov_b32_e32 v58, v2
	v_mov_b32_e32 v59, v2
	v_mov_b32_e32 v60, v2
	v_mov_b32_e32 v61, v2
	v_mov_b32_e32 v62, v2
	v_mov_b32_e32 v63, v2
	v_mov_b32_e32 v64, v2
	v_mov_b32_e32 v65, v2
	v_mov_b32_e32 v66, v2
	v_mov_b32_e32 v67, v2
	v_mov_b32_e32 v68, v2
	v_mov_b32_e32 v69, v2
	v_mov_b32_e32 v70, v2
	v_mov_b32_e32 v71, v2
	v_mov_b32_e32 v72, v2
	v_mov_b32_e32 v73, v2
	v_mov_b32_e32 v74, v2
	v_mov_b32_e32 v75, v2
	v_mov_b32_e32 v76, v2
	v_mov_b32_e32 v77, v2
	v_mov_b32_e32 v78, v2
	v_mov_b32_e32 v79, v2
	v_mov_b32_e32 v80, v2
	v_mov_b32_e32 v81, v2
	v_mov_b32_e32 v82, v2
	v_mov_b32_e32 v83, v2
	v_mov_b32_e32 v84, v2
	v_mov_b32_e32 v85, v2
	v_mov_b32_e32 v86, v2
	v_mov_b32_e32 v87, v2
	v_mov_b32_e32 v88, v2
	v_mov_b32_e32 v89, v2
	v_mov_b32_e32 v90, v2
	v_mov_b32_e32 v91, v2
	v_mov_b32_e32 v92, v2
	v_mov_b32_e32 v93, v2
	v_mov_b32_e32 v94, v2
	v_mov_b32_e32 v95, v2
	v_mov_b32_e32 v96, v2
	v_mov_b32_e32 v97, v2
	v_mov_b32_e32 v98, v2
	v_mov_b32_e32 v99, v2
	v_mov_b32_e32 v100, v2
	v_mov_b32_e32 v101, v2
	v_mov_b32_e32 v102, v2
	v_mov_b32_e32 v103, v2
	v_mov_b32_e32 v104, v2
	v_mov_b32_e32 v105, v2
	v_mov_b32_e32 v106, v2
	v_mov_b32_e32 v107, v2
	v_mov_b32_e32 v108, v2
	v_mov_b32_e32 v109, v2
	v_mov_b32_e32 v110, v2
	v_mov_b32_e32 v111, v2
	v_mov_b32_e32 v112, v2
	v_mov_b32_e32 v113, v2
	v_mov_b32_e32 v114, v2
	v_mov_b32_e32 v115, v2
	v_mov_b32_e32 v116, v2
	v_mov_b32_e32 v117, v2
	v_mov_b32_e32 v118, v2
	v_mov_b32_e32 v119, v2
	v_mov_b32_e32 v120, v2
	v_mov_b32_e32 v121, v2
	v_mov_b32_e32 v122, v2
	v_mov_b32_e32 v123, v2
	v_mov_b32_e32 v124, v2
	v_mov_b32_e32 v125, v2
	v_mov_b32_e32 v126, v2
	v_mov_b32_e32 v127, v2
	v_mov_b32_e32 v128, v2
	v_mov_b32_e32 v129, v2
	s_branch .LBB0_324
